# FFN1/G1B epilogue sigmoid: IEEE f32 division expansion replaced by v_rcp_f32 (f32, same form the baseline uses for its other sigmoids); plus attn2 staging loads issued together and SCAN1 raw loads iss
# speedup vs baseline: 1.0441x; 1.0251x over previous
; #define LAS __attribute__((address_space(3)))
; __device__ __forceinline__ void ph_attn2(Ctx& C) {
;     ...
; #pragma unroll
;         for (int i = 0; i < 6; ++i) { const int kc = (tid >> 3) + 64 * i, ch = tid & 7, ki = kbase + kc; u32x4 w = (u32x4){0u, 0u, 0u, 0u}, wk = (u32x4){0u, 0u, 0u, 0u};
;             if (ki >= 0 && ki < n) { const bf16* rp = z + (size_t)((ki << dsh) + res) * NQKV + 8 * ch; w = *(const u32x4*)(rp + colv); wk = *(const u32x4*)(rp + colk); }
;             *(LAS u32x4*)(kim + kc * 72 + 8 * ch) = wk;
;             LAS bf16* dp = vt + (8 * ch) * AT_VTS + kc;
;             dp[0] = (bf16)(w.x & 0xffff); dp[AT_VTS] = (bf16)(w.x >> 16); dp[2 * AT_VTS] = (bf16)(w.y & 0xffff); dp[3 * AT_VTS] = (bf16)(w.y >> 16);
;             dp[4 * AT_VTS] = (bf16)(w.z & 0xffff); dp[5 * AT_VTS] = (bf16)(w.z >> 16); dp[6 * AT_VTS] = (bf16)(w.w & 0xffff); dp[7 * AT_VTS] = (bf16)(w.w >> 16); }
.LBB0_310:
	s_ashr_i32 s90, s96, 9
	s_bfe_u32 s33, s96, 0x60003
	s_lshl_b32 s1, s90, 1
	s_and_b32 s97, s96, 7
	s_bfm_b32 s70, s1, 0
	s_lshr_b32 s74, s33, s1
	s_and_b32 s75, s70, s33
	s_lshl_b32 s93, s74, 8
	s_and_b32 s33, s96, 0xfffffe00
	s_lshl_b32 s86, s97, 6
	s_lshr_b32 s91, 0x4000, s1
	s_or_b32 s72, s86, s33
	v_add_u32_e32 v14, s93, v193
	s_ashr_i32 s73, s72, 31
	v_cmp_lt_i32_e32 vcc, -1, v14
	v_cmp_gt_i32_e64 s[70:71], s91, v14
	v_lshl_add_u64 v[12:13], s[72:73], 1, v[80:81]
	s_and_b64 s[76:77], vcc, s[70:71]
	v_mov_b32_e32 v8, v14
	v_cmp_lt_i32_e32 vcc, -1, v8
	v_cmp_gt_i32_e64 s[70:71], s91, v8
	s_and_b64 s[76:77], vcc, s[70:71]
	v_mov_b32_e32 v16, 0
	v_mov_b32_e32 v17, 0
	v_mov_b32_e32 v18, 0
	v_mov_b32_e32 v19, 0
	v_mov_b32_e32 v20, 0
	v_mov_b32_e32 v21, 0
	v_mov_b32_e32 v22, 0
	v_mov_b32_e32 v23, 0
	s_and_saveexec_b64 s[70:71], s[76:77]
	s_cbranch_execz .Latt_kv_skip0
	v_lshlrev_b32_e32 v0, s1, v8
	v_add_u32_e32 v0, s75, v0
	v_mad_u64_u32 v[0:1], s[76:77], v0, s95, v[12:13]
	v_add_co_u32_e32 v2, vcc, 0x1000, v0
	s_nop 1
	v_addc_co_u32_e32 v3, vcc, 0, v1, vcc
	global_load_dwordx4 v[20:23], v[2:3], off offset:2048
	s_nop 0
	global_load_dwordx4 v[16:19], v[0:1], off offset:3072
.Latt_kv_skip0:
	s_or_b64 exec, exec, s[70:71]
	v_add_u32_e32 v8, s93, v187
	v_cmp_lt_i32_e32 vcc, -1, v8
	v_cmp_gt_i32_e64 s[70:71], s91, v8
	s_and_b64 s[76:77], vcc, s[70:71]
	v_mov_b32_e32 v24, 0
	v_mov_b32_e32 v25, 0
	v_mov_b32_e32 v26, 0
	v_mov_b32_e32 v27, 0
	v_mov_b32_e32 v28, 0
	v_mov_b32_e32 v29, 0
	v_mov_b32_e32 v30, 0
	v_mov_b32_e32 v31, 0
	s_and_saveexec_b64 s[70:71], s[76:77]
	s_cbranch_execz .Latt_kv_skip1
	v_lshlrev_b32_e32 v0, s1, v8
	v_add_u32_e32 v0, s75, v0
	v_mad_u64_u32 v[0:1], s[76:77], v0, s95, v[12:13]
	v_add_co_u32_e32 v2, vcc, 0x1000, v0
	s_nop 1
	v_addc_co_u32_e32 v3, vcc, 0, v1, vcc
	global_load_dwordx4 v[28:31], v[2:3], off offset:2048
	s_nop 0
	global_load_dwordx4 v[24:27], v[0:1], off offset:3072
.Latt_kv_skip1:
	s_or_b64 exec, exec, s[70:71]
	v_add_u32_e32 v8, 0x80, v14
	v_cmp_lt_i32_e32 vcc, -1, v8
	v_cmp_gt_i32_e64 s[70:71], s91, v8
	s_and_b64 s[76:77], vcc, s[70:71]
	v_mov_b32_e32 v32, 0
	v_mov_b32_e32 v33, 0
	v_mov_b32_e32 v34, 0
	v_mov_b32_e32 v35, 0
	v_mov_b32_e32 v36, 0
	v_mov_b32_e32 v37, 0
	v_mov_b32_e32 v38, 0
	v_mov_b32_e32 v39, 0
	s_and_saveexec_b64 s[70:71], s[76:77]
	s_cbranch_execz .Latt_kv_skip2
	v_lshlrev_b32_e32 v0, s1, v8
	v_add_u32_e32 v0, s75, v0
	v_mad_u64_u32 v[0:1], s[76:77], v0, s95, v[12:13]
	v_add_co_u32_e32 v2, vcc, 0x1000, v0
	s_nop 1
	v_addc_co_u32_e32 v3, vcc, 0, v1, vcc
	global_load_dwordx4 v[36:39], v[2:3], off offset:2048
	s_nop 0
	global_load_dwordx4 v[32:35], v[0:1], off offset:3072
.Latt_kv_skip2:
	s_or_b64 exec, exec, s[70:71]
	v_add_u32_e32 v8, 0xc0, v14
	v_cmp_lt_i32_e32 vcc, -1, v8
	v_cmp_gt_i32_e64 s[70:71], s91, v8
	s_and_b64 s[76:77], vcc, s[70:71]
	v_mov_b32_e32 v40, 0
	v_mov_b32_e32 v41, 0
	v_mov_b32_e32 v42, 0
	v_mov_b32_e32 v43, 0
	v_mov_b32_e32 v44, 0
	v_mov_b32_e32 v45, 0
	v_mov_b32_e32 v46, 0
	v_mov_b32_e32 v47, 0
	s_and_saveexec_b64 s[70:71], s[76:77]
	s_cbranch_execz .Latt_kv_skip3
	v_lshlrev_b32_e32 v0, s1, v8
	v_add_u32_e32 v0, s75, v0
	v_mad_u64_u32 v[0:1], s[76:77], v0, s95, v[12:13]
	v_add_co_u32_e32 v2, vcc, 0x1000, v0
	s_nop 1
	v_addc_co_u32_e32 v3, vcc, 0, v1, vcc
	global_load_dwordx4 v[44:47], v[2:3], off offset:2048
	s_nop 0
	global_load_dwordx4 v[40:43], v[0:1], off offset:3072
.Latt_kv_skip3:
	s_or_b64 exec, exec, s[70:71]
	v_add_u32_e32 v8, 0x100, v14
	v_cmp_lt_i32_e32 vcc, -1, v8
	v_cmp_gt_i32_e64 s[70:71], s91, v8
	s_and_b64 s[76:77], vcc, s[70:71]
	v_mov_b32_e32 v48, 0
	v_mov_b32_e32 v49, 0
	v_mov_b32_e32 v50, 0
	v_mov_b32_e32 v51, 0
	v_mov_b32_e32 v52, 0
	v_mov_b32_e32 v53, 0
	v_mov_b32_e32 v54, 0
	v_mov_b32_e32 v55, 0
	s_and_saveexec_b64 s[70:71], s[76:77]
	s_cbranch_execz .Latt_kv_skip4
	v_lshlrev_b32_e32 v0, s1, v8
	v_add_u32_e32 v0, s75, v0
	v_mad_u64_u32 v[0:1], s[76:77], v0, s95, v[12:13]
	v_add_co_u32_e32 v2, vcc, 0x1000, v0
	s_nop 1
	v_addc_co_u32_e32 v3, vcc, 0, v1, vcc
	global_load_dwordx4 v[52:55], v[2:3], off offset:2048
	s_nop 0
	global_load_dwordx4 v[48:51], v[0:1], off offset:3072
.Latt_kv_skip4:
	s_or_b64 exec, exec, s[70:71]
	v_add_u32_e32 v8, 0x140, v14
	v_cmp_lt_i32_e32 vcc, -1, v8
	v_cmp_gt_i32_e64 s[70:71], s91, v8
	s_and_b64 s[76:77], vcc, s[70:71]
	v_mov_b32_e32 v56, 0
	v_mov_b32_e32 v57, 0
	v_mov_b32_e32 v58, 0
	v_mov_b32_e32 v59, 0
	v_mov_b32_e32 v60, 0
	v_mov_b32_e32 v61, 0
	v_mov_b32_e32 v62, 0
	v_mov_b32_e32 v63, 0
	s_and_saveexec_b64 s[70:71], s[76:77]
	s_cbranch_execz .Latt_kv_skip5
	v_lshlrev_b32_e32 v0, s1, v8
	v_add_u32_e32 v0, s75, v0
	v_mad_u64_u32 v[0:1], s[76:77], v0, s95, v[12:13]
	v_add_co_u32_e32 v2, vcc, 0x1000, v0
	s_nop 1
	v_addc_co_u32_e32 v3, vcc, 0, v1, vcc
	global_load_dwordx4 v[60:63], v[2:3], off offset:2048
	s_nop 0
	global_load_dwordx4 v[56:59], v[0:1], off offset:3072
; #define LAS __attribute__((address_space(3)))
; __device__ __forceinline__ void ph_attn2(Ctx& C) {
;     ...
;         const float slope_d = exp2f(-8.0f * (float)(g * 8 + h + 1) / 24.0f) * (float)d;
; #pragma unroll
;         for (int i = 0; i < 6; ++i) { const int kc = (tid >> 3) + 64 * i, ch = tid & 7, ki = kbase + kc; u32x4 w = (u32x4){0u, 0u, 0u, 0u}, wk = (u32x4){0u, 0u, 0u, 0u};
;             if (ki >= 0 && ki < n) { const bf16* rp = z + (size_t)((ki << dsh) + res) * NQKV + 8 * ch; w = *(const u32x4*)(rp + colv); wk = *(const u32x4*)(rp + colk); }
;             *(LAS u32x4*)(kim + kc * 72 + 8 * ch) = wk;
;             LAS bf16* dp = vt + (8 * ch) * AT_VTS + kc;
;             dp[0] = (bf16)(w.x & 0xffff); dp[AT_VTS] = (bf16)(w.x >> 16); dp[2 * AT_VTS] = (bf16)(w.y & 0xffff); dp[3 * AT_VTS] = (bf16)(w.y >> 16);
;             dp[4 * AT_VTS] = (bf16)(w.z & 0xffff); dp[5 * AT_VTS] = (bf16)(w.z >> 16); dp[6 * AT_VTS] = (bf16)(w.w & 0xffff); dp[7 * AT_VTS] = (bf16)(w.w >> 16); }
;         __syncthreads();
;         const int qb = tl * 256 + 32 * wave; const int qtok = ((qb + r31) << dsh) + res;
;         bf16x8 qf[4];
; #pragma unroll
;         for (int ks = 0; ks < 4; ++ks) qf[ks] = *(const bf16x8*)(z + (size_t)qtok * NQKV + colq + 16 * ks + 8 * hh);
.Latt_kv_skip5:
	s_or_b64 exec, exec, s[70:71]
	s_add_i32 s93, s93, s94
	v_or_b32_e32 v0, s93, v186
	v_lshlrev_b32_e32 v0, s1, v0
	v_add_u32_e32 v176, s75, v0
	v_mov_b64_e32 v[0:1], s[80:81]
	v_mad_i64_i32 v[0:1], s[70:71], v176, s95, v[0:1]
	v_lshl_add_u64 v[0:1], s[72:73], 1, v[0:1]
	v_lshl_add_u64 v[4:5], v[82:83], 1, v[0:1]
	global_load_dwordx4 v[0:3], v[4:5], off
	global_load_dwordx4 v[178:181], v[4:5], off offset:32
	global_load_dwordx4 v[182:185], v[4:5], off offset:64
	global_load_dwordx4 v[206:209], v[4:5], off offset:96
	s_lshl_b32 s33, 1, s1
	s_lshl_b32 s70, s90, 3
	s_or_b32 s70, s97, s70
	s_add_i32 s70, s70, 1
	v_cvt_f32_i32_e32 v8, s70
	v_cvt_f32_u32_e32 v133, s33
	s_mov_b32 s33, 0xc2fc0000
	v_mul_f32_e32 v8, 0xc1000000, v8
	v_div_scale_f32 v9, s[70:71], s89, s89, v8
	v_rcp_f32_e32 v10, v9
	s_waitcnt vmcnt(4)
	v_add_u32_e32 v11, v188, v190
	ds_write_b128 v11, v[16:19] offset:49664
	ds_write_b16 v191, v20
	ds_write_b16_d16_hi v191, v20 offset:776
	ds_write_b16 v191, v21 offset:1552
	ds_write_b16_d16_hi v191, v21 offset:2328
	ds_write_b16 v191, v22 offset:3104
	ds_write_b16_d16_hi v191, v22 offset:3880
	ds_write_b16 v191, v23 offset:4656
	ds_write_b16_d16_hi v191, v23 offset:5432
	ds_write_b128 v194, v[24:27] offset:49664
	ds_write_b16 v191, v28 offset:128
	ds_write_b16_d16_hi v191, v28 offset:904
	ds_write_b16 v191, v29 offset:1680
	ds_write_b16_d16_hi v191, v29 offset:2456
	ds_write_b16 v191, v30 offset:3232
	ds_write_b16_d16_hi v191, v30 offset:4008
	ds_write_b16 v191, v31 offset:4784
	ds_write_b16_d16_hi v191, v31 offset:5560
	ds_write_b128 v195, v[32:35] offset:49664
	ds_write_b16 v191, v36 offset:256
	ds_write_b16_d16_hi v191, v36 offset:1032
	ds_write_b16 v191, v37 offset:1808
	ds_write_b16_d16_hi v191, v37 offset:2584
	ds_write_b16 v191, v38 offset:3360
	ds_write_b16_d16_hi v191, v38 offset:4136
	ds_write_b16 v191, v39 offset:4912
	ds_write_b16_d16_hi v191, v39 offset:5688
	ds_write_b128 v196, v[40:43] offset:49664
	ds_write_b16 v191, v44 offset:384
	ds_write_b16_d16_hi v191, v44 offset:1160
	ds_write_b16 v191, v45 offset:1936
	ds_write_b16_d16_hi v191, v45 offset:2712
	ds_write_b16 v191, v46 offset:3488
	ds_write_b16_d16_hi v191, v46 offset:4264
	ds_write_b16 v191, v47 offset:5040
	ds_write_b16_d16_hi v191, v47 offset:5816
	ds_write_b128 v202, v[48:51] offset:49664
	ds_write_b16 v191, v52 offset:512
	ds_write_b16_d16_hi v191, v52 offset:1288
	ds_write_b16 v191, v53 offset:2064
	ds_write_b16_d16_hi v191, v53 offset:2840
	ds_write_b16 v191, v54 offset:3616
	ds_write_b16_d16_hi v191, v54 offset:4392
	ds_write_b16 v191, v55 offset:5168
	ds_write_b16_d16_hi v191, v55 offset:5944
	ds_write_b128 v202, v[56:59] offset:58880
	ds_write_b16 v191, v60 offset:640
	ds_write_b16_d16_hi v191, v60 offset:1416
	ds_write_b16 v191, v61 offset:2192
	ds_write_b16_d16_hi v191, v61 offset:2968
	ds_write_b16 v191, v62 offset:3744
	ds_write_b16_d16_hi v191, v62 offset:4520
	ds_write_b16 v191, v63 offset:5296
	ds_write_b16_d16_hi v191, v63 offset:6072
	s_waitcnt lgkmcnt(0)
	s_barrier
	v_fma_f32 v11, -v9, v10, 1.0
	v_fmac_f32_e32 v10, v11, v10
	v_div_scale_f32 v11, vcc, v8, s89, v8
	v_mul_f32_e32 v12, v11, v10
	v_fma_f32 v13, -v9, v12, v11
	v_fmac_f32_e32 v12, v13, v10
	v_fma_f32 v9, -v9, v12, v11
	v_div_fmas_f32 v9, v9, v10, v12
	v_div_fixup_f32 v8, v9, s89, v8
	v_cmp_gt_f32_e32 vcc, s33, v8
	s_and_b64 s[70:71], vcc, exec
	s_cselect_b32 s33, 0xffffffc0, 0
	v_cndmask_b32_e32 v15, 0, v203, vcc
	v_add_f32_e32 v15, v8, v15
	v_exp_f32_e32 v15, v15
	s_nop 0
	v_ldexp_f32 v177, v15, s33
	ds_read_b128 v[4:7], v197 offset:49664
	ds_read_b128 v[8:11], v197 offset:49696
	s_lshr_b32 s1, 64, s1
	s_add_i32 s1, s1, -1
	s_cmp_eq_u32 s74, s1
	s_cselect_b64 s[70:71], -1, 0
	s_cmp_eq_u32 s74, 0
	s_cselect_b64 s[72:73], -1, 0
	s_or_b64 s[70:71], s[72:73], s[70:71]
	s_andn2_b64 vcc, exec, s[70:71]
	s_waitcnt vmcnt(3) lgkmcnt(1)
	v_mfma_f32_32x32x16_bf16 v[64:79], v[4:7], v[0:3], 0
	ds_read_b128 v[4:7], v197 offset:49728
	s_waitcnt vmcnt(2) lgkmcnt(1)
	v_mfma_f32_32x32x16_bf16 v[64:79], v[8:11], v[178:181], v[64:79]
	s_waitcnt vmcnt(1) lgkmcnt(0)
	v_mfma_f32_32x32x16_bf16 v[64:79], v[4:7], v[182:185], v[64:79]
	ds_read_b128 v[4:7], v197 offset:49760
	s_waitcnt vmcnt(0) lgkmcnt(0)
	v_mfma_f32_32x32x16_bf16 v[64:79], v[4:7], v[206:209], v[64:79]
	ds_read_b128 v[4:7], v198 offset:49664
	ds_read_b128 v[8:11], v198 offset:49696
	s_waitcnt lgkmcnt(1)
	v_mfma_f32_32x32x16_bf16 v[48:63], v[4:7], v[0:3], 0
	ds_read_b128 v[4:7], v198 offset:49728
	s_waitcnt lgkmcnt(1)
	v_mfma_f32_32x32x16_bf16 v[48:63], v[8:11], v[178:181], v[48:63]
	s_waitcnt lgkmcnt(0)
	v_mfma_f32_32x32x16_bf16 v[48:63], v[4:7], v[182:185], v[48:63]
	ds_read_b128 v[4:7], v198 offset:49760
	s_waitcnt lgkmcnt(0)
	v_mfma_f32_32x32x16_bf16 v[48:63], v[4:7], v[206:209], v[48:63]
	ds_read_b128 v[4:7], v199 offset:49664
	ds_read_b128 v[8:11], v199 offset:49696
	s_waitcnt lgkmcnt(1)
	v_mfma_f32_32x32x16_bf16 v[32:47], v[4:7], v[0:3], 0
	ds_read_b128 v[4:7], v199 offset:49728
	s_waitcnt lgkmcnt(1)
	v_mfma_f32_32x32x16_bf16 v[32:47], v[8:11], v[178:181], v[32:47]
	s_waitcnt lgkmcnt(0)
	v_mfma_f32_32x32x16_bf16 v[32:47], v[4:7], v[182:185], v[32:47]
	ds_read_b128 v[4:7], v199 offset:49760
	s_waitcnt lgkmcnt(0)
	v_mfma_f32_32x32x16_bf16 v[32:47], v[4:7], v[206:209], v[32:47]
	ds_read_b128 v[4:7], v200 offset:49664
	ds_read_b128 v[8:11], v200 offset:49696
	s_waitcnt lgkmcnt(1)
	v_mfma_f32_32x32x16_bf16 v[16:31], v[4:7], v[0:3], 0
	ds_read_b128 v[4:7], v200 offset:49728
	s_waitcnt lgkmcnt(1)
	v_mfma_f32_32x32x16_bf16 v[16:31], v[8:11], v[178:181], v[16:31]
	s_waitcnt lgkmcnt(0)
; #define LAS __attribute__((address_space(3)))
; __device__ __forceinline__ void ph_attn2(Ctx& C) {
;     ...
;         for (int kt = 0; kt < 5; ++kt) {
; #pragma unroll
;             for (int e = 0; e < 16; ++e) sacc[kt][e] = 0.f;
;             const LAS bf16* kp = kim + (32 * wave + 32 * kt + r31) * 72 + 8 * hh;
; #pragma unroll
;             for (int ks = 0; ks < 4; ++ks) { const bf16x8 kf = *(const LAS bf16x8*)(kp + 16 * ks); sacc[kt] = __builtin_amdgcn_mfma_f32_32x32x16_bf16(kf, qf[ks], sacc[kt], 0, 0, 0); } }
;         const float LOG2E = 1.44269504f, slope2 = slope_d * LOG2E, c0f = (float)(4 * hh - 64 - r31);
;         const bool edge = (tl == 0) || (tl == (n >> 8) - 1);
;         float m = -3.0e38f;
; #pragma unroll
;         for (int kt = 0; kt < 5; ++kt)
; #pragma unroll
;             for (int e = 0; e < 16; ++e) { const float relf = (float)(32 * kt + (e & 3) + 8 * (e >> 2)) + c0f; float sc = sacc[kt][e] * LOG2E - slope2 * __builtin_fabsf(relf);
;                 if (kt == 0) sc = relf >= -64.0f ? sc : -1e30f;
;                 if (kt == 4) sc = relf <= 64.0f ? sc : -1e30f;
;                 sacc[kt][e] = sc; }
	v_mfma_f32_32x32x16_bf16 v[16:31], v[4:7], v[182:185], v[16:31]
	ds_read_b128 v[4:7], v200 offset:49760
	s_waitcnt lgkmcnt(0)
	v_mfma_f32_32x32x16_bf16 v[16:31], v[4:7], v[206:209], v[16:31]
	ds_read_b128 v[4:7], v201 offset:49664
	ds_read_b128 v[210:213], v201 offset:49696
	s_waitcnt lgkmcnt(1)
	v_mfma_f32_32x32x16_bf16 v[0:15], v[4:7], v[0:3], 0
	s_waitcnt lgkmcnt(0)
	v_mfma_f32_32x32x16_bf16 v[0:15], v[210:213], v[178:181], v[0:15]
	ds_read_b128 v[178:181], v201 offset:49728
	s_waitcnt lgkmcnt(0)
	v_mfma_f32_32x32x16_bf16 v[0:15], v[178:181], v[182:185], v[0:15]
	ds_read_b128 v[178:181], v201 offset:49760
	s_waitcnt lgkmcnt(0)
	v_mfma_f32_32x32x16_bf16 v[0:15], v[178:181], v[206:209], v[0:15]
	v_mul_f32_e32 v179, v177, v133
	v_and_b32_e32 v133, 0x7fffffff, v87
	s_nop 9
	v_mov_b32_e32 v178, v15
	v_pk_mul_f32 v[184:185], v[178:179], s[88:89] op_sel_hi:[1,0]
	s_nop 0
	v_pk_mul_f32 v[178:179], v[132:133], v[184:185] op_sel:[0,1]
	s_nop 0
	v_pk_fma_f32 v[64:65], v[64:65], s[88:89], v[178:179] op_sel_hi:[1,0,1] neg_lo:[0,0,1] neg_hi:[0,0,1]
	s_nop 0
	v_cndmask_b32_e64 v15, v204, v65, s[6:7]
	v_cndmask_b32_e64 v177, v204, v64, s[4:5]
	v_mov_b32_e32 v64, v66
	v_mov_b32_e32 v65, v185
	v_pk_mul_f32 v[64:65], v[88:89], v[64:65]
	v_and_b32_e32 v66, 0x7fffffff, v90
	v_sub_f32_e32 v64, v64, v65
	v_cndmask_b32_e64 v133, v204, v64, s[8:9]
	v_mov_b32_e32 v64, v67
	v_and_b32_e32 v67, 0x7fffffff, v91
	v_mov_b32_e32 v65, v68
	v_pk_mul_f32 v[66:67], v[66:67], v[184:185] op_sel:[0,1]
	s_nop 0
	v_pk_fma_f32 v[64:65], v[64:65], s[88:89], v[66:67] op_sel_hi:[1,0,1] neg_lo:[0,0,1] neg_hi:[0,0,1]
	v_and_b32_e32 v67, 0x7fffffff, v93
	v_and_b32_e32 v66, 0x7fffffff, v92
	v_cndmask_b32_e64 v205, v204, v65, s[10:11]
	v_cndmask_b32_e64 v206, v204, v64, s[12:13]
	v_mov_b32_e32 v64, v69
	v_mov_b32_e32 v65, v70
	v_pk_mul_f32 v[66:67], v[66:67], v[184:185] op_sel:[0,1]
	s_nop 0
	v_pk_fma_f32 v[64:65], v[64:65], s[88:89], v[66:67] op_sel_hi:[1,0,1] neg_lo:[0,0,1] neg_hi:[0,0,1]
	v_and_b32_e32 v67, 0x7fffffff, v95
	v_and_b32_e32 v66, 0x7fffffff, v94
	v_cndmask_b32_e64 v207, v204, v65, s[14:15]
	v_cndmask_b32_e64 v208, v204, v64, s[16:17]
	v_mov_b32_e32 v64, v71
	v_mov_b32_e32 v65, v72
	v_pk_mul_f32 v[66:67], v[66:67], v[184:185] op_sel:[0,1]
	s_nop 0
	v_pk_fma_f32 v[64:65], v[64:65], s[88:89], v[66:67] op_sel_hi:[1,0,1] neg_lo:[0,0,1] neg_hi:[0,0,1]
	v_and_b32_e32 v67, 0x7fffffff, v97
	v_and_b32_e32 v66, 0x7fffffff, v96
	v_cndmask_b32_e64 v209, v204, v65, s[18:19]
	v_cndmask_b32_e64 v210, v204, v64, s[20:21]
	v_mov_b32_e32 v64, v73
	v_mov_b32_e32 v65, v74
	v_pk_mul_f32 v[66:67], v[66:67], v[184:185] op_sel:[0,1]
	s_nop 0
	v_pk_fma_f32 v[64:65], v[64:65], s[88:89], v[66:67] op_sel_hi:[1,0,1] neg_lo:[0,0,1] neg_hi:[0,0,1]
	v_and_b32_e32 v67, 0x7fffffff, v99
	v_and_b32_e32 v66, 0x7fffffff, v98
	v_cndmask_b32_e64 v211, v204, v65, s[22:23]
	v_cndmask_b32_e64 v212, v204, v64, s[24:25]
	v_mov_b32_e32 v64, v75
	v_mov_b32_e32 v65, v76
	v_pk_mul_f32 v[66:67], v[66:67], v[184:185] op_sel:[0,1]
	s_nop 0
	v_pk_fma_f32 v[64:65], v[64:65], s[88:89], v[66:67] op_sel_hi:[1,0,1] neg_lo:[0,0,1] neg_hi:[0,0,1]
	v_and_b32_e32 v67, 0x7fffffff, v101
	v_and_b32_e32 v66, 0x7fffffff, v100
	v_cndmask_b32_e64 v223, v204, v65, s[26:27]
	v_cndmask_b32_e64 v224, v204, v64, s[28:29]
	v_mov_b32_e32 v64, v77
	v_mov_b32_e32 v65, v78
	v_pk_mul_f32 v[66:67], v[66:67], v[184:185] op_sel:[0,1]
	s_nop 0
	v_pk_fma_f32 v[64:65], v[64:65], s[88:89], v[66:67] op_sel_hi:[1,0,1] neg_lo:[0,0,1] neg_hi:[0,0,1]
	s_nop 0
	v_cndmask_b32_e64 v225, v204, v65, s[30:31]
	v_cndmask_b32_e64 v226, v204, v64, s[34:35]
	v_mov_b32_e32 v64, v79
	v_mov_b32_e32 v65, v185
	v_pk_mul_f32 v[64:65], v[102:103], v[64:65]
	s_nop 0
	v_sub_f32_e32 v64, v64, v65
	v_cndmask_b32_e64 v227, v204, v64, s[36:37]
	v_pk_mul_f32 v[64:65], v[134:135], v[184:185] op_sel:[0,1]
	s_nop 0
	v_pk_fma_f32 v[64:65], v[48:49], s[88:89], v[64:65] op_sel_hi:[1,0,1] neg_lo:[0,0,1] neg_hi:[0,0,1]
	v_mov_b32_e32 v48, v50
	v_mov_b32_e32 v49, v185
	v_mul_f32_e32 v50, v105, v185
	v_pk_fma_f32 v[66:67], v[104:105], v[48:49], v[50:51] op_sel_hi:[1,1,0] neg_lo:[0,0,1] neg_hi:[0,0,1]
	v_mov_b32_e32 v48, v51
	v_mov_b32_e32 v49, v52
	v_pk_mul_f32 v[50:51], v[136:137], v[184:185] op_sel:[0,1]
	s_nop 0
	v_pk_fma_f32 v[70:71], v[48:49], s[88:89], v[50:51] op_sel_hi:[1,0,1] neg_lo:[0,0,1] neg_hi:[0,0,1]
	v_mov_b32_e32 v48, v53
	v_mov_b32_e32 v49, v54
	v_pk_mul_f32 v[50:51], v[138:139], v[184:185] op_sel:[0,1]
	s_nop 0
	v_pk_fma_f32 v[68:69], v[48:49], s[88:89], v[50:51] op_sel_hi:[1,0,1] neg_lo:[0,0,1] neg_hi:[0,0,1]
	v_mov_b32_e32 v48, v55
	v_mov_b32_e32 v49, v56
	v_pk_mul_f32 v[50:51], v[140:141], v[184:185] op_sel:[0,1]
	s_nop 0
	v_pk_fma_f32 v[72:73], v[48:49], s[88:89], v[50:51] op_sel_hi:[1,0,1] neg_lo:[0,0,1] neg_hi:[0,0,1]
	v_mov_b32_e32 v48, v57
	v_mov_b32_e32 v49, v58
	v_pk_mul_f32 v[50:51], v[142:143], v[184:185] op_sel:[0,1]
	s_nop 0
	v_pk_fma_f32 v[56:57], v[48:49], s[88:89], v[50:51] op_sel_hi:[1,0,1] neg_lo:[0,0,1] neg_hi:[0,0,1]
	v_mov_b32_e32 v48, v59
	v_mov_b32_e32 v49, v60
	v_pk_mul_f32 v[50:51], v[144:145], v[184:185] op_sel:[0,1]
	s_nop 0
	v_pk_fma_f32 v[74:75], v[48:49], s[88:89], v[50:51] op_sel_hi:[1,0,1] neg_lo:[0,0,1] neg_hi:[0,0,1]
	v_mov_b32_e32 v48, v61
	v_mov_b32_e32 v49, v62
	v_pk_mul_f32 v[50:51], v[146:147], v[184:185] op_sel:[0,1]
	s_nop 0
	v_pk_fma_f32 v[58:59], v[48:49], s[88:89], v[50:51] op_sel_hi:[1,0,1] neg_lo:[0,0,1] neg_hi:[0,0,1]
	v_mov_b32_e32 v48, v63
	v_mov_b32_e32 v49, v185
	v_mul_f32_e32 v50, v107, v185
	v_pk_fma_f32 v[178:179], v[106:107], v[48:49], v[50:51] op_sel_hi:[1,1,0] neg_lo:[0,0,1] neg_hi:[0,0,1]
; __device__ __forceinline__ void ph_attn2(Ctx& C) {
;     ...
;         for (int kt = 0; kt < 5; ++kt)
; #pragma unroll
;             for (int e = 0; e < 16; ++e) { const float relf = (float)(32 * kt + (e & 3) + 8 * (e >> 2)) + c0f; float sc = sacc[kt][e] * LOG2E - slope2 * __builtin_fabsf(relf);
;                 if (kt == 0) sc = relf >= -64.0f ? sc : -1e30f;
;                 if (kt == 4) sc = relf <= 64.0f ? sc : -1e30f;
;                 sacc[kt][e] = sc; }
	v_pk_mul_f32 v[48:49], v[148:149], v[184:185] op_sel:[0,1]
	s_nop 0
	v_pk_fma_f32 v[54:55], v[32:33], s[88:89], v[48:49] op_sel_hi:[1,0,1] neg_lo:[0,0,1] neg_hi:[0,0,1]
	v_mov_b32_e32 v32, v34
	v_mov_b32_e32 v33, v185
	v_mul_f32_e32 v34, v109, v185
	v_pk_fma_f32 v[60:61], v[108:109], v[32:33], v[34:35] op_sel_hi:[1,1,0] neg_lo:[0,0,1] neg_hi:[0,0,1]
	v_mov_b32_e32 v32, v35
	v_mov_b32_e32 v33, v36
	v_pk_mul_f32 v[34:35], v[150:151], v[184:185] op_sel:[0,1]
	s_nop 0
	v_pk_fma_f32 v[76:77], v[32:33], s[88:89], v[34:35] op_sel_hi:[1,0,1] neg_lo:[0,0,1] neg_hi:[0,0,1]
	v_mov_b32_e32 v32, v37
	v_mov_b32_e32 v33, v38
	v_pk_mul_f32 v[34:35], v[152:153], v[184:185] op_sel:[0,1]
	s_nop 0
	v_pk_fma_f32 v[62:63], v[32:33], s[88:89], v[34:35] op_sel_hi:[1,0,1] neg_lo:[0,0,1] neg_hi:[0,0,1]
	v_mov_b32_e32 v32, v39
	v_mov_b32_e32 v33, v40
	v_pk_mul_f32 v[34:35], v[154:155], v[184:185] op_sel:[0,1]
	s_nop 0
	v_pk_fma_f32 v[180:181], v[32:33], s[88:89], v[34:35] op_sel_hi:[1,0,1] neg_lo:[0,0,1] neg_hi:[0,0,1]
	v_mov_b32_e32 v32, v41
	v_mov_b32_e32 v33, v42
	v_pk_mul_f32 v[34:35], v[156:157], v[184:185] op_sel:[0,1]
	s_nop 0
	v_pk_fma_f32 v[78:79], v[32:33], s[88:89], v[34:35] op_sel_hi:[1,0,1] neg_lo:[0,0,1] neg_hi:[0,0,1]
	v_mov_b32_e32 v32, v43
	v_mov_b32_e32 v33, v44
	v_pk_mul_f32 v[34:35], v[158:159], v[184:185] op_sel:[0,1]
	s_nop 0
	v_pk_fma_f32 v[182:183], v[32:33], s[88:89], v[34:35] op_sel_hi:[1,0,1] neg_lo:[0,0,1] neg_hi:[0,0,1]
	v_mov_b32_e32 v32, v45
	v_mov_b32_e32 v33, v46
	v_pk_mul_f32 v[34:35], v[160:161], v[184:185] op_sel:[0,1]
	s_nop 0
	v_pk_fma_f32 v[50:51], v[32:33], s[88:89], v[34:35] op_sel_hi:[1,0,1] neg_lo:[0,0,1] neg_hi:[0,0,1]
	v_mov_b32_e32 v32, v47
	v_mov_b32_e32 v33, v185
	v_mul_f32_e32 v34, v111, v185
	v_pk_fma_f32 v[52:53], v[110:111], v[32:33], v[34:35] op_sel_hi:[1,1,0] neg_lo:[0,0,1] neg_hi:[0,0,1]
	v_pk_mul_f32 v[32:33], v[162:163], v[184:185] op_sel:[0,1]
	s_nop 0
	v_pk_fma_f32 v[46:47], v[16:17], s[88:89], v[32:33] op_sel_hi:[1,0,1] neg_lo:[0,0,1] neg_hi:[0,0,1]
	v_mov_b32_e32 v16, v18
	v_mov_b32_e32 v17, v185
	v_mul_f32_e32 v18, v113, v185
	v_pk_fma_f32 v[48:49], v[112:113], v[16:17], v[18:19] op_sel_hi:[1,1,0] neg_lo:[0,0,1] neg_hi:[0,0,1]
	v_mov_b32_e32 v16, v19
	v_mov_b32_e32 v17, v20
	v_pk_mul_f32 v[18:19], v[164:165], v[184:185] op_sel:[0,1]
	s_nop 0
	v_pk_fma_f32 v[44:45], v[16:17], s[88:89], v[18:19] op_sel_hi:[1,0,1] neg_lo:[0,0,1] neg_hi:[0,0,1]
	v_mov_b32_e32 v16, v21
	v_mov_b32_e32 v17, v22
	v_pk_mul_f32 v[18:19], v[166:167], v[184:185] op_sel:[0,1]
	s_nop 0
	v_pk_fma_f32 v[42:43], v[16:17], s[88:89], v[18:19] op_sel_hi:[1,0,1] neg_lo:[0,0,1] neg_hi:[0,0,1]
	v_mov_b32_e32 v16, v23
	v_mov_b32_e32 v17, v24
	v_pk_mul_f32 v[18:19], v[168:169], v[184:185] op_sel:[0,1]
	s_nop 0
	v_pk_fma_f32 v[38:39], v[16:17], s[88:89], v[18:19] op_sel_hi:[1,0,1] neg_lo:[0,0,1] neg_hi:[0,0,1]
	v_mov_b32_e32 v16, v25
	v_mov_b32_e32 v17, v26
	v_pk_mul_f32 v[18:19], v[170:171], v[184:185] op_sel:[0,1]
	s_nop 0
	v_pk_fma_f32 v[40:41], v[16:17], s[88:89], v[18:19] op_sel_hi:[1,0,1] neg_lo:[0,0,1] neg_hi:[0,0,1]
	v_mov_b32_e32 v16, v27
	v_mov_b32_e32 v17, v28
	v_pk_mul_f32 v[18:19], v[172:173], v[184:185] op_sel:[0,1]
	s_nop 0
	v_pk_fma_f32 v[34:35], v[16:17], s[88:89], v[18:19] op_sel_hi:[1,0,1] neg_lo:[0,0,1] neg_hi:[0,0,1]
	v_mov_b32_e32 v16, v29
	v_mov_b32_e32 v17, v30
	v_pk_mul_f32 v[18:19], v[174:175], v[184:185] op_sel:[0,1]
	s_nop 0
	v_pk_fma_f32 v[36:37], v[16:17], s[88:89], v[18:19] op_sel_hi:[1,0,1] neg_lo:[0,0,1] neg_hi:[0,0,1]
	v_mov_b32_e32 v16, v31
	v_mov_b32_e32 v17, v185
	v_mul_f32_e32 v18, v115, v185
	v_pk_fma_f32 v[32:33], v[114:115], v[16:17], v[18:19] op_sel_hi:[1,1,0] neg_lo:[0,0,1] neg_hi:[0,0,1]
	v_and_b32_e32 v17, 0x7fffffff, v117
	v_and_b32_e32 v16, 0x7fffffff, v116
	v_pk_mul_f32 v[16:17], v[16:17], v[184:185] op_sel:[0,1]
	s_nop 0
	v_pk_fma_f32 v[0:1], v[0:1], s[88:89], v[16:17] op_sel_hi:[1,0,1] neg_lo:[0,0,1] neg_hi:[0,0,1]
	s_nop 0
	v_cndmask_b32_e64 v220, v204, v1, s[38:39]
	v_cndmask_b32_e64 v221, v204, v0, s[40:41]
	v_mov_b32_e32 v0, v2
	v_mov_b32_e32 v1, v185
	v_pk_mul_f32 v[0:1], v[118:119], v[0:1]
	v_and_b32_e32 v2, 0x7fffffff, v120
	v_sub_f32_e32 v0, v0, v1
	v_cndmask_b32_e64 v222, v204, v0, s[42:43]
	v_mov_b32_e32 v0, v3
	v_and_b32_e32 v3, 0x7fffffff, v121
	v_mov_b32_e32 v1, v4
	v_pk_mul_f32 v[2:3], v[2:3], v[184:185] op_sel:[0,1]
	s_nop 0
	v_pk_fma_f32 v[0:1], v[0:1], s[88:89], v[2:3] op_sel_hi:[1,0,1] neg_lo:[0,0,1] neg_hi:[0,0,1]
	v_and_b32_e32 v3, 0x7fffffff, v123
	v_and_b32_e32 v2, 0x7fffffff, v122
	v_cndmask_b32_e64 v217, v204, v1, s[44:45]
	v_cndmask_b32_e64 v218, v204, v0, s[46:47]
	v_mov_b32_e32 v0, v5
	v_mov_b32_e32 v1, v6
	v_pk_mul_f32 v[2:3], v[2:3], v[184:185] op_sel:[0,1]
	s_nop 0
	v_pk_fma_f32 v[0:1], v[0:1], s[88:89], v[2:3] op_sel_hi:[1,0,1] neg_lo:[0,0,1] neg_hi:[0,0,1]
	v_and_b32_e32 v3, 0x7fffffff, v125
	v_and_b32_e32 v2, 0x7fffffff, v124
	v_cndmask_b32_e64 v214, v204, v1, s[48:49]
	v_cndmask_b32_e64 v219, v204, v0, s[50:51]
	v_mov_b32_e32 v0, v7
	v_mov_b32_e32 v1, v8
	v_pk_mul_f32 v[2:3], v[2:3], v[184:185] op_sel:[0,1]
	s_nop 0
	v_pk_fma_f32 v[0:1], v[0:1], s[88:89], v[2:3] op_sel_hi:[1,0,1] neg_lo:[0,0,1] neg_hi:[0,0,1]
	v_and_b32_e32 v3, 0x7fffffff, v127
	v_and_b32_e32 v2, 0x7fffffff, v126
	v_cndmask_b32_e64 v67, v204, v1, s[52:53]
	v_cndmask_b32_e64 v213, v204, v0, s[54:55]
	v_mov_b32_e32 v0, v9
	v_mov_b32_e32 v1, v10
	v_pk_mul_f32 v[2:3], v[2:3], v[184:185] op_sel:[0,1]
	s_nop 0
	v_pk_fma_f32 v[0:1], v[0:1], s[88:89], v[2:3] op_sel_hi:[1,0,1] neg_lo:[0,0,1] neg_hi:[0,0,1]
	v_and_b32_e32 v3, 0x7fffffff, v129
	v_and_b32_e32 v2, 0x7fffffff, v128
	v_cndmask_b32_e64 v53, v204, v1, s[56:57]
	v_cndmask_b32_e64 v216, v204, v0, s[58:59]
	v_mov_b32_e32 v0, v11
	v_mov_b32_e32 v1, v12
	v_pk_mul_f32 v[2:3], v[2:3], v[184:185] op_sel:[0,1]
	s_nop 0
	v_pk_fma_f32 v[0:1], v[0:1], s[88:89], v[2:3] op_sel_hi:[1,0,1] neg_lo:[0,0,1] neg_hi:[0,0,1]
	v_and_b32_e32 v3, 0x7fffffff, v131
	v_and_b32_e32 v2, 0x7fffffff, v130
	v_cndmask_b32_e64 v49, v204, v1, s[60:61]
	v_cndmask_b32_e64 v215, v204, v0, s[62:63]
	v_mov_b32_e32 v0, v13
	v_mov_b32_e32 v1, v14
	v_pk_mul_f32 v[2:3], v[2:3], v[184:185] op_sel:[0,1]
	s_nop 0
	v_pk_fma_f32 v[0:1], v[0:1], s[88:89], v[2:3] op_sel_hi:[1,0,1] neg_lo:[0,0,1] neg_hi:[0,0,1]
	s_nop 0
	v_cndmask_b32_e64 v179, v204, v0, s[66:67]
	v_fma_f32 v0, -|v192|, v185, v184
	v_cndmask_b32_e64 v61, v204, v1, s[64:65]
	v_cndmask_b32_e64 v33, v204, v0, s[68:69]
	s_cbranch_vccnz .LBB0_324
; __device__ __forceinline__ void ph_attn2(Ctx& C) {
;     ...
;         if (edge) {
; #pragma unroll
;             for (int kt = 0; kt < 5; ++kt)
; #pragma unroll
;                 for (int e = 0; e < 16; ++e) { const int kidx = qb - 64 + 32 * kt + (e & 3) + 8 * (e >> 2) + 4 * hh; sacc[kt][e] = (kidx >= 0 && kidx < n) ? sacc[kt][e] : -1e30f; } }
	v_add_u32_e32 v0, s93, v189
	v_cmp_gt_i32_e32 vcc, s91, v0
	v_cmp_lt_i32_e64 s[72:73], -1, v0
	s_and_b64 vcc, s[72:73], vcc
	v_or_b32_e32 v2, 1, v0
	v_cndmask_b32_e32 v177, v204, v177, vcc
	v_cmp_gt_i32_e32 vcc, s91, v2
	s_and_b64 vcc, s[72:73], vcc
	v_or_b32_e32 v2, 2, v0
	v_cndmask_b32_e32 v15, v204, v15, vcc
	v_cmp_gt_i32_e32 vcc, s91, v2
	s_and_b64 vcc, s[72:73], vcc
	v_or_b32_e32 v2, 3, v0
	v_add_u32_e32 v1, 8, v0
	v_cndmask_b32_e32 v133, v204, v133, vcc
	v_cmp_gt_i32_e32 vcc, s91, v2
	v_cmp_lt_i32_e64 s[70:71], -1, v1
	v_cmp_gt_i32_e64 s[74:75], s91, v1
	s_and_b64 vcc, s[72:73], vcc
	v_cndmask_b32_e32 v206, v204, v206, vcc
	s_and_b64 vcc, s[70:71], s[74:75]
	v_add_u32_e32 v2, 9, v0
	v_cndmask_b32_e32 v205, v204, v205, vcc
	v_add_u32_e32 v1, 10, v0
	v_cmp_lt_i32_e32 vcc, -1, v2
	v_cmp_gt_i32_e64 s[72:73], s91, v2
	v_cmp_lt_i32_e64 s[70:71], -1, v1
	v_cmp_gt_i32_e64 s[74:75], s91, v1
	s_and_b64 vcc, vcc, s[72:73]
	v_cndmask_b32_e32 v208, v204, v208, vcc
	s_and_b64 vcc, s[70:71], s[74:75]
	v_add_u32_e32 v2, 11, v0
	v_cndmask_b32_e32 v207, v204, v207, vcc
	v_add_u32_e32 v1, 16, v0
	v_cmp_lt_i32_e32 vcc, -1, v2
	v_cmp_gt_i32_e64 s[72:73], s91, v2
	v_cmp_lt_i32_e64 s[70:71], -1, v1
	v_cmp_gt_i32_e64 s[74:75], s91, v1
	s_and_b64 vcc, vcc, s[72:73]
	v_cndmask_b32_e32 v210, v204, v210, vcc
	s_and_b64 vcc, s[70:71], s[74:75]
	v_add_u32_e32 v2, 17, v0
	v_cndmask_b32_e32 v209, v204, v209, vcc
	v_add_u32_e32 v1, 18, v0
	v_cmp_lt_i32_e32 vcc, -1, v2
	v_cmp_gt_i32_e64 s[72:73], s91, v2
	v_cmp_lt_i32_e64 s[70:71], -1, v1
	v_cmp_gt_i32_e64 s[74:75], s91, v1
	s_and_b64 vcc, vcc, s[72:73]
	v_cndmask_b32_e32 v212, v204, v212, vcc
	s_and_b64 vcc, s[70:71], s[74:75]
	v_add_u32_e32 v2, 19, v0
	v_cndmask_b32_e32 v211, v204, v211, vcc
	v_add_u32_e32 v1, 24, v0
	v_cmp_lt_i32_e32 vcc, -1, v2
	v_cmp_gt_i32_e64 s[72:73], s91, v2
	v_cmp_lt_i32_e64 s[70:71], -1, v1
	v_cmp_gt_i32_e64 s[74:75], s91, v1
	s_and_b64 vcc, vcc, s[72:73]
	v_cndmask_b32_e32 v224, v204, v224, vcc
	s_and_b64 vcc, s[70:71], s[74:75]
	v_add_u32_e32 v2, 25, v0
	v_cndmask_b32_e32 v223, v204, v223, vcc
	v_add_u32_e32 v1, 26, v0
	v_cmp_lt_i32_e32 vcc, -1, v2
	v_cmp_gt_i32_e64 s[72:73], s91, v2
	v_cmp_lt_i32_e64 s[70:71], -1, v1
	v_cmp_gt_i32_e64 s[74:75], s91, v1
	s_and_b64 vcc, vcc, s[72:73]
	v_cndmask_b32_e32 v226, v204, v226, vcc
	s_and_b64 vcc, s[70:71], s[74:75]
	v_add_u32_e32 v1, 27, v0
	v_cndmask_b32_e32 v225, v204, v225, vcc
	v_cmp_lt_i32_e32 vcc, -1, v1
	v_cmp_gt_i32_e64 s[70:71], s91, v1
	s_and_b64 vcc, vcc, s[70:71]
	v_add_u32_e32 v2, 32, v0
	v_cndmask_b32_e32 v227, v204, v227, vcc
	v_cmp_gt_i32_e32 vcc, s91, v2
	v_cmp_lt_i32_e64 s[72:73], -1, v2
	s_and_b64 vcc, s[72:73], vcc
	v_or_b32_e32 v3, 1, v2
	v_cndmask_b32_e32 v64, v204, v64, vcc
	v_cmp_gt_i32_e32 vcc, s91, v3
	s_and_b64 vcc, s[72:73], vcc
	v_or_b32_e32 v3, 2, v2
	v_cndmask_b32_e32 v65, v204, v65, vcc
	v_cmp_gt_i32_e32 vcc, s91, v3
	s_and_b64 vcc, s[72:73], vcc
	v_or_b32_e32 v2, 3, v2
	v_add_u32_e32 v1, 40, v0
	v_cndmask_b32_e32 v66, v204, v66, vcc
	v_cmp_gt_i32_e32 vcc, s91, v2
	v_cmp_lt_i32_e64 s[70:71], -1, v1
	v_cmp_gt_i32_e64 s[74:75], s91, v1
	s_and_b64 vcc, s[72:73], vcc
	v_cndmask_b32_e32 v70, v204, v70, vcc
	s_and_b64 vcc, s[70:71], s[74:75]
	v_add_u32_e32 v2, 41, v0
	v_cndmask_b32_e32 v71, v204, v71, vcc
	v_add_u32_e32 v1, 42, v0
	v_cmp_lt_i32_e32 vcc, -1, v2
	v_cmp_gt_i32_e64 s[72:73], s91, v2
	v_cmp_lt_i32_e64 s[70:71], -1, v1
	v_cmp_gt_i32_e64 s[74:75], s91, v1
	s_and_b64 vcc, vcc, s[72:73]
	v_cndmask_b32_e32 v68, v204, v68, vcc
	s_and_b64 vcc, s[70:71], s[74:75]
	v_add_u32_e32 v2, 43, v0
	v_cndmask_b32_e32 v69, v204, v69, vcc
	v_add_u32_e32 v1, 48, v0
	v_cmp_lt_i32_e32 vcc, -1, v2
	v_cmp_gt_i32_e64 s[72:73], s91, v2
	v_cmp_lt_i32_e64 s[70:71], -1, v1
	v_cmp_gt_i32_e64 s[74:75], s91, v1
	s_and_b64 vcc, vcc, s[72:73]
	v_cndmask_b32_e32 v72, v204, v72, vcc
	s_and_b64 vcc, s[70:71], s[74:75]
	v_add_u32_e32 v2, 49, v0
	v_cndmask_b32_e32 v73, v204, v73, vcc
	v_add_u32_e32 v1, 50, v0
	v_cmp_lt_i32_e32 vcc, -1, v2
	v_cmp_gt_i32_e64 s[72:73], s91, v2
	v_cmp_lt_i32_e64 s[70:71], -1, v1
	v_cmp_gt_i32_e64 s[74:75], s91, v1
	s_and_b64 vcc, vcc, s[72:73]
	v_cndmask_b32_e32 v56, v204, v56, vcc
	s_and_b64 vcc, s[70:71], s[74:75]
	v_add_u32_e32 v2, 51, v0
	v_cndmask_b32_e32 v57, v204, v57, vcc
	v_add_u32_e32 v1, 56, v0
	v_cmp_lt_i32_e32 vcc, -1, v2
	v_cmp_gt_i32_e64 s[72:73], s91, v2
	v_cmp_lt_i32_e64 s[70:71], -1, v1
	v_cmp_gt_i32_e64 s[74:75], s91, v1
	s_and_b64 vcc, vcc, s[72:73]
	v_cndmask_b32_e32 v74, v204, v74, vcc
	s_and_b64 vcc, s[70:71], s[74:75]
	v_add_u32_e32 v2, 57, v0
	v_cndmask_b32_e32 v75, v204, v75, vcc
	v_add_u32_e32 v1, 58, v0
	v_cmp_lt_i32_e32 vcc, -1, v2
	v_cmp_gt_i32_e64 s[72:73], s91, v2
	v_cmp_lt_i32_e64 s[70:71], -1, v1
	v_cmp_gt_i32_e64 s[74:75], s91, v1
	s_and_b64 vcc, vcc, s[72:73]
	v_cndmask_b32_e32 v58, v204, v58, vcc
	s_and_b64 vcc, s[70:71], s[74:75]
	v_add_u32_e32 v1, 59, v0
	v_cndmask_b32_e32 v59, v204, v59, vcc
	v_cmp_lt_i32_e32 vcc, -1, v1
	v_cmp_gt_i32_e64 s[70:71], s91, v1
	s_and_b64 vcc, vcc, s[70:71]
	v_add_u32_e32 v2, s93, v84
	v_cndmask_b32_e32 v178, v204, v178, vcc
	v_cmp_gt_i32_e32 vcc, s91, v2
	v_cmp_lt_i32_e64 s[72:73], -1, v2
	s_and_b64 vcc, s[72:73], vcc
	v_or_b32_e32 v3, 1, v2
	v_cndmask_b32_e32 v54, v204, v54, vcc
	v_cmp_gt_i32_e32 vcc, s91, v3
	s_and_b64 vcc, s[72:73], vcc
	v_or_b32_e32 v3, 2, v2
	v_cndmask_b32_e32 v55, v204, v55, vcc
	v_cmp_gt_i32_e32 vcc, s91, v3
	s_and_b64 vcc, s[72:73], vcc
	v_or_b32_e32 v3, 3, v2
	v_add_u32_e32 v1, 0x48, v0
	v_cndmask_b32_e32 v60, v204, v60, vcc
	v_cmp_gt_i32_e32 vcc, s91, v3
	v_cmp_lt_i32_e64 s[70:71], -1, v1
	v_cmp_gt_i32_e64 s[74:75], s91, v1
; __device__ __forceinline__ void ph_attn2(Ctx& C) {
;     ...
;         if (edge) {
; #pragma unroll
;             for (int kt = 0; kt < 5; ++kt)
; #pragma unroll
;                 for (int e = 0; e < 16; ++e) { const int kidx = qb - 64 + 32 * kt + (e & 3) + 8 * (e >> 2) + 4 * hh; sacc[kt][e] = (kidx >= 0 && kidx < n) ? sacc[kt][e] : -1e30f; } }
	s_and_b64 vcc, s[72:73], vcc
	v_cndmask_b32_e32 v76, v204, v76, vcc
	s_and_b64 vcc, s[70:71], s[74:75]
	v_add_u32_e32 v3, 9, v2
	v_cndmask_b32_e32 v77, v204, v77, vcc
	v_add_u32_e32 v1, 10, v2
	v_cmp_lt_i32_e32 vcc, -1, v3
	v_cmp_gt_i32_e64 s[72:73], s91, v3
	v_cmp_lt_i32_e64 s[70:71], -1, v1
	v_cmp_gt_i32_e64 s[74:75], s91, v1
	s_and_b64 vcc, vcc, s[72:73]
	v_cndmask_b32_e32 v62, v204, v62, vcc
	s_and_b64 vcc, s[70:71], s[74:75]
	v_add_u32_e32 v3, 11, v2
	v_cndmask_b32_e32 v63, v204, v63, vcc
	v_add_u32_e32 v1, 0x50, v0
	v_cmp_lt_i32_e32 vcc, -1, v3
	v_cmp_gt_i32_e64 s[72:73], s91, v3
	v_cmp_lt_i32_e64 s[70:71], -1, v1
	v_cmp_gt_i32_e64 s[74:75], s91, v1
	s_and_b64 vcc, vcc, s[72:73]
	v_cndmask_b32_e32 v180, v204, v180, vcc
	s_and_b64 vcc, s[70:71], s[74:75]
	v_add_u32_e32 v3, 17, v2
	v_cndmask_b32_e32 v181, v204, v181, vcc
	v_add_u32_e32 v1, 18, v2
	v_cmp_lt_i32_e32 vcc, -1, v3
	v_cmp_gt_i32_e64 s[72:73], s91, v3
	v_cmp_lt_i32_e64 s[70:71], -1, v1
	v_cmp_gt_i32_e64 s[74:75], s91, v1
	s_and_b64 vcc, vcc, s[72:73]
	v_cndmask_b32_e32 v78, v204, v78, vcc
	s_and_b64 vcc, s[70:71], s[74:75]
	v_add_u32_e32 v3, 19, v2
	v_cndmask_b32_e32 v79, v204, v79, vcc
	v_add_u32_e32 v1, 0x58, v0
	v_cmp_lt_i32_e32 vcc, -1, v3
	v_cmp_gt_i32_e64 s[72:73], s91, v3
	v_cmp_lt_i32_e64 s[70:71], -1, v1
	v_cmp_gt_i32_e64 s[74:75], s91, v1
	s_and_b64 vcc, vcc, s[72:73]
	v_cndmask_b32_e32 v182, v204, v182, vcc
	s_and_b64 vcc, s[70:71], s[74:75]
	v_add_u32_e32 v3, 25, v2
	v_cndmask_b32_e32 v183, v204, v183, vcc
	v_add_u32_e32 v1, 26, v2
	v_cmp_lt_i32_e32 vcc, -1, v3
	v_cmp_gt_i32_e64 s[72:73], s91, v3
	v_cmp_lt_i32_e64 s[70:71], -1, v1
	v_cmp_gt_i32_e64 s[74:75], s91, v1
	s_and_b64 vcc, vcc, s[72:73]
	v_cndmask_b32_e32 v50, v204, v50, vcc
	s_and_b64 vcc, s[70:71], s[74:75]
	v_add_u32_e32 v1, 27, v2
	v_cndmask_b32_e32 v51, v204, v51, vcc
	v_cmp_lt_i32_e32 vcc, -1, v1
	v_cmp_gt_i32_e64 s[70:71], s91, v1
	s_and_b64 vcc, vcc, s[70:71]
	v_add_u32_e32 v2, 0x60, v0
	v_cndmask_b32_e32 v52, v204, v52, vcc
	v_cmp_gt_i32_e32 vcc, s91, v2
	v_cmp_lt_i32_e64 s[72:73], -1, v2
	s_and_b64 vcc, s[72:73], vcc
	v_or_b32_e32 v3, 1, v2
	v_cndmask_b32_e32 v46, v204, v46, vcc
	v_cmp_gt_i32_e32 vcc, s91, v3
	s_and_b64 vcc, s[72:73], vcc
	v_or_b32_e32 v3, 2, v2
	v_cndmask_b32_e32 v47, v204, v47, vcc
	v_cmp_gt_i32_e32 vcc, s91, v3
	s_and_b64 vcc, s[72:73], vcc
	v_or_b32_e32 v2, 3, v2
	v_add_u32_e32 v1, 0x68, v0
	v_cndmask_b32_e32 v48, v204, v48, vcc
	v_cmp_gt_i32_e32 vcc, s91, v2
	v_cmp_lt_i32_e64 s[70:71], -1, v1
	v_cmp_gt_i32_e64 s[74:75], s91, v1
	s_and_b64 vcc, s[72:73], vcc
	v_cndmask_b32_e32 v44, v204, v44, vcc
	s_and_b64 vcc, s[70:71], s[74:75]
	v_add_u32_e32 v2, 0x69, v0
	v_cndmask_b32_e32 v45, v204, v45, vcc
	v_add_u32_e32 v1, 0x6a, v0
	v_cmp_lt_i32_e32 vcc, -1, v2
	v_cmp_gt_i32_e64 s[72:73], s91, v2
	v_cmp_lt_i32_e64 s[70:71], -1, v1
	v_cmp_gt_i32_e64 s[74:75], s91, v1
	s_and_b64 vcc, vcc, s[72:73]
	v_cndmask_b32_e32 v42, v204, v42, vcc
	s_and_b64 vcc, s[70:71], s[74:75]
	v_add_u32_e32 v2, 0x6b, v0
	v_cndmask_b32_e32 v43, v204, v43, vcc
	v_add_u32_e32 v1, 0x70, v0
	v_cmp_lt_i32_e32 vcc, -1, v2
	v_cmp_gt_i32_e64 s[72:73], s91, v2
	v_cmp_lt_i32_e64 s[70:71], -1, v1
	v_cmp_gt_i32_e64 s[74:75], s91, v1
	s_and_b64 vcc, vcc, s[72:73]
	v_cndmask_b32_e32 v38, v204, v38, vcc
	s_and_b64 vcc, s[70:71], s[74:75]
	v_add_u32_e32 v2, 0x71, v0
	v_cndmask_b32_e32 v39, v204, v39, vcc
	v_add_u32_e32 v1, 0x72, v0
	v_cmp_lt_i32_e32 vcc, -1, v2
	v_cmp_gt_i32_e64 s[72:73], s91, v2
	v_cmp_lt_i32_e64 s[70:71], -1, v1
	v_cmp_gt_i32_e64 s[74:75], s91, v1
; __device__ __forceinline__ void ph_attn2(Ctx& C) {
;     ...
;         if (edge) {
; #pragma unroll
;             for (int kt = 0; kt < 5; ++kt)
; #pragma unroll
;                 for (int e = 0; e < 16; ++e) { const int kidx = qb - 64 + 32 * kt + (e & 3) + 8 * (e >> 2) + 4 * hh; sacc[kt][e] = (kidx >= 0 && kidx < n) ? sacc[kt][e] : -1e30f; } }
	s_and_b64 vcc, vcc, s[72:73]
	v_cndmask_b32_e32 v40, v204, v40, vcc
	s_and_b64 vcc, s[70:71], s[74:75]
	v_add_u32_e32 v2, 0x73, v0
	v_cndmask_b32_e32 v41, v204, v41, vcc
	v_add_u32_e32 v1, 0x78, v0
	v_cmp_lt_i32_e32 vcc, -1, v2
	v_cmp_gt_i32_e64 s[72:73], s91, v2
	v_cmp_lt_i32_e64 s[70:71], -1, v1
	v_cmp_gt_i32_e64 s[74:75], s91, v1
	s_and_b64 vcc, vcc, s[72:73]
	v_cndmask_b32_e32 v34, v204, v34, vcc
	s_and_b64 vcc, s[70:71], s[74:75]
	v_add_u32_e32 v2, 0x79, v0
	v_cndmask_b32_e32 v35, v204, v35, vcc
	v_add_u32_e32 v1, 0x7a, v0
	v_cmp_lt_i32_e32 vcc, -1, v2
	v_cmp_gt_i32_e64 s[72:73], s91, v2
	v_cmp_lt_i32_e64 s[70:71], -1, v1
	v_cmp_gt_i32_e64 s[74:75], s91, v1
	s_and_b64 vcc, vcc, s[72:73]
	v_cndmask_b32_e32 v36, v204, v36, vcc
	s_and_b64 vcc, s[70:71], s[74:75]
	v_add_u32_e32 v1, 0x7b, v0
	v_cndmask_b32_e32 v37, v204, v37, vcc
	v_cmp_lt_i32_e32 vcc, -1, v1
	v_cmp_gt_i32_e64 s[70:71], s91, v1
	s_and_b64 vcc, vcc, s[70:71]
	v_add_u32_e32 v2, 0x80, v0
	v_cndmask_b32_e32 v32, v204, v32, vcc
	v_cmp_gt_i32_e32 vcc, s91, v2
	v_cmp_lt_i32_e64 s[72:73], -1, v2
	s_and_b64 vcc, s[72:73], vcc
	v_or_b32_e32 v3, 1, v2
	v_cndmask_b32_e32 v221, v204, v221, vcc
	v_cmp_gt_i32_e32 vcc, s91, v3
	s_and_b64 vcc, s[72:73], vcc
	v_or_b32_e32 v3, 2, v2
	v_cndmask_b32_e32 v220, v204, v220, vcc
	v_cmp_gt_i32_e32 vcc, s91, v3
	s_and_b64 vcc, s[72:73], vcc
	v_or_b32_e32 v2, 3, v2
	v_add_u32_e32 v1, 0x88, v0
	v_cndmask_b32_e32 v222, v204, v222, vcc
	v_cmp_gt_i32_e32 vcc, s91, v2
	v_cmp_lt_i32_e64 s[70:71], -1, v1
	v_cmp_gt_i32_e64 s[74:75], s91, v1
	s_and_b64 vcc, s[72:73], vcc
	v_cndmask_b32_e32 v218, v204, v218, vcc
	s_and_b64 vcc, s[70:71], s[74:75]
	v_add_u32_e32 v2, 0x89, v0
	v_cndmask_b32_e32 v217, v204, v217, vcc
	v_add_u32_e32 v1, 0x8a, v0
	v_cmp_lt_i32_e32 vcc, -1, v2
	v_cmp_gt_i32_e64 s[72:73], s91, v2
	v_cmp_lt_i32_e64 s[70:71], -1, v1
	v_cmp_gt_i32_e64 s[74:75], s91, v1
	s_and_b64 vcc, vcc, s[72:73]
	v_cndmask_b32_e32 v219, v204, v219, vcc
	s_and_b64 vcc, s[70:71], s[74:75]
	v_add_u32_e32 v2, 0x8b, v0
	v_cndmask_b32_e32 v214, v204, v214, vcc
	v_add_u32_e32 v1, 0x90, v0
	v_cmp_lt_i32_e32 vcc, -1, v2
	v_cmp_gt_i32_e64 s[72:73], s91, v2
	v_cmp_lt_i32_e64 s[70:71], -1, v1
	v_cmp_gt_i32_e64 s[74:75], s91, v1
	s_and_b64 vcc, vcc, s[72:73]
	v_cndmask_b32_e32 v213, v204, v213, vcc
	s_and_b64 vcc, s[70:71], s[74:75]
	v_add_u32_e32 v2, 0x91, v0
	v_cndmask_b32_e32 v67, v204, v67, vcc
	v_add_u32_e32 v1, 0x92, v0
	v_cmp_lt_i32_e32 vcc, -1, v2
	v_cmp_gt_i32_e64 s[72:73], s91, v2
	v_cmp_lt_i32_e64 s[70:71], -1, v1
	v_cmp_gt_i32_e64 s[74:75], s91, v1
	s_and_b64 vcc, vcc, s[72:73]
	v_cndmask_b32_e32 v216, v204, v216, vcc
	s_and_b64 vcc, s[70:71], s[74:75]
	v_add_u32_e32 v2, 0x93, v0
	v_cndmask_b32_e32 v53, v204, v53, vcc
	v_add_u32_e32 v1, 0x98, v0
	v_cmp_lt_i32_e32 vcc, -1, v2
	v_cmp_gt_i32_e64 s[72:73], s91, v2
	v_cmp_lt_i32_e64 s[70:71], -1, v1
	v_cmp_gt_i32_e64 s[74:75], s91, v1
	s_and_b64 vcc, vcc, s[72:73]
	v_cndmask_b32_e32 v215, v204, v215, vcc
	s_and_b64 vcc, s[70:71], s[74:75]
	v_add_u32_e32 v2, 0x99, v0
	v_cndmask_b32_e32 v49, v204, v49, vcc
	v_add_u32_e32 v1, 0x9a, v0
	v_cmp_lt_i32_e32 vcc, -1, v2
	v_cmp_gt_i32_e64 s[72:73], s91, v2
	v_cmp_lt_i32_e64 s[70:71], -1, v1
	v_cmp_gt_i32_e64 s[74:75], s91, v1
	s_and_b64 vcc, vcc, s[72:73]
	v_cndmask_b32_e32 v179, v204, v179, vcc
	s_and_b64 vcc, s[70:71], s[74:75]
	v_add_u32_e32 v0, 0x9b, v0
	v_cndmask_b32_e32 v61, v204, v61, vcc
	v_cmp_lt_i32_e32 vcc, -1, v0
	v_cmp_gt_i32_e64 s[70:71], s91, v0
	s_and_b64 vcc, vcc, s[70:71]
	v_cndmask_b32_e32 v33, v204, v33, vcc

; #define RAW2(w) ((f32x2){__uint_as_float((w) << 16), __uint_as_float((w) & 0xffff0000u)})
; template <int role> __device__ __forceinline__ void ph_scan1m_r(Ctx& C) {
;     ...
;             const int sg0 = chunk * CHL + sb * 16; const long tk0 = z ? (long)S - 1 - sg0 : sg0; const long dtk = z ? -1 : 1;
;             asm volatile("s_waitcnt vmcnt(0)" ::: "memory");
;             int lane_i = lane0; asm volatile("" : "+v"(lane_i));
;             const int lane = lane_i, r31 = lane_i & 31, hh = lane_i >> 5, r31g = r31;
;             const long dix = dtk * RW;
;             const size_t rowu = (size_t)tk0 * RW + h * 64;
;             const int par = lane >> 5, c0 = 2 * (lane & 31), cme = c0 + par; const float pm = par ? 1.44269504f : 0.f;
;             f32x2 Lm[8], Lt[8], GT2;
;             { f32x2 bef = (f32x2){0.f, 0.f};
; #pragma unroll
;               for (int j = 0; j < 8; ++j) { auto sw = __builtin_amdgcn_permlane32_swap(rl[j], rl[j], false, false); asm volatile("s_nop 1" : "+v"(sw[0]), "+v"(sw[1]));
;                   const f32x2 e = RAW2(sw[0]), o = RAW2(sw[1]); const f32x2 be = bef + e;
;                   Lm[j] = bef * 1.44269504f + e * pm; Lt[j] = be * 1.44269504f + o * pm; bef = be + o; }
;               GT2 = (f32x2){__builtin_amdgcn_exp2f(bef.x * 1.44269504f), __builtin_amdgcn_exp2f(bef.y * 1.44269504f)}; }
.LBB0_709:
	s_waitcnt vmcnt(47)
	v_mov_b32_e32 v65, v142
	v_mov_b32_e32 v69, v142
	v_mov_b32_e32 v112, v140
	s_nop 0
	v_permlane32_swap_b32_e32 v65, v69
	s_waitcnt vmcnt(2)
	s_nop 1
	s_waitcnt vmcnt(43)
	v_lshlrev_b32_e32 v104, 16, v146
	v_lshlrev_b32_e32 v66, 16, v65
	v_and_b32_e32 v67, 0xffff0000, v65
	v_cmp_gt_u32_e32 vcc, 32, v112
	v_pk_add_f32 v[70:71], v[66:67], 0 op_sel_hi:[1,0]
	v_lshlrev_b32_e32 v68, 16, v69
	v_cndmask_b32_e64 v64, v141, 0, vcc
	v_and_b32_e32 v69, 0xffff0000, v69
	v_pk_mul_f32 v[72:73], v[70:71], s[24:25] op_sel_hi:[1,0]
	v_pk_fma_f32 v[66:67], v[64:65], v[66:67], 0 op_sel_hi:[0,1,0]
	v_pk_fma_f32 v[78:79], v[64:65], v[68:69], v[72:73] op_sel_hi:[0,1,1]
	s_waitcnt vmcnt(41)
	v_mov_b32_e32 v65, v148
	v_mov_b32_e32 v73, v148
	s_nop 1
	v_permlane32_swap_b32_e32 v65, v73
	v_pk_add_f32 v[68:69], v[70:71], v[68:69]
	s_nop 1
	v_and_b32_e32 v190, 31, v112
	v_lshlrev_b32_e32 v70, 16, v65
	v_and_b32_e32 v71, 0xffff0000, v65
	v_pk_add_f32 v[74:75], v[68:69], v[70:71]
	v_pk_mul_f32 v[70:71], v[64:65], v[70:71] op_sel_hi:[0,1]
	v_lshlrev_b32_e32 v72, 16, v73
	v_and_b32_e32 v73, 0xffff0000, v73
	v_pk_fma_f32 v[80:81], v[68:69], s[24:25], v[70:71] op_sel_hi:[1,0,1]
	v_pk_mul_f32 v[68:69], v[74:75], s[24:25] op_sel_hi:[1,0]
	v_ashrrev_i32_e32 v191, 5, v112
	v_pk_fma_f32 v[86:87], v[64:65], v[72:73], v[68:69] op_sel_hi:[0,1,1]
	v_pk_add_f32 v[68:69], v[74:75], v[72:73]
	s_waitcnt vmcnt(35)
	v_mov_b32_e32 v65, v154
	v_mov_b32_e32 v73, v154
	s_nop 1
	v_permlane32_swap_b32_e32 v65, v73
	s_nop 1
	v_exp_f32_e32 v66, v66
	v_lshlrev_b32_e32 v70, 16, v65
	v_and_b32_e32 v71, 0xffff0000, v65
	v_pk_add_f32 v[74:75], v[68:69], v[70:71]
	v_pk_mul_f32 v[70:71], v[64:65], v[70:71] op_sel_hi:[0,1]
	v_lshlrev_b32_e32 v72, 16, v73
	v_and_b32_e32 v73, 0xffff0000, v73
	v_pk_fma_f32 v[88:89], v[68:69], s[24:25], v[70:71] op_sel_hi:[1,0,1]
	v_pk_mul_f32 v[68:69], v[74:75], s[24:25] op_sel_hi:[1,0]
	v_exp_f32_e32 v67, v67
	v_pk_fma_f32 v[98:99], v[64:65], v[72:73], v[68:69] op_sel_hi:[0,1,1]
	v_pk_add_f32 v[68:69], v[74:75], v[72:73]
	s_waitcnt vmcnt(29)
	v_mov_b32_e32 v65, v160
	v_mov_b32_e32 v73, v160
	s_nop 1
	v_permlane32_swap_b32_e32 v65, v73
	s_nop 1
	v_and_b32_e32 v105, 0xffff0000, v146
	v_lshlrev_b32_e32 v70, 16, v65
	v_and_b32_e32 v71, 0xffff0000, v65
	v_pk_add_f32 v[74:75], v[68:69], v[70:71]
	v_pk_mul_f32 v[70:71], v[64:65], v[70:71] op_sel_hi:[0,1]
	v_lshlrev_b32_e32 v72, 16, v73
	v_and_b32_e32 v73, 0xffff0000, v73
	v_pk_fma_f32 v[94:95], v[68:69], s[24:25], v[70:71] op_sel_hi:[1,0,1]
	v_pk_mul_f32 v[68:69], v[74:75], s[24:25] op_sel_hi:[1,0]
	v_exp_f32_e32 v80, v80
	v_pk_fma_f32 v[96:97], v[64:65], v[72:73], v[68:69] op_sel_hi:[0,1,1]
	v_pk_add_f32 v[68:69], v[74:75], v[72:73]
	s_waitcnt vmcnt(23)
	v_mov_b32_e32 v65, v166
	v_mov_b32_e32 v73, v166
	s_nop 1
	v_permlane32_swap_b32_e32 v65, v73
	s_nop 1
	v_exp_f32_e32 v81, v81
	v_lshlrev_b32_e32 v70, 16, v65
	v_and_b32_e32 v71, 0xffff0000, v65
	v_pk_add_f32 v[74:75], v[68:69], v[70:71]
	v_pk_mul_f32 v[70:71], v[64:65], v[70:71] op_sel_hi:[0,1]
	v_lshlrev_b32_e32 v72, 16, v73
	v_and_b32_e32 v73, 0xffff0000, v73
	v_pk_fma_f32 v[90:91], v[68:69], s[24:25], v[70:71] op_sel_hi:[1,0,1]
	v_pk_mul_f32 v[68:69], v[74:75], s[24:25] op_sel_hi:[1,0]
	v_exp_f32_e32 v88, v88
	v_pk_fma_f32 v[92:93], v[64:65], v[72:73], v[68:69] op_sel_hi:[0,1,1]
	v_pk_add_f32 v[68:69], v[74:75], v[72:73]
	s_waitcnt vmcnt(17)
	v_mov_b32_e32 v65, v172
	v_mov_b32_e32 v73, v172
	s_nop 1
	v_permlane32_swap_b32_e32 v65, v73
	s_nop 1
	v_exp_f32_e32 v89, v89
	v_lshlrev_b32_e32 v70, 16, v65
	v_and_b32_e32 v71, 0xffff0000, v65
	v_pk_add_f32 v[74:75], v[68:69], v[70:71]
	v_pk_mul_f32 v[70:71], v[64:65], v[70:71] op_sel_hi:[0,1]
	v_lshlrev_b32_e32 v72, 16, v73
	v_and_b32_e32 v73, 0xffff0000, v73
	v_pk_fma_f32 v[82:83], v[68:69], s[24:25], v[70:71] op_sel_hi:[1,0,1]
	v_pk_mul_f32 v[68:69], v[74:75], s[24:25] op_sel_hi:[1,0]
	v_exp_f32_e32 v96, v96
	v_pk_fma_f32 v[84:85], v[64:65], v[72:73], v[68:69] op_sel_hi:[0,1,1]
	v_pk_add_f32 v[68:69], v[74:75], v[72:73]
	s_waitcnt vmcnt(11)
	v_mov_b32_e32 v65, v178
	v_mov_b32_e32 v73, v178
	s_nop 1
	v_permlane32_swap_b32_e32 v65, v73
	s_nop 1
	v_exp_f32_e32 v97, v97
	v_lshlrev_b32_e32 v70, 16, v65
	v_and_b32_e32 v71, 0xffff0000, v65
	v_pk_add_f32 v[100:101], v[68:69], v[70:71]
	v_pk_mul_f32 v[70:71], v[64:65], v[70:71] op_sel_hi:[0,1]
	v_lshlrev_b32_e32 v72, 16, v73
	v_and_b32_e32 v73, 0xffff0000, v73
	v_pk_fma_f32 v[74:75], v[68:69], s[24:25], v[70:71] op_sel_hi:[1,0,1]
	v_pk_mul_f32 v[68:69], v[100:101], s[24:25] op_sel_hi:[1,0]
	v_exp_f32_e32 v94, v94
	v_pk_fma_f32 v[76:77], v[64:65], v[72:73], v[68:69] op_sel_hi:[0,1,1]
	v_pk_add_f32 v[68:69], v[100:101], v[72:73]
	s_waitcnt vmcnt(5)
; #define LAS __attribute__((address_space(3)))
; __device__ __forceinline__ unsigned cvt_pk_bf16(float lo, float hi) { unsigned r; asm volatile("v_cvt_pk_bf16_f32 %0, %1, %2" : "=v"(r) : "v"(lo), "v"(hi)); return r; }
; #define RAW2(w) ((f32x2){__uint_as_float((w) << 16), __uint_as_float((w) & 0xffff0000u)})
; template <int role> __device__ __forceinline__ void ph_scan1m_r(Ctx& C) {
;     ...
;               GT2 = (f32x2){__builtin_amdgcn_exp2f(bef.x * 1.44269504f), __builtin_amdgcn_exp2f(bef.y * 1.44269504f)}; }
;             *(LAS f32x2*)(gT + c0) = GT2;
;             float bgx[8], bgy[8], kgx[8], kgy[8];
;             { LAS bf16* wKR = imKR + par * 72 + c0; LAS bf16* wBK = imBK + (8 * par) * 72 + c0;
; #pragma unroll
;               for (int j = 0; j < 8; ++j) {
;                   const f32x2 eL = (f32x2){__builtin_amdgcn_exp2f(Lt[j].x), __builtin_amdgcn_exp2f(Lt[j].y)}, eLm = (f32x2){__builtin_amdgcn_exp2f(Lm[j].x), __builtin_amdgcn_exp2f(Lm[j].y)};
;                   const f32x2 ie = (f32x2){__builtin_amdgcn_rcpf(eL.x), __builtin_amdgcn_rcpf(eL.y)};
;                   const f32x2 nk = RAW2(rn[j]), a_ = RAW2(ra[j]), rr = RAW2(rr_[j]);
;                   const f32x2 b_ = -nk * a_;
;                   const f32x2 kkh = nk * eLm, rh = rr * eL, bt = b_ * ie, bgf = bt * GT2;
;                   *(LAS unsigned*)(wKR + (2 * j) * 72) = pg8::cvt_pk_bf16(kkh.x, kkh.y); *(LAS unsigned*)(wKR + (16 + 2 * j) * 72) = pg8::cvt_pk_bf16(rh.x, rh.y);
;                   *(LAS unsigned*)(wBK + j * 72) = pg8::cvt_pk_bf16(bt.x, bt.y);
;                   f32x2 kgf = (f32x2){0.f, 0.f};
;                   if (role) { const f32x2 kr = RAW2(rk[j]); const f32x2 kd = kr * (a_ * ka2 + k1), kt_ = kd * ie; kgf = kt_ * GT2; *(LAS unsigned*)(wBK + (16 + j) * 72) = pg8::cvt_pk_bf16(kt_.x, kt_.y); }
;                   bgx[j] = bgf.x; bgy[j] = bgf.y; if (role) { kgx[j] = kgf.x; kgy[j] = kgf.y; } } }
	v_mov_b32_e32 v65, v184
	v_mov_b32_e32 v72, v184
	s_nop 1
	v_permlane32_swap_b32_e32 v65, v72
	s_nop 1
	v_exp_f32_e32 v95, v95
	v_lshlrev_b32_e32 v70, 16, v65
	v_and_b32_e32 v71, 0xffff0000, v65
	v_pk_add_f32 v[102:103], v[68:69], v[70:71]
	v_pk_mul_f32 v[70:71], v[64:65], v[70:71] op_sel_hi:[0,1]
	v_lshlrev_b32_e32 v100, 16, v72
	v_and_b32_e32 v101, 0xffff0000, v72
	v_pk_fma_f32 v[70:71], v[68:69], s[24:25], v[70:71] op_sel_hi:[1,0,1]
	v_pk_mul_f32 v[68:69], v[102:103], s[24:25] op_sel_hi:[1,0]
	v_exp_f32_e32 v92, v92
	v_pk_fma_f32 v[72:73], v[64:65], v[100:101], v[68:69] op_sel_hi:[0,1,1]
	v_pk_add_f32 v[64:65], v[102:103], v[100:101]
	v_lshl_add_u32 v68, v190, 3, s42
	v_mul_f32_e32 v64, 0x3fb8aa3b, v64
	v_mul_f32_e32 v65, 0x3fb8aa3b, v65
	v_exp_f32_e32 v64, v64
	v_exp_f32_e32 v65, v65
	v_lshlrev_b32_e32 v69, 2, v190
	v_lshlrev_b32_e32 v100, 16, v143
	v_and_b32_e32 v101, 0xffff0000, v143
	ds_write_b64 v68, v[64:65] offset:14336
	v_mul_lo_u32 v68, v191, s61
	v_add3_u32 v108, s42, v68, v69
	v_mul_lo_u32 v68, v191, s62
	v_add3_u32 v109, s42, v68, v69
	v_exp_f32_e32 v68, v78
	v_exp_f32_e32 v69, v79
	v_pk_mul_f32 v[66:67], v[66:67], v[100:101]
	v_lshlrev_b32_e32 v102, 16, v144
	v_rcp_f32_e32 v78, v68
	v_rcp_f32_e32 v79, v69
	v_and_b32_e32 v103, 0xffff0000, v144
	v_cvt_pk_bf16_f32 v66, v66, v67
	v_pk_mul_f32 v[106:107], v[102:103], v[100:101] neg_lo:[0,1] neg_hi:[0,1]
	v_pk_mul_f32 v[100:101], v[68:69], v[104:105]
	ds_write_b32 v108, v66
	v_cvt_pk_bf16_f32 v66, v100, v101
	v_pk_mul_f32 v[104:105], v[106:107], v[78:79]
	ds_write_b32 v108, v66 offset:2304
	v_cvt_pk_bf16_f32 v66, v104, v105
	ds_write_b32 v109, v66 offset:4608
	v_lshlrev_b32_e32 v66, 16, v145
	v_and_b32_e32 v67, 0xffff0000, v145
	v_pk_fma_f32 v[100:101], v[116:117], v[102:103], v[118:119]
	v_pk_mul_f32 v[68:69], v[104:105], v[64:65]
	v_pk_mul_f32 v[66:67], v[100:101], v[66:67]
	v_lshlrev_b32_e32 v100, 16, v149
	v_pk_mul_f32 v[78:79], v[66:67], v[78:79]
	v_and_b32_e32 v101, 0xffff0000, v149
	v_pk_mul_f32 v[66:67], v[78:79], v[64:65]
	v_cvt_pk_bf16_f32 v78, v78, v79
	ds_write_b32 v109, v78 offset:6912
	v_exp_f32_e32 v78, v86
	v_exp_f32_e32 v79, v87
	v_lshlrev_b32_e32 v102, 16, v150
	v_and_b32_e32 v103, 0xffff0000, v150
	v_rcp_f32_e32 v86, v78
	v_rcp_f32_e32 v87, v79
	v_lshlrev_b32_e32 v104, 16, v152
	v_and_b32_e32 v105, 0xffff0000, v152
	v_pk_mul_f32 v[106:107], v[102:103], v[100:101] neg_lo:[0,1] neg_hi:[0,1]
	v_pk_mul_f32 v[100:101], v[80:81], v[100:101]
	v_pk_mul_f32 v[78:79], v[78:79], v[104:105]
	v_cvt_pk_bf16_f32 v100, v100, v101
	ds_write_b32 v108, v100 offset:288
	v_cvt_pk_bf16_f32 v78, v78, v79
	v_pk_mul_f32 v[104:105], v[106:107], v[86:87]
	ds_write_b32 v108, v78 offset:2592
	v_cvt_pk_bf16_f32 v78, v104, v105
	ds_write_b32 v109, v78 offset:4752
	v_lshlrev_b32_e32 v78, 16, v151
	v_and_b32_e32 v79, 0xffff0000, v151
	v_pk_fma_f32 v[100:101], v[116:117], v[102:103], v[118:119]
	v_pk_mul_f32 v[80:81], v[104:105], v[64:65]
	v_pk_mul_f32 v[78:79], v[100:101], v[78:79]
	v_lshlrev_b32_e32 v100, 16, v155
	v_pk_mul_f32 v[86:87], v[78:79], v[86:87]
	v_and_b32_e32 v101, 0xffff0000, v155
	v_pk_mul_f32 v[78:79], v[86:87], v[64:65]
	v_cvt_pk_bf16_f32 v86, v86, v87
	ds_write_b32 v109, v86 offset:7056
	v_exp_f32_e32 v86, v98
	v_exp_f32_e32 v87, v99
	v_lshlrev_b32_e32 v102, 16, v156
	v_and_b32_e32 v103, 0xffff0000, v156
	v_rcp_f32_e32 v98, v86
	v_rcp_f32_e32 v99, v87
	v_lshlrev_b32_e32 v104, 16, v158
	v_and_b32_e32 v105, 0xffff0000, v158
	v_pk_mul_f32 v[106:107], v[102:103], v[100:101] neg_lo:[0,1] neg_hi:[0,1]
	v_pk_mul_f32 v[100:101], v[88:89], v[100:101]
	v_pk_mul_f32 v[86:87], v[86:87], v[104:105]
	v_cvt_pk_bf16_f32 v100, v100, v101
	ds_write_b32 v108, v100 offset:576
	v_cvt_pk_bf16_f32 v86, v86, v87
	v_pk_mul_f32 v[104:105], v[106:107], v[98:99]
	ds_write_b32 v108, v86 offset:2880
	v_cvt_pk_bf16_f32 v86, v104, v105
	ds_write_b32 v109, v86 offset:4896
	v_lshlrev_b32_e32 v86, 16, v157
	v_and_b32_e32 v87, 0xffff0000, v157
	v_pk_fma_f32 v[100:101], v[116:117], v[102:103], v[118:119]
	v_pk_mul_f32 v[88:89], v[104:105], v[64:65]
	v_pk_mul_f32 v[86:87], v[100:101], v[86:87]
	v_lshlrev_b32_e32 v100, 16, v161
	v_pk_mul_f32 v[98:99], v[86:87], v[98:99]
	v_and_b32_e32 v101, 0xffff0000, v161
	v_pk_mul_f32 v[86:87], v[98:99], v[64:65]
	v_cvt_pk_bf16_f32 v98, v98, v99
	ds_write_b32 v109, v98 offset:7200
	v_rcp_f32_e32 v98, v96
	v_rcp_f32_e32 v99, v97
	v_pk_mul_f32 v[94:95], v[94:95], v[100:101]
	v_lshlrev_b32_e32 v102, 16, v162
	v_and_b32_e32 v103, 0xffff0000, v162
	v_lshlrev_b32_e32 v104, 16, v164
	v_and_b32_e32 v105, 0xffff0000, v164
	v_cvt_pk_bf16_f32 v94, v94, v95
	v_pk_mul_f32 v[106:107], v[102:103], v[100:101] neg_lo:[0,1] neg_hi:[0,1]
	v_pk_mul_f32 v[100:101], v[96:97], v[104:105]
	ds_write_b32 v108, v94 offset:864
	v_cvt_pk_bf16_f32 v94, v100, v101
	v_pk_mul_f32 v[104:105], v[106:107], v[98:99]
	ds_write_b32 v108, v94 offset:3168
	v_cvt_pk_bf16_f32 v94, v104, v105
	ds_write_b32 v109, v94 offset:5040
	v_lshlrev_b32_e32 v94, 16, v163
	v_and_b32_e32 v95, 0xffff0000, v163
	v_pk_fma_f32 v[100:101], v[116:117], v[102:103], v[118:119]
	v_exp_f32_e32 v93, v93
	v_pk_mul_f32 v[94:95], v[100:101], v[94:95]
	v_exp_f32_e32 v90, v90
	v_exp_f32_e32 v91, v91
	v_pk_mul_f32 v[98:99], v[94:95], v[98:99]
	v_lshlrev_b32_e32 v100, 16, v167
	v_pk_mul_f32 v[94:95], v[98:99], v[64:65]
	v_cvt_pk_bf16_f32 v98, v98, v99
	ds_write_b32 v109, v98 offset:7344
	v_rcp_f32_e32 v98, v92
	v_rcp_f32_e32 v99, v93
	v_and_b32_e32 v101, 0xffff0000, v167
	v_pk_mul_f32 v[90:91], v[90:91], v[100:101]
	v_pk_mul_f32 v[96:97], v[104:105], v[64:65]
	v_lshlrev_b32_e32 v102, 16, v168
	v_and_b32_e32 v103, 0xffff0000, v168
; #define LAS __attribute__((address_space(3)))
; template <int role> __device__ __forceinline__ void ph_scan1m_r(Ctx& C) {
;     ...
;             float bgx[8], bgy[8], kgx[8], kgy[8];
;             { LAS bf16* wKR = imKR + par * 72 + c0; LAS bf16* wBK = imBK + (8 * par) * 72 + c0;
; #pragma unroll
;               for (int j = 0; j < 8; ++j) {
;                   const f32x2 eL = (f32x2){__builtin_amdgcn_exp2f(Lt[j].x), __builtin_amdgcn_exp2f(Lt[j].y)}, eLm = (f32x2){__builtin_amdgcn_exp2f(Lm[j].x), __builtin_amdgcn_exp2f(Lm[j].y)};
;                   const f32x2 ie = (f32x2){__builtin_amdgcn_rcpf(eL.x), __builtin_amdgcn_rcpf(eL.y)};
;                   const f32x2 nk = RAW2(rn[j]), a_ = RAW2(ra[j]), rr = RAW2(rr_[j]);
;                   const f32x2 b_ = -nk * a_;
;                   const f32x2 kkh = nk * eLm, rh = rr * eL, bt = b_ * ie, bgf = bt * GT2;
;                   *(LAS unsigned*)(wKR + (2 * j) * 72) = pg8::cvt_pk_bf16(kkh.x, kkh.y); *(LAS unsigned*)(wKR + (16 + 2 * j) * 72) = pg8::cvt_pk_bf16(rh.x, rh.y);
;                   *(LAS unsigned*)(wBK + j * 72) = pg8::cvt_pk_bf16(bt.x, bt.y);
;                   f32x2 kgf = (f32x2){0.f, 0.f};
;                   if (role) { const f32x2 kr = RAW2(rk[j]); const f32x2 kd = kr * (a_ * ka2 + k1), kt_ = kd * ie; kgf = kt_ * GT2; *(LAS unsigned*)(wBK + (16 + j) * 72) = pg8::cvt_pk_bf16(kt_.x, kt_.y); }
;                   bgx[j] = bgf.x; bgy[j] = bgf.y; if (role) { kgx[j] = kgf.x; kgy[j] = kgf.y; } } }
;             { u32x4 w0, w1;
; #pragma unroll
;               for (int q = 0; q < 4; ++q) { w0[q] = pg8::cvt_pk_bf16(bgx[2 * q], bgx[2 * q + 1]); w1[q] = pg8::cvt_pk_bf16(bgy[2 * q], bgy[2 * q + 1]); }
;               *(LAS u32x4*)(imBGT + c0 * 40 + 8 * par) = w0; *(LAS u32x4*)(imBGT + (c0 + 1) * 40 + 8 * par) = w1;
;               if (role) {
; #pragma unroll
;                   for (int q = 0; q < 4; ++q) { w0[q] = pg8::cvt_pk_bf16(kgx[2 * q], kgx[2 * q + 1]); w1[q] = pg8::cvt_pk_bf16(kgy[2 * q], kgy[2 * q + 1]); }
;                   *(LAS u32x4*)(imBGT + c0 * 40 + 16 + 8 * par) = w0; *(LAS u32x4*)(imBGT + (c0 + 1) * 40 + 16 + 8 * par) = w1;
; #pragma unroll
;                   for (int q = 0; q < 4; ++q) { w0[q] = __builtin_amdgcn_perm(rv[2 * q + 1], rv[2 * q], 0x05040100u); w1[q] = __builtin_amdgcn_perm(rv[2 * q + 1], rv[2 * q], 0x07060302u); }
	v_lshlrev_b32_e32 v104, 16, v170
	v_and_b32_e32 v105, 0xffff0000, v170
	v_cvt_pk_bf16_f32 v90, v90, v91
	v_pk_mul_f32 v[106:107], v[102:103], v[100:101] neg_lo:[0,1] neg_hi:[0,1]
	v_pk_mul_f32 v[92:93], v[92:93], v[104:105]
	ds_write_b32 v108, v90 offset:1152
	v_cvt_pk_bf16_f32 v90, v92, v93
	v_pk_mul_f32 v[100:101], v[106:107], v[98:99]
	ds_write_b32 v108, v90 offset:3456
	v_cvt_pk_bf16_f32 v90, v100, v101
	ds_write_b32 v109, v90 offset:5184
	v_lshlrev_b32_e32 v90, 16, v169
	v_and_b32_e32 v91, 0xffff0000, v169
	v_pk_fma_f32 v[92:93], v[116:117], v[102:103], v[118:119]
	v_exp_f32_e32 v84, v84
	v_exp_f32_e32 v85, v85
	v_pk_mul_f32 v[90:91], v[92:93], v[90:91]
	v_exp_f32_e32 v82, v82
	v_exp_f32_e32 v83, v83
	v_pk_mul_f32 v[90:91], v[90:91], v[98:99]
	v_lshlrev_b32_e32 v98, 16, v173
	v_pk_mul_f32 v[92:93], v[90:91], v[64:65]
	v_cvt_pk_bf16_f32 v90, v90, v91
	ds_write_b32 v109, v90 offset:7488
	v_rcp_f32_e32 v90, v84
	v_rcp_f32_e32 v91, v85
	v_and_b32_e32 v99, 0xffff0000, v173
	v_pk_mul_f32 v[82:83], v[82:83], v[98:99]
	v_pk_mul_f32 v[104:105], v[100:101], v[64:65]
	v_lshlrev_b32_e32 v100, 16, v174
	v_and_b32_e32 v101, 0xffff0000, v174
	v_lshlrev_b32_e32 v102, 16, v176
	v_and_b32_e32 v103, 0xffff0000, v176
	v_cvt_pk_bf16_f32 v82, v82, v83
	v_pk_mul_f32 v[106:107], v[100:101], v[98:99] neg_lo:[0,1] neg_hi:[0,1]
	v_pk_mul_f32 v[84:85], v[84:85], v[102:103]
	ds_write_b32 v108, v82 offset:1440
	v_cvt_pk_bf16_f32 v82, v84, v85
	v_pk_mul_f32 v[98:99], v[106:107], v[90:91]
	ds_write_b32 v108, v82 offset:3744
	v_cvt_pk_bf16_f32 v82, v98, v99
	ds_write_b32 v109, v82 offset:5328
	v_lshlrev_b32_e32 v82, 16, v175
	v_and_b32_e32 v83, 0xffff0000, v175
	v_pk_fma_f32 v[84:85], v[116:117], v[100:101], v[118:119]
	v_exp_f32_e32 v76, v76
	v_exp_f32_e32 v77, v77
	v_pk_mul_f32 v[82:83], v[84:85], v[82:83]
	v_exp_f32_e32 v74, v74
	v_exp_f32_e32 v75, v75
	v_pk_mul_f32 v[82:83], v[82:83], v[90:91]
	v_lshlrev_b32_e32 v90, 16, v179
	v_pk_mul_f32 v[84:85], v[82:83], v[64:65]
	v_cvt_pk_bf16_f32 v82, v82, v83
	ds_write_b32 v109, v82 offset:7632
	v_rcp_f32_e32 v82, v76
	v_rcp_f32_e32 v83, v77
	v_and_b32_e32 v91, 0xffff0000, v179
	v_pk_mul_f32 v[74:75], v[74:75], v[90:91]
	v_pk_mul_f32 v[102:103], v[98:99], v[64:65]
	v_lshlrev_b32_e32 v98, 16, v180
	v_and_b32_e32 v99, 0xffff0000, v180
	v_lshlrev_b32_e32 v100, 16, v182
	v_and_b32_e32 v101, 0xffff0000, v182
	v_cvt_pk_bf16_f32 v74, v74, v75
	v_pk_mul_f32 v[106:107], v[98:99], v[90:91] neg_lo:[0,1] neg_hi:[0,1]
	v_pk_mul_f32 v[76:77], v[76:77], v[100:101]
	ds_write_b32 v108, v74 offset:1728
	v_cvt_pk_bf16_f32 v74, v76, v77
	v_pk_mul_f32 v[90:91], v[106:107], v[82:83]
	ds_write_b32 v108, v74 offset:4032
	v_cvt_pk_bf16_f32 v74, v90, v91
	ds_write_b32 v109, v74 offset:5472
	v_lshlrev_b32_e32 v74, 16, v181
	v_and_b32_e32 v75, 0xffff0000, v181
	v_pk_fma_f32 v[76:77], v[116:117], v[98:99], v[118:119]
	v_exp_f32_e32 v72, v72
	v_exp_f32_e32 v73, v73
	v_pk_mul_f32 v[74:75], v[76:77], v[74:75]
	v_exp_f32_e32 v70, v70
	v_exp_f32_e32 v71, v71
	v_pk_mul_f32 v[74:75], v[74:75], v[82:83]
	s_waitcnt vmcnt(4)
	v_lshlrev_b32_e32 v82, 16, v185
	v_pk_mul_f32 v[76:77], v[64:65], v[74:75]
	v_cvt_pk_bf16_f32 v74, v74, v75
	ds_write_b32 v109, v74 offset:7776
	v_rcp_f32_e32 v74, v72
	v_rcp_f32_e32 v75, v73
	v_and_b32_e32 v83, 0xffff0000, v185
	v_pk_mul_f32 v[70:71], v[70:71], v[82:83]
	v_pk_mul_f32 v[100:101], v[64:65], v[90:91]
	s_waitcnt vmcnt(3)
	v_lshlrev_b32_e32 v90, 16, v186
	v_and_b32_e32 v91, 0xffff0000, v186
	s_waitcnt vmcnt(1)
	v_lshlrev_b32_e32 v98, 16, v188
	v_and_b32_e32 v99, 0xffff0000, v188
	v_cvt_pk_bf16_f32 v70, v70, v71
	v_pk_mul_f32 v[106:107], v[90:91], v[82:83] neg_lo:[0,1] neg_hi:[0,1]
	v_pk_mul_f32 v[72:73], v[72:73], v[98:99]
	ds_write_b32 v108, v70 offset:2016
	v_cvt_pk_bf16_f32 v70, v72, v73
	v_pk_mul_f32 v[82:83], v[106:107], v[74:75]
	ds_write_b32 v108, v70 offset:4320
	v_cvt_pk_bf16_f32 v70, v82, v83
	ds_write_b32 v109, v70 offset:5616
	v_lshlrev_b32_e32 v70, 16, v187
	v_and_b32_e32 v71, 0xffff0000, v187
	v_pk_fma_f32 v[72:73], v[116:117], v[90:91], v[118:119]
	v_pk_mul_f32 v[98:99], v[64:65], v[82:83]
	v_pk_mul_f32 v[70:71], v[72:73], v[70:71]
	s_add_i32 s79, s22, s72
	v_pk_mul_f32 v[70:71], v[70:71], v[74:75]
	s_add_i32 s2, s75, 16
	v_pk_mul_f32 v[82:83], v[64:65], v[70:71]
	v_cvt_pk_bf16_f32 v64, v70, v71
	ds_write_b32 v109, v64 offset:7920
	v_cvt_pk_bf16_f32 v68, v68, v80
	v_cvt_pk_bf16_f32 v72, v69, v81
	v_cvt_pk_bf16_f32 v69, v88, v96
	v_cvt_pk_bf16_f32 v73, v89, v97
	v_cvt_pk_bf16_f32 v70, v104, v102
	v_lshlrev_b32_e32 v104, 4, v191
	v_add_u32_e32 v192, s42, v104
	v_lshl_or_b32 v81, v190, 1, 1
	v_mad_u32_u24 v80, v190, s63, v192
	v_mad_u32_u24 v88, v81, s64, v192
	v_cvt_pk_bf16_f32 v74, v105, v103
	v_cvt_pk_bf16_f32 v71, v100, v98
	v_cvt_pk_bf16_f32 v75, v101, v99
	ds_write_b128 v80, v[68:71] offset:9216
	ds_write_b128 v88, v[72:75] offset:9216
	v_cvt_pk_bf16_f32 v64, v66, v78
	v_cvt_pk_bf16_f32 v68, v67, v79
	v_cvt_pk_bf16_f32 v65, v86, v94
	v_cvt_pk_bf16_f32 v69, v87, v95
	v_cvt_pk_bf16_f32 v66, v92, v84
	v_cvt_pk_bf16_f32 v70, v93, v85
	v_cvt_pk_bf16_f32 v67, v76, v82
	v_cvt_pk_bf16_f32 v71, v77, v83
	ds_write_b128 v80, v[64:67] offset:9248
	ds_write_b128 v88, v[68:71] offset:9248
	v_perm_b32 v64, v153, v147, s65
	v_perm_b32 v65, v165, v159, s65
	v_perm_b32 v66, v177, v171, s65
	s_waitcnt vmcnt(0)
	v_perm_b32 v67, v189, v183, s65
	v_mad_u32_u24 v72, v190, s67, v192
	v_perm_b32 v68, v153, v147, s66
	v_perm_b32 v69, v165, v159, s66
	v_perm_b32 v70, v177, v171, s66
	v_perm_b32 v71, v189, v183, s66
	ds_write_b128 v72, v[64:67] offset:14592
	v_mad_u32_u24 v64, v81, 48, v192
	ds_write_b128 v64, v[68:71] offset:14592
	s_waitcnt lgkmcnt(0)
	s_and_b64 s[0:1], s[30:31], exec
	s_cselect_b32 s38, s79, s2
	v_lshlrev_b32_e32 v193, 3, v191
	s_cmpk_eq_i32 s72, 0x1f0
	s_cbranch_scc1 .Lsc1_r1_noload
; template <int role> __device__ __forceinline__ void ph_scan1m_r(Ctx& C) {
;     ...
;             if (sb + 1 < CHL / 16) SM_LOADRAW(sb + 1);
	s_add_i32 s79, s79, 16
	s_and_b64 s[0:1], s[30:31], exec
	s_cselect_b32 s0, s79, s75
	s_ashr_i32 s1, s0, 31
	s_lshl_b64 s[0:1], s[0:1], 11
	s_or_b32 s0, s0, s78
	s_add_u32 s2, s27, s0
	s_addc_u32 s3, s29, s1
	s_add_u32 s4, s40, s0
	s_addc_u32 s5, s41, s1
	s_add_u32 s6, s70, s0
	s_addc_u32 s7, s71, s1
	s_add_u32 s8, s47, s0
	s_addc_u32 s9, s49, s1
	v_mov_b32_e32 v232, v140
	s_add_u32 s10, s43, s0
	s_addc_u32 s11, s44, s1
	v_ashrrev_i32_e32 v246, 5, v232
	v_ashrrev_i32_e32 v233, 31, v246
	v_lshlrev_b32_e32 v232, 1, v232
	s_add_u32 s12, s45, s0
	v_mov_b64_e32 v[244:245], s[36:37]
	v_and_b32_e32 v252, 62, v232
	s_addc_u32 s13, s46, s1
	v_mul_lo_u32 v247, s34, v233
	v_mul_lo_u32 v248, s35, v246
	v_mad_u64_u32 v[232:233], s[0:1], s34, v246, 0
	v_mad_u64_u32 v[244:245], s[0:1], s34, v246, v[244:245]
	v_add3_u32 v233, v233, v247, v248
	v_or_b32_e32 v232, v232, v252
	v_add3_u32 v245, v248, v245, v247
	v_lshlrev_b64 v[232:233], 1, v[232:233]
	v_or_b32_e32 v246, v244, v252
	v_mov_b32_e32 v247, v245
	v_lshl_add_u64 v[234:235], s[2:3], 0, v[232:233]
	v_lshl_add_u64 v[240:241], s[8:9], 0, v[232:233]
	v_lshlrev_b64 v[246:247], 1, v[246:247]
	v_lshl_add_u64 v[236:237], s[4:5], 0, v[232:233]
	v_lshl_add_u64 v[238:239], s[6:7], 0, v[232:233]
	v_lshl_add_u64 v[242:243], s[10:11], 0, v[232:233]
	v_lshl_add_u64 v[232:233], s[12:13], 0, v[232:233]
	v_lshl_add_u64 v[248:249], s[2:3], 0, v[246:247]
	v_lshl_add_u64 v[250:251], s[4:5], 0, v[246:247]
	global_load_dword v142, v[234:235], off
	global_load_dword v143, v[236:237], off
	global_load_dword v144, v[238:239], off
	global_load_dword v145, v[240:241], off
	global_load_dword v146, v[242:243], off
	global_load_dword v147, v[232:233], off
	global_load_dword v148, v[248:249], off
	global_load_dword v149, v[250:251], off
	v_lshl_add_u64 v[240:241], v[244:245], 0, s[36:37]
	v_or_b32_e32 v242, v240, v252
	v_mov_b32_e32 v243, v241
	v_lshl_add_u64 v[232:233], s[6:7], 0, v[246:247]
	v_lshl_add_u64 v[236:237], s[10:11], 0, v[246:247]
	v_lshlrev_b64 v[242:243], 1, v[242:243]
	v_lshl_add_u64 v[234:235], s[8:9], 0, v[246:247]
	v_lshl_add_u64 v[238:239], s[12:13], 0, v[246:247]
	v_lshl_add_u64 v[244:245], s[2:3], 0, v[242:243]
	v_lshl_add_u64 v[246:247], s[4:5], 0, v[242:243]
	v_lshl_add_u64 v[248:249], s[6:7], 0, v[242:243]
	v_lshl_add_u64 v[250:251], s[8:9], 0, v[242:243]
	global_load_dword v150, v[232:233], off
	global_load_dword v151, v[234:235], off
	global_load_dword v152, v[236:237], off
	global_load_dword v153, v[238:239], off
	global_load_dword v154, v[244:245], off
	global_load_dword v155, v[246:247], off
	global_load_dword v156, v[248:249], off
	global_load_dword v157, v[250:251], off
	v_lshl_add_u64 v[236:237], v[240:241], 0, s[36:37]
	v_or_b32_e32 v238, v236, v252
	v_mov_b32_e32 v239, v237
	v_lshl_add_u64 v[232:233], s[10:11], 0, v[242:243]
	v_lshlrev_b64 v[238:239], 1, v[238:239]
	v_lshl_add_u64 v[234:235], s[12:13], 0, v[242:243]
	v_lshl_add_u64 v[240:241], s[2:3], 0, v[238:239]
	v_lshl_add_u64 v[242:243], s[4:5], 0, v[238:239]
	v_lshl_add_u64 v[244:245], s[6:7], 0, v[238:239]
	v_lshl_add_u64 v[246:247], s[8:9], 0, v[238:239]
	v_lshl_add_u64 v[248:249], s[10:11], 0, v[238:239]
	v_lshl_add_u64 v[238:239], s[12:13], 0, v[238:239]
	global_load_dword v158, v[232:233], off
	global_load_dword v159, v[234:235], off
	global_load_dword v160, v[240:241], off
	global_load_dword v161, v[242:243], off
	global_load_dword v162, v[244:245], off
	global_load_dword v163, v[246:247], off
	global_load_dword v164, v[248:249], off
	global_load_dword v165, v[238:239], off
	v_lshl_add_u64 v[232:233], v[236:237], 0, s[36:37]
	v_or_b32_e32 v234, v232, v252
	v_mov_b32_e32 v235, v233
	v_lshl_add_u64 v[232:233], v[232:233], 0, s[36:37]
	v_lshlrev_b64 v[234:235], 1, v[234:235]
	v_or_b32_e32 v246, v232, v252
	v_mov_b32_e32 v247, v233
	v_lshl_add_u64 v[236:237], s[2:3], 0, v[234:235]
	v_lshl_add_u64 v[242:243], s[8:9], 0, v[234:235]
	v_lshlrev_b64 v[246:247], 1, v[246:247]
	v_lshl_add_u64 v[232:233], v[232:233], 0, s[36:37]
	v_lshl_add_u64 v[238:239], s[4:5], 0, v[234:235]
	v_lshl_add_u64 v[240:241], s[6:7], 0, v[234:235]
	v_lshl_add_u64 v[244:245], s[10:11], 0, v[234:235]
	v_lshl_add_u64 v[234:235], s[12:13], 0, v[234:235]
	v_lshl_add_u64 v[248:249], s[2:3], 0, v[246:247]
	v_lshl_add_u64 v[250:251], s[4:5], 0, v[246:247]
	global_load_dword v166, v[236:237], off
	global_load_dword v167, v[238:239], off
	global_load_dword v168, v[240:241], off
	global_load_dword v169, v[242:243], off
	global_load_dword v170, v[244:245], off
	global_load_dword v171, v[234:235], off
	global_load_dword v172, v[248:249], off
	global_load_dword v173, v[250:251], off
	v_or_b32_e32 v242, v232, v252
	v_mov_b32_e32 v243, v233
	v_lshl_add_u64 v[232:233], v[232:233], 0, s[36:37]
	v_lshl_add_u64 v[234:235], s[6:7], 0, v[246:247]
	v_lshlrev_b64 v[242:243], 1, v[242:243]
	v_or_b32_e32 v232, v232, v252
	v_lshl_add_u64 v[236:237], s[8:9], 0, v[246:247]
	v_lshl_add_u64 v[238:239], s[10:11], 0, v[246:247]
	v_lshl_add_u64 v[240:241], s[12:13], 0, v[246:247]
	v_lshl_add_u64 v[244:245], s[2:3], 0, v[242:243]
	v_lshl_add_u64 v[246:247], s[4:5], 0, v[242:243]
	v_lshl_add_u64 v[248:249], s[6:7], 0, v[242:243]
	v_lshl_add_u64 v[250:251], s[8:9], 0, v[242:243]
	global_load_dword v174, v[234:235], off
	global_load_dword v175, v[236:237], off
	global_load_dword v176, v[238:239], off
	global_load_dword v177, v[240:241], off
	global_load_dword v178, v[244:245], off
	global_load_dword v179, v[246:247], off
	global_load_dword v180, v[248:249], off
	global_load_dword v181, v[250:251], off
	v_lshl_add_u64 v[234:235], s[10:11], 0, v[242:243]
	v_lshlrev_b64 v[232:233], 1, v[232:233]
	v_lshl_add_u64 v[236:237], s[12:13], 0, v[242:243]
	v_lshl_add_u64 v[238:239], s[2:3], 0, v[232:233]
	v_lshl_add_u64 v[240:241], s[4:5], 0, v[232:233]
	v_lshl_add_u64 v[242:243], s[6:7], 0, v[232:233]
	v_lshl_add_u64 v[244:245], s[8:9], 0, v[232:233]
	v_lshl_add_u64 v[246:247], s[10:11], 0, v[232:233]
	v_lshl_add_u64 v[232:233], s[12:13], 0, v[232:233]
	global_load_dword v182, v[234:235], off
	global_load_dword v183, v[236:237], off
	global_load_dword v184, v[238:239], off
	global_load_dword v185, v[240:241], off
	global_load_dword v186, v[242:243], off
	global_load_dword v187, v[244:245], off
	global_load_dword v188, v[246:247], off
	global_load_dword v189, v[232:233], off
; #define LAS __attribute__((address_space(3)))
; template <int role> __device__ __forceinline__ void ph_scan1m_r(Ctx& C) {
;     ...
;             { f32x16 m;
; #pragma unroll
;               for (int e = 0; e < 16; ++e) m[e] = 0.f;
; #pragma unroll
;               for (int ks = 0; ks < 4; ++ks) { const bf16x8 af = *(const LAS bf16x8*)(imBK + r31 * 72 + 16 * ks + 8 * hh), bfr = *(const LAS bf16x8*)(imKR + r31 * 72 + 16 * ks + 8 * hh); m = __builtin_amdgcn_mfma_f32_32x32x16_bf16(af, bfr, m, 0, 0, 0); }
;               asm volatile("s_waitcnt lgkmcnt(0)" ::: "memory");
;               const int tq = r31 & 15; const bool ycol = r31 >= 16;
; #pragma unroll
;               for (int g = 0; g < 4; ++g) { f32x4 o;
; #pragma unroll
;                   for (int e = 0; e < 4; ++e) { const int sq = 2 * (4 * hh + e) + (g & 1); const bool ok = ycol ? (sq <= tq) : (sq < tq); o[e] = ok ? m[4 * g + e] : 0.f; }
;                   *(LAS f32x4*)(MT + r31 * 36 + 8 * g + 4 * hh) = o; } }
;             asm volatile("s_waitcnt lgkmcnt(0)" ::: "memory");
;             __builtin_amdgcn_sched_barrier(0);
;             f32x16 ya[2];
; #pragma unroll
;             for (int ct = 0; ct < 2; ++ct)
; #pragma unroll
;                 for (int e = 0; e < 16; ++e) ya[ct][e] = 0.f;
; #pragma unroll
;             for (int kt = 0; kt < 2; ++kt)
; #pragma unroll
;                 for (int sI = 0; sI < 2; ++sI) { const LAS bf16* ap = imKR + r31 * 72 + 32 * kt + 16 * sI + 4 * hh; const u32x2 lo = *(const LAS u32x2*)ap, hi = *(const LAS u32x2*)(ap + 8);
;                     u32x4 pa; pa.x = lo.x; pa.y = lo.y; pa.z = hi.x; pa.w = hi.y; const bf16x8 af = __builtin_bit_cast(bf16x8, pa);
; #pragma unroll
;                     for (int ct = 0; ct < 2; ++ct) { const f32x16& x = st[kt][ct];
;                         const bf16x8 bfr = pack8s(x[8 * sI], x[8 * sI + 1], x[8 * sI + 2], x[8 * sI + 3], x[8 * sI + 4], x[8 * sI + 5], x[8 * sI + 6], x[8 * sI + 7]);
;                         ya[ct] = __builtin_amdgcn_mfma_f32_32x32x16_bf16(af, bfr, ya[ct], 0, 0, 0); } }
.Lsc1_r1_noload:
	v_mov_b32_e32 v194, s42
	s_ashr_i32 s39, s38, 31
	v_mad_u32_u24 v100, v190, 48, v72
	ds_read_b128 v[64:67], v100 offset:4608
	ds_read_b128 v[68:71], v100
	ds_read_b128 v[80:83], v100 offset:32
	ds_read_b128 v[84:87], v100 offset:4640
	ds_read_b128 v[88:91], v100 offset:4672
	ds_read_b128 v[92:95], v100 offset:4704
	ds_read_b128 v[96:99], v100 offset:64
	ds_read_b128 v[100:103], v100 offset:96
	v_and_b32_e32 v105, 15, v112
	v_cmp_lt_i32_e64 s[2:3], v193, v105
	v_or_b32_e32 v106, 2, v193
	v_cmp_le_i32_e64 s[4:5], v106, v105
	v_cndmask_b32_e64 v107, 0, 1, s[2:3]
	s_waitcnt lgkmcnt(6)
	v_mfma_f32_32x32x16_bf16 v[64:79], v[64:67], v[68:71], 0
	v_cmp_le_i32_e64 s[2:3], v193, v105
	v_mad_u32_u24 v195, v190, s61, v194
	v_add_u32_e32 v104, v195, v104
	s_waitcnt lgkmcnt(0)
	s_waitcnt lgkmcnt(4)
	v_mfma_f32_32x32x16_bf16 v[64:79], v[84:87], v[80:83], v[64:79]
	v_cndmask_b32_e64 v80, 0, 1, s[2:3]
	v_cmp_lt_i32_e64 s[2:3], v106, v105
	v_cndmask_b32_e64 v82, 0, 1, s[4:5]
	s_nop 0
	v_cndmask_b32_e64 v81, 0, 1, s[2:3]
	v_cmp_gt_u32_e64 s[2:3], 16, v190
	s_waitcnt lgkmcnt(1)
	v_mfma_f32_32x32x16_bf16 v[64:79], v[88:91], v[96:99], v[64:79]
	v_cndmask_b32_e64 v81, v82, v81, s[2:3]
	v_or_b32_e32 v82, 4, v193
	v_cndmask_b32_e64 v80, v80, v107, s[2:3]
	v_cmp_lt_i32_e64 s[4:5], v82, v105
	v_and_b32_e32 v80, 1, v80
	v_and_b32_e32 v81, 1, v81
	v_cndmask_b32_e64 v83, 0, 1, s[4:5]
	v_cmp_le_i32_e64 s[4:5], v82, v105
	s_waitcnt lgkmcnt(0)
	v_mfma_f32_32x32x16_bf16 v[64:79], v[92:95], v[100:103], v[64:79]
	v_cmp_eq_u32_e64 s[6:7], 1, v81
	v_cndmask_b32_e64 v82, 0, 1, s[4:5]
	v_cmp_eq_u32_e64 s[4:5], 1, v80
	v_or_b32_e32 v80, 6, v193
	v_cmp_lt_i32_e64 s[10:11], v80, v105
	v_cndmask_b32_e64 v82, v82, v83, s[2:3]
	v_and_b32_e32 v82, 1, v82
	v_cndmask_b32_e64 v81, 0, 1, s[10:11]
	v_cmp_le_i32_e64 s[10:11], v80, v105
	v_cmp_eq_u32_e64 s[8:9], 1, v82
	s_nop 1
	v_cndmask_b32_e64 v64, 0, v64, s[4:5]
	v_cndmask_b32_e64 v80, 0, 1, s[10:11]
	v_cndmask_b32_e64 v80, v80, v81, s[2:3]
	v_and_b32_e32 v80, 1, v80
	v_cmp_eq_u32_e64 s[10:11], 1, v80
	v_cndmask_b32_e64 v65, 0, v65, s[6:7]
	v_cndmask_b32_e64 v66, 0, v66, s[8:9]
	v_cndmask_b32_e64 v67, 0, v67, s[10:11]
	ds_write_b128 v104, v[64:67] offset:4608
	v_or_b32_e32 v65, 3, v193
	v_cmp_lt_i32_e64 s[14:15], v65, v105
	v_cndmask_b32_e64 v64, 0, 1, s[2:3]
	v_or_b32_e32 v64, v193, v64
	v_cndmask_b32_e64 v66, 0, 1, s[14:15]
	v_cmp_le_i32_e64 s[14:15], v65, v105
	v_cmp_gt_i32_e64 s[12:13], v105, v64
	s_nop 0
	v_cndmask_b32_e64 v65, 0, 1, s[14:15]
	v_cndmask_b32_e64 v65, v65, v66, s[2:3]
	v_or_b32_e32 v66, 5, v193
	v_cmp_lt_i32_e64 s[16:17], v66, v105
	v_cndmask_b32_e64 v64, 0, v68, s[12:13]
	v_and_b32_e32 v65, 1, v65
	v_cndmask_b32_e64 v67, 0, 1, s[16:17]
	v_cmp_le_i32_e64 s[16:17], v66, v105
	v_cmp_eq_u32_e64 s[14:15], 1, v65
	s_nop 0
	v_cndmask_b32_e64 v66, 0, 1, s[16:17]
	v_cndmask_b32_e64 v66, v66, v67, s[2:3]
	v_or_b32_e32 v67, 7, v193
	v_cmp_lt_i32_e64 s[18:19], v67, v105
	v_and_b32_e32 v66, 1, v66
	v_cmp_eq_u32_e64 s[16:17], 1, v66
	v_cndmask_b32_e64 v68, 0, 1, s[18:19]
	v_cmp_le_i32_e64 s[18:19], v67, v105
	v_cndmask_b32_e64 v65, 0, v69, s[14:15]
	v_cndmask_b32_e64 v66, 0, v70, s[16:17]
	v_cndmask_b32_e64 v67, 0, 1, s[18:19]
	v_cndmask_b32_e64 v67, v67, v68, s[2:3]
	v_and_b32_e32 v67, 1, v67
	v_cmp_eq_u32_e64 s[2:3], 1, v67
	s_nop 1
	v_cndmask_b32_e64 v67, 0, v71, s[2:3]
	ds_write_b128 v104, v[64:67] offset:4640
	v_cndmask_b32_e64 v64, 0, v72, s[4:5]
	v_cndmask_b32_e64 v65, 0, v73, s[6:7]
	v_cndmask_b32_e64 v66, 0, v74, s[8:9]
	v_cndmask_b32_e64 v67, 0, v75, s[10:11]
	ds_write_b128 v104, v[64:67] offset:4672
	v_cndmask_b32_e64 v64, 0, v76, s[12:13]
	v_cndmask_b32_e64 v65, 0, v77, s[14:15]
	v_cndmask_b32_e64 v66, 0, v78, s[16:17]
	v_cndmask_b32_e64 v67, 0, v79, s[2:3]
	ds_write_b128 v104, v[64:67] offset:4704
	s_waitcnt lgkmcnt(0)
	v_add_u32_e32 v104, v195, v193
	ds_read2_b64 v[64:67], v104 offset1:2
	v_cvt_pk_bf16_f32 v68, v0, v1
	v_cvt_pk_bf16_f32 v69, v2, v3
	v_cvt_pk_bf16_f32 v70, v4, v5
	v_cvt_pk_bf16_f32 v71, v6, v7
	s_nop 1
	v_mad_u64_u32 v[120:121], s[0:1], v191, 24, v[104:105]
	s_waitcnt lgkmcnt(0)
	v_mfma_f32_32x32x16_bf16 v[80:95], v[64:67], v[68:71], 0
	v_cvt_pk_bf16_f32 v68, v48, v49
	v_cvt_pk_bf16_f32 v69, v50, v51
	v_cvt_pk_bf16_f32 v70, v52, v53
	v_cvt_pk_bf16_f32 v71, v54, v55
	s_nop 1
	ds_read2_b64 v[96:99], v104 offset0:4 offset1:6
	v_cvt_pk_bf16_f32 v100, v8, v9
	v_cvt_pk_bf16_f32 v101, v10, v11
	v_cvt_pk_bf16_f32 v102, v12, v13
	v_cvt_pk_bf16_f32 v103, v14, v15
	s_nop 1
	v_mfma_f32_32x32x16_bf16 v[64:79], v[64:67], v[68:71], 0
	s_waitcnt lgkmcnt(0)
	v_mfma_f32_32x32x16_bf16 v[80:95], v[96:99], v[100:103], v[80:95]
	v_cvt_pk_bf16_f32 v100, v56, v57
	v_cvt_pk_bf16_f32 v101, v58, v59
	v_cvt_pk_bf16_f32 v102, v60, v61
	v_cvt_pk_bf16_f32 v103, v62, v63
	s_nop 1
	s_nop 0
	v_mfma_f32_32x32x16_bf16 v[64:79], v[96:99], v[100:103], v[64:79]
	ds_read2_b64 v[96:99], v104 offset0:8 offset1:10
	v_cvt_pk_bf16_f32 v100, v32, v33
	v_cvt_pk_bf16_f32 v101, v34, v35
	v_cvt_pk_bf16_f32 v102, v36, v37
	v_cvt_pk_bf16_f32 v103, v38, v39
	s_nop 1
	s_waitcnt lgkmcnt(0)
	v_mfma_f32_32x32x16_bf16 v[80:95], v[96:99], v[100:103], v[80:95]
	v_cvt_pk_bf16_f32 v100, v16, v17
	v_cvt_pk_bf16_f32 v101, v18, v19
	v_cvt_pk_bf16_f32 v102, v20, v21
	v_cvt_pk_bf16_f32 v103, v22, v23
	s_nop 1
	s_nop 0
	v_mfma_f32_32x32x16_bf16 v[64:79], v[96:99], v[100:103], v[64:79]
	ds_read2_b64 v[96:99], v104 offset0:12 offset1:14
	v_cvt_pk_bf16_f32 v100, v40, v41
	v_cvt_pk_bf16_f32 v101, v42, v43
	v_cvt_pk_bf16_f32 v102, v44, v45
	v_cvt_pk_bf16_f32 v103, v46, v47
	s_nop 1
	s_waitcnt lgkmcnt(0)
; #define LAS __attribute__((address_space(3)))
; template <int role> __device__ __forceinline__ void ph_scan1m_r(Ctx& C) {
;     ...
;                         ya[ct] = __builtin_amdgcn_mfma_f32_32x32x16_bf16(af, bfr, ya[ct], 0, 0, 0); } }
;             bf16x8 vfr[2];
;             if (role) { const f32x4 m0 = *(const LAS f32x4*)(MT + r31 * 36 + 16 + 8 * hh), m1 = *(const LAS f32x4*)(MT + r31 * 36 + 20 + 8 * hh); const bf16x8 af = pack8s(m0[0], m0[1], m0[2], m0[3], m1[0], m1[1], m1[2], m1[3]);
; #pragma unroll
;                 for (int ct = 0; ct < 2; ++ct) { vfr[ct] = *(const LAS bf16x8*)(imVT + (32 * ct + r31) * 24 + 8 * hh); ya[ct] = __builtin_amdgcn_mfma_f32_32x32x16_bf16(af, vfr[ct], ya[ct], 0, 0, 0); } }
;             __builtin_amdgcn_sched_barrier(0);
;             f32x2 u2[16];
; #pragma unroll
;             for (int e = 0; e < 4; ++e) {
;                 const auto a0 = __builtin_amdgcn_permlane32_swap(__float_as_uint(ya[0][e]), __float_as_uint(ya[0][e]), false, false), a1 = __builtin_amdgcn_permlane32_swap(__float_as_uint(ya[1][e]), __float_as_uint(ya[1][e]), false, false);
;                 const auto b0 = __builtin_amdgcn_permlane32_swap(__float_as_uint(ya[0][4 + e]), __float_as_uint(ya[0][4 + e]), false, false), b1 = __builtin_amdgcn_permlane32_swap(__float_as_uint(ya[1][4 + e]), __float_as_uint(ya[1][4 + e]), false, false);
;                 u2[e] = (f32x2){__uint_as_float(a0[0]), __uint_as_float(a1[0])}; u2[4 + e] = (f32x2){__uint_as_float(a0[1]), __uint_as_float(a1[1])};
;                 u2[8 + e] = (f32x2){__uint_as_float(b0[0]), __uint_as_float(b1[0])}; u2[12 + e] = (f32x2){__uint_as_float(b0[1]), __uint_as_float(b1[1])}; }
; #pragma unroll
;             for (int t = 1; t < 16; ++t) { f32x2 a = u2[t]; float clast = 0.f;
; #pragma unroll
;                 for (int q = 0; q < 4; ++q) { const int smin = q < 2 ? 8 * q : 8 * (q - 2) + 1;
;                     if (smin < t) { const f32x4 cf = *(const LAS f32x4*)(MT + t * 36 + 4 * q);
; #pragma unroll
;                         for (int e = 0; e < 4; ++e) { const int sl = 4 * q + e, st_ = sl < 8 ? 2 * sl : 2 * (sl - 8) + 1; if (st_ == t - 1) clast = cf[e]; else if (st_ < t) a += u2[st_] * cf[e]; } } }
;                 a += u2[t - 1] * clast;
;                 u2[t] = a; }
	v_mfma_f32_32x32x16_bf16 v[80:95], v[96:99], v[100:103], v[80:95]
	v_cvt_pk_bf16_f32 v100, v24, v25
	v_cvt_pk_bf16_f32 v101, v26, v27
	v_cvt_pk_bf16_f32 v102, v28, v29
	v_cvt_pk_bf16_f32 v103, v30, v31
	s_nop 1
	ds_read_b128 v[104:107], v120 offset:4672
	ds_read_b128 v[108:111], v120 offset:4688
	s_waitcnt lgkmcnt(0)
	v_cvt_pk_bf16_f32 v122, v104, v105
	v_cvt_pk_bf16_f32 v123, v106, v107
	v_cvt_pk_bf16_f32 v124, v108, v109
	v_cvt_pk_bf16_f32 v125, v110, v111
	s_nop 1
	v_mfma_f32_32x32x16_bf16 v[64:79], v[96:99], v[100:103], v[64:79]
	v_mad_u32_u24 v96, v190, 48, v192
	ds_read_b128 v[100:103], v96 offset:14592
	ds_read_b128 v[96:99], v96 offset:16128
	s_waitcnt lgkmcnt(1)
	v_mfma_f32_32x32x16_bf16 v[80:95], v[122:125], v[100:103], v[80:95]
	s_waitcnt lgkmcnt(0)
	v_mfma_f32_32x32x16_bf16 v[64:79], v[122:125], v[96:99], v[64:79]
	v_add_u32_e32 v121, 0x1000, v194
	ds_read2_b32 v[126:127], v121 offset0:164 offset1:200
	s_nop 7
	v_mov_b32_e32 v104, v80
	v_mov_b32_e32 v138, v80
	v_mov_b32_e32 v105, v64
	v_mov_b32_e32 v139, v64
	v_mov_b32_e32 v106, v81
	v_mov_b32_e32 v196, v81
	v_mov_b32_e32 v107, v65
	v_mov_b32_e32 v197, v65
	v_permlane32_swap_b32_e32 v104, v138
	v_permlane32_swap_b32_e32 v105, v139
	v_permlane32_swap_b32_e32 v106, v196
	v_permlane32_swap_b32_e32 v107, v197
	v_mov_b32_e32 v122, v82
	v_mov_b32_e32 v200, v82
	v_mov_b32_e32 v123, v66
	v_mov_b32_e32 v201, v66
	v_permlane32_swap_b32_e32 v122, v200
	s_nop 0
	v_permlane32_swap_b32_e32 v123, v201
	s_waitcnt lgkmcnt(0)
	v_pk_fma_f32 v[106:107], v[126:127], v[104:105], v[106:107] op_sel_hi:[0,1,1]
	v_mov_b32_e32 v126, v127
	v_pk_fma_f32 v[122:123], v[126:127], v[104:105], v[122:123] op_sel_hi:[0,1,1]
	ds_read_b32 v198, v194 offset:4928
	ds_read_b64 v[204:205], v194 offset:5040
	ds_read_b32 v206, v194 offset:5072
	ds_read2_b64 v[126:129], v121 offset0:136 offset1:140
	ds_read_b96 v[130:132], v194 offset:5328
	v_mov_b32_e32 v124, v83
	v_mov_b32_e32 v202, v83
	v_mov_b32_e32 v125, v67
	v_mov_b32_e32 v203, v67
	v_permlane32_swap_b32_e32 v124, v202
	s_nop 0
	v_permlane32_swap_b32_e32 v125, v203
	s_waitcnt lgkmcnt(4)
	v_pk_fma_f32 v[122:123], v[106:107], v[198:199], v[122:123] op_sel_hi:[1,0,1]
	s_waitcnt lgkmcnt(3)
	v_pk_fma_f32 v[124:125], v[204:205], v[104:105], v[124:125] op_sel_hi:[0,1,1]
	s_waitcnt lgkmcnt(1)
	v_pk_fma_f32 v[138:139], v[126:127], v[104:105], v[138:139] op_sel_hi:[0,1,1]
	v_pk_fma_f32 v[124:125], v[106:107], v[206:207], v[124:125] op_sel_hi:[1,0,1]
	v_pk_fma_f32 v[126:127], v[122:123], v[126:127], v[138:139] op_sel:[0,1,0]
	ds_read_b64 v[138:139], v194 offset:5360
	v_pk_fma_f32 v[124:125], v[204:205], v[122:123], v[124:125] op_sel:[1,0,0]
	v_pk_fma_f32 v[126:127], v[106:107], v[128:129], v[126:127] op_sel_hi:[1,0,1]
	ds_read_b96 v[204:206], v194 offset:5648
	v_pk_fma_f32 v[126:127], v[128:129], v[124:125], v[126:127] op_sel:[1,0,0]
	s_waitcnt lgkmcnt(2)
	v_pk_fma_f32 v[128:129], v[130:131], v[104:105], v[196:197] op_sel_hi:[0,1,1]
	ds_read_b96 v[196:198], v194 offset:5472
	v_pk_fma_f32 v[128:129], v[122:123], v[130:131], v[128:129] op_sel:[0,1,0]
	v_mov_b32_e32 v130, v132
	s_waitcnt lgkmcnt(2)
	v_pk_fma_f32 v[128:129], v[106:107], v[138:139], v[128:129] op_sel_hi:[1,0,1]
	v_mov_b32_e32 v208, v84
	v_pk_fma_f32 v[128:129], v[124:125], v[138:139], v[128:129] op_sel:[0,1,0]
	s_waitcnt lgkmcnt(0)
	v_pk_fma_f32 v[138:139], v[196:197], v[104:105], v[200:201] op_sel_hi:[0,1,1]
	v_pk_fma_f32 v[128:129], v[130:131], v[126:127], v[128:129] op_sel_hi:[0,1,1]
	ds_read_b96 v[130:132], v194 offset:5504
	v_pk_fma_f32 v[138:139], v[122:123], v[196:197], v[138:139] op_sel:[0,1,0]
	v_mov_b32_e32 v196, v198
	v_pk_fma_f32 v[138:139], v[196:197], v[126:127], v[138:139] op_sel_hi:[0,1,1]
	ds_read_b128 v[196:199], v194 offset:5616
	s_waitcnt lgkmcnt(1)
	v_pk_fma_f32 v[138:139], v[106:107], v[130:131], v[138:139] op_sel_hi:[1,0,1]
	v_mov_b32_e32 v136, v84
	v_pk_fma_f32 v[130:131], v[124:125], v[130:131], v[138:139] op_sel:[0,1,0]
	v_mov_b32_e32 v209, v68
	v_pk_fma_f32 v[130:131], v[132:133], v[128:129], v[130:131] op_sel_hi:[0,1,1]
	s_waitcnt lgkmcnt(0)
	v_pk_fma_f32 v[132:133], v[196:197], v[104:105], v[202:203] op_sel_hi:[0,1,1]
	v_pk_fma_f32 v[132:133], v[122:123], v[196:197], v[132:133] op_sel:[0,1,0]
	ds_read_b128 v[200:203], v194 offset:5760
	v_pk_fma_f32 v[132:133], v[126:127], v[198:199], v[132:133] op_sel_hi:[1,0,1]
	v_mov_b32_e32 v137, v68
	v_pk_fma_f32 v[132:133], v[106:107], v[204:205], v[132:133] op_sel_hi:[1,0,1]
	v_mov_b32_e32 v138, v206
	v_pk_fma_f32 v[132:133], v[124:125], v[204:205], v[132:133] op_sel:[0,1,0]
	v_permlane32_swap_b32_e32 v208, v136
	v_permlane32_swap_b32_e32 v209, v137
	v_pk_fma_f32 v[132:133], v[138:139], v[128:129], v[132:133] op_sel_hi:[0,1,1]
	v_mov_b32_e32 v138, v199
	v_pk_fma_f32 v[132:133], v[138:139], v[130:131], v[132:133] op_sel_hi:[0,1,1]
	s_waitcnt lgkmcnt(0)
	v_pk_fma_f32 v[138:139], v[200:201], v[104:105], v[208:209] op_sel_hi:[0,1,1]
	ds_read_b128 v[196:199], v194 offset:5792
	v_pk_fma_f32 v[138:139], v[122:123], v[200:201], v[138:139] op_sel:[0,1,0]
	v_mov_b32_e32 v200, v203
	v_pk_fma_f32 v[138:139], v[126:127], v[202:203], v[138:139] op_sel_hi:[1,0,1]
	v_mov_b32_e32 v210, v85
	v_pk_fma_f32 v[138:139], v[200:201], v[130:131], v[138:139] op_sel_hi:[0,1,1]
	ds_read_b128 v[200:203], v194 offset:5904
	s_waitcnt lgkmcnt(1)
	v_pk_fma_f32 v[138:139], v[106:107], v[196:197], v[138:139] op_sel_hi:[1,0,1]
	v_mov_b32_e32 v134, v85
	v_mov_b32_e32 v211, v69
	v_mov_b32_e32 v135, v69
	v_pk_fma_f32 v[138:139], v[124:125], v[196:197], v[138:139] op_sel:[0,1,0]
	v_permlane32_swap_b32_e32 v210, v134
	v_permlane32_swap_b32_e32 v211, v135
	v_pk_fma_f32 v[138:139], v[128:129], v[198:199], v[138:139] op_sel_hi:[1,0,1]
	v_mov_b32_e32 v196, v199
	v_pk_fma_f32 v[138:139], v[196:197], v[132:133], v[138:139] op_sel_hi:[0,1,1]
	s_waitcnt lgkmcnt(0)
; #define LAS __attribute__((address_space(3)))
; template <int role> __device__ __forceinline__ void ph_scan1m_r(Ctx& C) {
;     ...
;             for (int t = 1; t < 16; ++t) { f32x2 a = u2[t]; float clast = 0.f;
; #pragma unroll
;                 for (int q = 0; q < 4; ++q) { const int smin = q < 2 ? 8 * q : 8 * (q - 2) + 1;
;                     if (smin < t) { const f32x4 cf = *(const LAS f32x4*)(MT + t * 36 + 4 * q);
; #pragma unroll
;                         for (int e = 0; e < 4; ++e) { const int sl = 4 * q + e, st_ = sl < 8 ? 2 * sl : 2 * (sl - 8) + 1; if (st_ == t - 1) clast = cf[e]; else if (st_ < t) a += u2[st_] * cf[e]; } } }
;                 a += u2[t - 1] * clast;
;                 u2[t] = a; }
	v_pk_fma_f32 v[196:197], v[200:201], v[104:105], v[210:211] op_sel_hi:[0,1,1]
	v_pk_fma_f32 v[196:197], v[122:123], v[200:201], v[196:197] op_sel:[0,1,0]
	v_add_u32_e32 v121, 0x1400, v194
	v_pk_fma_f32 v[200:201], v[126:127], v[202:203], v[196:197] op_sel_hi:[1,0,1]
	ds_read_b128 v[196:199], v194 offset:5936
	v_mov_b32_e32 v202, v203
	v_pk_fma_f32 v[204:205], v[202:203], v[130:131], v[200:201] op_sel_hi:[0,1,1]
	ds_read2_b32 v[206:207], v121 offset0:200 offset1:236
	ds_read_b128 v[200:203], v194 offset:6048
	v_mov_b32_e32 v212, v86
	s_waitcnt lgkmcnt(2)
	v_pk_fma_f32 v[204:205], v[106:107], v[196:197], v[204:205] op_sel_hi:[1,0,1]
	v_mov_b32_e32 v110, v86
	v_pk_fma_f32 v[196:197], v[124:125], v[196:197], v[204:205] op_sel:[0,1,0]
	v_mov_b32_e32 v213, v70
	v_mov_b32_e32 v111, v70
	v_pk_fma_f32 v[196:197], v[128:129], v[198:199], v[196:197] op_sel_hi:[1,0,1]
	v_mov_b32_e32 v198, v199
	v_permlane32_swap_b32_e32 v212, v110
	v_permlane32_swap_b32_e32 v213, v111
	v_pk_fma_f32 v[196:197], v[198:199], v[132:133], v[196:197] op_sel_hi:[0,1,1]
	s_waitcnt lgkmcnt(1)
	v_pk_fma_f32 v[208:209], v[206:207], v[138:139], v[196:197] op_sel_hi:[0,1,1]
	s_waitcnt lgkmcnt(0)
	v_pk_fma_f32 v[196:197], v[200:201], v[104:105], v[212:213] op_sel_hi:[0,1,1]
	v_pk_fma_f32 v[196:197], v[122:123], v[200:201], v[196:197] op_sel:[0,1,0]
	ds_read_b32 v204, v194 offset:6096
	v_pk_fma_f32 v[200:201], v[126:127], v[202:203], v[196:197] op_sel_hi:[1,0,1]
	ds_read_b128 v[196:199], v194 offset:6080
	v_mov_b32_e32 v202, v203
	v_pk_fma_f32 v[200:201], v[130:131], v[202:203], v[200:201] op_sel_hi:[1,0,1]
	v_mov_b32_e32 v202, v207
	v_pk_fma_f32 v[200:201], v[202:203], v[138:139], v[200:201] op_sel_hi:[0,1,1]
	s_waitcnt lgkmcnt(0)
	v_pk_fma_f32 v[200:201], v[106:107], v[196:197], v[200:201] op_sel_hi:[1,0,1]
	v_mov_b32_e32 v214, v87
	v_pk_fma_f32 v[196:197], v[124:125], v[196:197], v[200:201] op_sel:[0,1,0]
	ds_read_b128 v[200:203], v194 offset:6192
	v_mov_b32_e32 v108, v87
	v_mov_b32_e32 v215, v71
	v_mov_b32_e32 v109, v71
	v_pk_fma_f32 v[196:197], v[128:129], v[198:199], v[196:197] op_sel_hi:[1,0,1]
	v_mov_b32_e32 v198, v199
	v_permlane32_swap_b32_e32 v214, v108
	v_permlane32_swap_b32_e32 v215, v109
	v_pk_fma_f32 v[196:197], v[132:133], v[198:199], v[196:197] op_sel_hi:[1,0,1]
	v_add_u32_e32 v121, 0x1800, v194
	v_pk_fma_f32 v[210:211], v[204:205], v[208:209], v[196:197] op_sel_hi:[0,1,1]
	ds_read_b64 v[204:205], v194 offset:6208
	s_waitcnt lgkmcnt(1)
	v_pk_fma_f32 v[196:197], v[200:201], v[104:105], v[214:215] op_sel_hi:[0,1,1]
	v_pk_fma_f32 v[196:197], v[122:123], v[200:201], v[196:197] op_sel:[0,1,0]
	s_nop 0
	v_pk_fma_f32 v[200:201], v[126:127], v[202:203], v[196:197] op_sel_hi:[1,0,1]
	ds_read_b128 v[196:199], v194 offset:6224
	v_mov_b32_e32 v202, v203
	v_pk_fma_f32 v[200:201], v[130:131], v[202:203], v[200:201] op_sel_hi:[1,0,1]
	ds_read_b32 v202, v194 offset:6240
	s_waitcnt lgkmcnt(2)
	v_pk_fma_f32 v[200:201], v[138:139], v[204:205], v[200:201] op_sel_hi:[1,0,1]
	s_waitcnt lgkmcnt(1)
	v_mov_b32_e32 v206, v199
	v_pk_fma_f32 v[200:201], v[106:107], v[196:197], v[200:201] op_sel_hi:[1,0,1]
	s_nop 0
	v_pk_fma_f32 v[196:197], v[124:125], v[196:197], v[200:201] op_sel:[0,1,0]
	s_nop 0
	v_pk_fma_f32 v[200:201], v[128:129], v[198:199], v[196:197] op_sel_hi:[1,0,1]
	ds_read_b128 v[196:199], v194 offset:6336
	v_pk_fma_f32 v[200:201], v[132:133], v[206:207], v[200:201] op_sel_hi:[1,0,1]
	s_waitcnt lgkmcnt(1)
	v_pk_fma_f32 v[200:201], v[202:203], v[208:209], v[200:201] op_sel_hi:[0,1,1]
	v_pk_fma_f32 v[212:213], v[204:205], v[210:211], v[200:201] op_sel:[1,0,0]
	ds_read2_b64 v[204:207], v121 offset0:26 offset1:30
	ds_read_b128 v[200:203], v194 offset:6368
	s_waitcnt lgkmcnt(2)
	v_pk_fma_f32 v[136:137], v[196:197], v[104:105], v[136:137] op_sel_hi:[0,1,1]
	v_pk_fma_f32 v[136:137], v[122:123], v[196:197], v[136:137] op_sel:[0,1,0]
	v_mov_b32_e32 v196, v199
	v_pk_fma_f32 v[136:137], v[126:127], v[198:199], v[136:137] op_sel_hi:[1,0,1]
	v_cndmask_b32_e32 v121, v128, v126, vcc
	v_pk_fma_f32 v[136:137], v[130:131], v[196:197], v[136:137] op_sel_hi:[1,0,1]
	ds_read_b128 v[196:199], v194 offset:6480
	s_waitcnt lgkmcnt(2)
	v_pk_fma_f32 v[136:137], v[138:139], v[204:205], v[136:137] op_sel_hi:[1,0,1]
	s_nop 0
	v_pk_fma_f32 v[136:137], v[204:205], v[210:211], v[136:137] op_sel:[1,0,0]
	s_waitcnt lgkmcnt(1)
	v_pk_fma_f32 v[136:137], v[106:107], v[200:201], v[136:137] op_sel_hi:[1,0,1]
	s_nop 0
	v_pk_fma_f32 v[136:137], v[124:125], v[200:201], v[136:137] op_sel:[0,1,0]
	v_mov_b32_e32 v200, v203
	v_pk_fma_f32 v[136:137], v[128:129], v[202:203], v[136:137] op_sel_hi:[1,0,1]
	s_nop 0
	v_pk_fma_f32 v[136:137], v[132:133], v[200:201], v[136:137] op_sel_hi:[1,0,1]
	ds_read_b96 v[200:202], v194 offset:6496
	s_waitcnt lgkmcnt(1)
	v_pk_fma_f32 v[134:135], v[196:197], v[104:105], v[134:135] op_sel_hi:[0,1,1]
	v_pk_fma_f32 v[136:137], v[208:209], v[206:207], v[136:137] op_sel_hi:[1,0,1]
	v_pk_fma_f32 v[134:135], v[122:123], v[196:197], v[134:135] op_sel:[0,1,0]
	v_pk_fma_f32 v[204:205], v[206:207], v[212:213], v[136:137] op_sel:[1,0,0]
	v_pk_fma_f32 v[196:197], v[126:127], v[198:199], v[134:135] op_sel_hi:[1,0,1]
	ds_read_b128 v[134:137], v194 offset:6512
	v_mov_b32_e32 v198, v199
	v_pk_fma_f32 v[196:197], v[130:131], v[198:199], v[196:197] op_sel_hi:[1,0,1]
	ds_read_b64 v[198:199], v194 offset:6528
	s_waitcnt lgkmcnt(2)
	v_pk_fma_f32 v[196:197], v[138:139], v[200:201], v[196:197] op_sel_hi:[1,0,1]
	s_nop 0
	v_pk_fma_f32 v[196:197], v[210:211], v[200:201], v[196:197] op_sel:[0,1,0]
	s_waitcnt lgkmcnt(1)
; #define LAS __attribute__((address_space(3)))
; template <int role> __device__ __forceinline__ void ph_scan1m_r(Ctx& C) {
;     ...
;             for (int t = 1; t < 16; ++t) { f32x2 a = u2[t]; float clast = 0.f;
; #pragma unroll
;                 for (int q = 0; q < 4; ++q) { const int smin = q < 2 ? 8 * q : 8 * (q - 2) + 1;
;                     if (smin < t) { const f32x4 cf = *(const LAS f32x4*)(MT + t * 36 + 4 * q);
; #pragma unroll
;                         for (int e = 0; e < 4; ++e) { const int sl = 4 * q + e, st_ = sl < 8 ? 2 * sl : 2 * (sl - 8) + 1; if (st_ == t - 1) clast = cf[e]; else if (st_ < t) a += u2[st_] * cf[e]; } } }
;                 a += u2[t - 1] * clast;
;                 u2[t] = a; }
;             bf16x8 ufr[2];
;             ufr[0] = pack8s(hh ? u2[1].x : u2[0].x, hh ? u2[3].x : u2[2].x, hh ? u2[5].x : u2[4].x, hh ? u2[7].x : u2[6].x, hh ? u2[9].x : u2[8].x, hh ? u2[11].x : u2[10].x, hh ? u2[13].x : u2[12].x, hh ? u2[15].x : u2[14].x);
;             ufr[1] = pack8s(hh ? u2[1].y : u2[0].y, hh ? u2[3].y : u2[2].y, hh ? u2[5].y : u2[4].y, hh ? u2[7].y : u2[6].y, hh ? u2[9].y : u2[8].y, hh ? u2[11].y : u2[10].y, hh ? u2[13].y : u2[12].y, hh ? u2[15].y : u2[14].y);
;             __builtin_amdgcn_sched_barrier(0);
;             { const f32x4 m0 = *(const LAS f32x4*)(MT + r31 * 36 + 8 * hh), m1 = *(const LAS f32x4*)(MT + r31 * 36 + 4 + 8 * hh); const bf16x8 af = pack8s(m0[0], m0[1], m0[2], m0[3], m1[0], m1[1], m1[2], m1[3]);
; #pragma unroll
;               for (int ct = 0; ct < 2; ++ct) ya[ct] = __builtin_amdgcn_mfma_f32_32x32x16_bf16(af, ufr[ct], ya[ct], 0, 0, 0); }
;             { LAS bf16* ys = (LAS bf16*)MT;
; #pragma unroll
;               for (int ct = 0; ct < 2; ++ct)
; #pragma unroll
;                   for (int e = 0; e < 8; e += 2) { const unsigned pw = pg8::cvt_pk_bf16(ya[ct][8 + e], ya[ct][9 + e]); const int t = (e & 3) + 4 * hh + 8 * (e >> 2); LAS bf16* d = ys + t * 72 + 32 * ct + r31; d[0] = (bf16)pw; d[72] = (bf16)(pw >> 16); }
;               asm volatile("s_waitcnt lgkmcnt(0)" ::: "memory");
; #pragma unroll
;               for (int i = 0; i < 2; ++i) { const int t = (lane >> 3) + 8 * i; const u32x4 w = *(const LAS u32x4*)(ys + t * 72 + 8 * (lane & 7)); *(u32x4*)(g_out + zoff + rowu + (long)t * dix + 8 * (lane & 7)) = w; }
;               asm volatile("s_waitcnt lgkmcnt(0)" ::: "memory"); }
	v_pk_fma_f32 v[196:197], v[106:107], v[134:135], v[196:197] op_sel_hi:[1,0,1]
	s_nop 0
	v_pk_fma_f32 v[134:135], v[124:125], v[134:135], v[196:197] op_sel:[0,1,0]
	s_nop 0
	v_pk_fma_f32 v[134:135], v[128:129], v[136:137], v[134:135] op_sel_hi:[1,0,1]
	v_mov_b32_e32 v136, v137
	v_pk_fma_f32 v[134:135], v[132:133], v[136:137], v[134:135] op_sel_hi:[1,0,1]
	s_waitcnt lgkmcnt(0)
	v_pk_fma_f32 v[196:197], v[208:209], v[198:199], v[134:135] op_sel_hi:[1,0,1]
	ds_read_b128 v[134:137], v194 offset:6624
	v_pk_fma_f32 v[196:197], v[198:199], v[212:213], v[196:197] op_sel:[1,0,0]
	v_mov_b32_e32 v198, v202
	v_pk_fma_f32 v[200:201], v[198:199], v[204:205], v[196:197] op_sel_hi:[0,1,1]
	ds_read_b96 v[196:198], v194 offset:6640
	s_waitcnt lgkmcnt(1)
	v_pk_fma_f32 v[110:111], v[134:135], v[104:105], v[110:111] op_sel_hi:[0,1,1]
	v_pk_fma_f32 v[110:111], v[122:123], v[134:135], v[110:111] op_sel:[0,1,0]
	v_mov_b32_e32 v134, v137
	v_pk_fma_f32 v[110:111], v[126:127], v[136:137], v[110:111] op_sel_hi:[1,0,1]
	s_nop 0
	v_pk_fma_f32 v[110:111], v[130:131], v[134:135], v[110:111] op_sel_hi:[1,0,1]
	ds_read_b128 v[134:137], v194 offset:6656
	s_waitcnt lgkmcnt(1)
	v_pk_fma_f32 v[110:111], v[138:139], v[196:197], v[110:111] op_sel_hi:[1,0,1]
	s_nop 0
	v_pk_fma_f32 v[110:111], v[210:211], v[196:197], v[110:111] op_sel:[0,1,0]
	v_mov_b32_e32 v196, v198
	v_pk_fma_f32 v[110:111], v[196:197], v[204:205], v[110:111] op_sel_hi:[0,1,1]
	ds_read_b96 v[196:198], v194 offset:6672
	s_waitcnt lgkmcnt(1)
	v_pk_fma_f32 v[110:111], v[106:107], v[134:135], v[110:111] op_sel_hi:[1,0,1]
	s_nop 0
	v_pk_fma_f32 v[110:111], v[124:125], v[134:135], v[110:111] op_sel:[0,1,0]
	v_mov_b32_e32 v134, v137
	v_pk_fma_f32 v[110:111], v[128:129], v[136:137], v[110:111] op_sel_hi:[1,0,1]
	s_nop 0
	v_pk_fma_f32 v[110:111], v[132:133], v[134:135], v[110:111] op_sel_hi:[1,0,1]
	ds_read_b128 v[134:137], v194 offset:6768
	s_waitcnt lgkmcnt(1)
	v_pk_fma_f32 v[110:111], v[208:209], v[196:197], v[110:111] op_sel_hi:[1,0,1]
	s_nop 0
	v_pk_fma_f32 v[110:111], v[212:213], v[196:197], v[110:111] op_sel:[0,1,0]
	v_mov_b32_e32 v196, v198
	v_pk_fma_f32 v[202:203], v[196:197], v[200:201], v[110:111] op_sel_hi:[0,1,1]
	ds_read_b128 v[196:199], v194 offset:6784
	s_waitcnt lgkmcnt(1)
	v_pk_fma_f32 v[108:109], v[134:135], v[104:105], v[108:109] op_sel_hi:[0,1,1]
	v_pk_fma_f32 v[108:109], v[122:123], v[134:135], v[108:109] op_sel:[0,1,0]
	v_mov_b32_e32 v110, v137
	v_pk_fma_f32 v[108:109], v[126:127], v[136:137], v[108:109] op_sel_hi:[1,0,1]
	v_cndmask_b32_e32 v104, v106, v104, vcc
	v_pk_fma_f32 v[134:135], v[130:131], v[110:111], v[108:109] op_sel_hi:[1,0,1]
	ds_read_b128 v[108:111], v194 offset:6800
	s_waitcnt lgkmcnt(1)
	v_pk_fma_f32 v[134:135], v[138:139], v[196:197], v[134:135] op_sel_hi:[1,0,1]
	v_cndmask_b32_e32 v126, v212, v210, vcc
	v_pk_fma_f32 v[134:135], v[210:211], v[196:197], v[134:135] op_sel:[0,1,0]
	s_nop 0
	v_pk_fma_f32 v[196:197], v[198:199], v[204:205], v[134:135] op_sel_hi:[0,1,1]
	ds_read_b96 v[134:136], v194 offset:6816
	s_waitcnt lgkmcnt(1)
	v_pk_fma_f32 v[196:197], v[106:107], v[108:109], v[196:197] op_sel_hi:[1,0,1]
	v_cndmask_b32_e32 v106, v124, v122, vcc
	v_pk_fma_f32 v[108:109], v[124:125], v[108:109], v[196:197] op_sel:[0,1,0]
	v_cndmask_b32_e32 v122, v132, v130, vcc
	v_pk_fma_f32 v[108:109], v[128:129], v[110:111], v[108:109] op_sel_hi:[1,0,1]
	v_mov_b32_e32 v110, v111
	v_pk_fma_f32 v[108:109], v[132:133], v[110:111], v[108:109] op_sel_hi:[1,0,1]
	s_waitcnt lgkmcnt(0)
	v_mov_b32_e32 v110, v136
	v_pk_fma_f32 v[108:109], v[208:209], v[134:135], v[108:109] op_sel_hi:[1,0,1]
	v_cndmask_b32_e32 v124, v208, v138, vcc
	v_pk_fma_f32 v[108:109], v[212:213], v[134:135], v[108:109] op_sel:[0,1,0]
	v_cndmask_b32_e32 v128, v200, v204, vcc
	v_pk_fma_f32 v[108:109], v[110:111], v[200:201], v[108:109] op_sel_hi:[0,1,1]
	v_mov_b32_e32 v110, v199
	v_pk_fma_f32 v[134:135], v[110:111], v[202:203], v[108:109] op_sel_hi:[0,1,1]
	v_cndmask_b32_e32 v130, v134, v202, vcc
	v_cvt_pk_bf16_f32 v108, v104, v106
	v_cvt_pk_bf16_f32 v109, v121, v122
	v_cvt_pk_bf16_f32 v110, v124, v126
	v_cvt_pk_bf16_f32 v111, v128, v130
	s_nop 1
	v_cndmask_b32_e32 v121, v107, v105, vcc
	v_cndmask_b32_e32 v122, v125, v123, vcc
	v_cndmask_b32_e32 v123, v129, v127, vcc
	v_cndmask_b32_e32 v124, v133, v131, vcc
	v_cndmask_b32_e32 v125, v209, v139, vcc
	v_cndmask_b32_e32 v126, v213, v211, vcc
	v_cndmask_b32_e32 v127, v201, v205, vcc
	v_cndmask_b32_e32 v128, v135, v203, vcc
	v_cvt_pk_bf16_f32 v104, v121, v122
	v_cvt_pk_bf16_f32 v105, v123, v124
	v_cvt_pk_bf16_f32 v106, v125, v126
	v_cvt_pk_bf16_f32 v107, v127, v128
	s_nop 1
	ds_read_b128 v[122:125], v120 offset:4608
	ds_read_b128 v[126:129], v120 offset:4624
	s_lshl_b64 s[0:1], s[38:39], 11
	s_add_u32 s0, s73, s0
	s_addc_u32 s1, s74, s1
	s_waitcnt lgkmcnt(0)
	v_cvt_pk_bf16_f32 v130, v122, v123
	v_cvt_pk_bf16_f32 v131, v124, v125
	v_cvt_pk_bf16_f32 v132, v126, v127
	v_cvt_pk_bf16_f32 v133, v128, v129
	s_nop 1
	s_nop 0
	v_mfma_f32_32x32x16_bf16 v[80:95], v[130:133], v[108:111], v[80:95]
	v_mfma_f32_32x32x16_bf16 v[64:79], v[130:133], v[104:107], v[64:79]
	s_nop 10
	v_mul_i32_i24_e32 v80, 0xffffff72, v190
	v_mul_lo_u32 v81, v191, s68
	v_add3_u32 v80, v195, v80, v81
	v_cvt_pk_bf16_f32 v81, v88, v89
	ds_write_b16 v80, v81 offset:4608
	ds_write_b16_d16_hi v80, v81 offset:4752
	v_cvt_pk_bf16_f32 v64, v90, v91
	ds_write_b16 v80, v64 offset:4896
	ds_write_b16_d16_hi v80, v64 offset:5040
	v_cvt_pk_bf16_f32 v64, v92, v93
	ds_write_b16 v80, v64 offset:5760
	ds_write_b16_d16_hi v80, v64 offset:5904
	v_cvt_pk_bf16_f32 v64, v94, v95
	ds_write_b16 v80, v64 offset:6048
	ds_write_b16_d16_hi v80, v64 offset:6192
	v_cvt_pk_bf16_f32 v64, v72, v73
	ds_write_b16 v80, v64 offset:4672
	ds_write_b16_d16_hi v80, v64 offset:4816
	v_cvt_pk_bf16_f32 v64, v74, v75
	ds_write_b16 v80, v64 offset:4960
	ds_write_b16_d16_hi v80, v64 offset:5104
	v_cvt_pk_bf16_f32 v64, v76, v77
	ds_write_b16 v80, v64 offset:5824
	ds_write_b16_d16_hi v80, v64 offset:5968
	v_cvt_pk_bf16_f32 v64, v78, v79
	ds_write_b16 v80, v64 offset:6112
	ds_write_b16_d16_hi v80, v64 offset:6256
	v_ashrrev_i32_e32 v76, 3, v112
	v_lshlrev_b32_e32 v64, 4, v112
	v_and_b32_e32 v112, 0x70, v64
	v_mul_lo_u32 v64, v76, s61
	s_waitcnt lgkmcnt(0)
	v_add3_u32 v70, s42, v112, v64
	ds_read_b128 v[64:67], v70 offset:4608
	v_ashrrev_i32_e32 v68, 31, v76
	v_lshl_add_u64 v[72:73], s[0:1], 0, v[112:113]
	v_mul_lo_u32 v71, s34, v68
	v_mul_lo_u32 v74, s35, v76
	v_mad_u64_u32 v[68:69], s[0:1], s34, v76, 0
	v_add3_u32 v69, v69, v71, v74
	v_lshl_add_u64 v[74:75], v[68:69], 1, v[72:73]
	ds_read_b128 v[68:71], v70 offset:5760
	s_waitcnt lgkmcnt(1)
	global_store_dwordx4 v[74:75], v[64:67], off
	s_nop 1
	v_add_u32_e32 v64, 8, v76
	v_ashrrev_i32_e32 v65, 31, v64
	v_mul_lo_u32 v66, s34, v65
	v_mul_lo_u32 v67, s35, v64
	v_mad_u64_u32 v[64:65], s[0:1], s34, v64, 0
	v_add3_u32 v65, v65, v66, v67
	v_lshl_add_u64 v[64:65], v[64:65], 1, v[72:73]
	s_waitcnt lgkmcnt(0)
	global_store_dwordx4 v[64:65], v[68:71], off
	s_waitcnt lgkmcnt(0)
	s_branch .LBB0_708

; #define RAW2(w) ((f32x2){__uint_as_float((w) << 16), __uint_as_float((w) & 0xffff0000u)})
; template <int role> __device__ __forceinline__ void ph_scan1m_r(Ctx& C) {
;     ...
;             const int sg0 = chunk * CHL + sb * 16; const long tk0 = z ? (long)S - 1 - sg0 : sg0; const long dtk = z ? -1 : 1;
;             asm volatile("s_waitcnt vmcnt(0)" ::: "memory");
;             int lane_i = lane0; asm volatile("" : "+v"(lane_i));
;             const int lane = lane_i, r31 = lane_i & 31, hh = lane_i >> 5, r31g = r31;
;             const long dix = dtk * RW;
;             const size_t rowu = (size_t)tk0 * RW + h * 64;
;             const int par = lane >> 5, c0 = 2 * (lane & 31), cme = c0 + par; const float pm = par ? 1.44269504f : 0.f;
;             f32x2 Lm[8], Lt[8], GT2;
;             { f32x2 bef = (f32x2){0.f, 0.f};
; #pragma unroll
;               for (int j = 0; j < 8; ++j) { auto sw = __builtin_amdgcn_permlane32_swap(rl[j], rl[j], false, false); asm volatile("s_nop 1" : "+v"(sw[0]), "+v"(sw[1]));
;                   const f32x2 e = RAW2(sw[0]), o = RAW2(sw[1]); const f32x2 be = bef + e;
;                   Lm[j] = bef * 1.44269504f + e * pm; Lt[j] = be * 1.44269504f + o * pm; bef = be + o; }
;               GT2 = (f32x2){__builtin_amdgcn_exp2f(bef.x * 1.44269504f), __builtin_amdgcn_exp2f(bef.y * 1.44269504f)}; }
.LBB0_720:
	s_waitcnt vmcnt(31)
	v_mov_b32_e32 v65, v126
	v_mov_b32_e32 v69, v126
	v_mov_b32_e32 v159, v124
	s_nop 0
	v_permlane32_swap_b32_e32 v65, v69
	s_waitcnt vmcnt(2)
	s_nop 1
	s_waitcnt vmcnt(29)
	v_lshlrev_b32_e32 v102, 16, v128
	v_cmp_gt_u32_e32 vcc, 32, v159
	v_lshlrev_b32_e32 v66, 16, v65
	v_and_b32_e32 v67, 0xffff0000, v65
	v_cndmask_b32_e64 v64, v125, 0, vcc
	v_pk_add_f32 v[70:71], v[66:67], 0 op_sel_hi:[1,0]
	v_lshlrev_b32_e32 v68, 16, v69
	v_and_b32_e32 v69, 0xffff0000, v69
	v_pk_fma_f32 v[78:79], v[64:65], v[66:67], 0 op_sel_hi:[0,1,0]
	v_pk_mul_f32 v[66:67], v[70:71], s[22:23] op_sel_hi:[1,0]
	v_and_b32_e32 v158, 31, v159
	v_pk_fma_f32 v[84:85], v[64:65], v[68:69], v[66:67] op_sel_hi:[0,1,1]
	v_pk_add_f32 v[66:67], v[70:71], v[68:69]
	s_waitcnt vmcnt(27)
	v_mov_b32_e32 v65, v130
	v_mov_b32_e32 v71, v130
	s_nop 1
	v_permlane32_swap_b32_e32 v65, v71
	s_nop 1
	v_ashrrev_i32_e32 v160, 5, v159
	v_lshlrev_b32_e32 v68, 16, v65
	v_and_b32_e32 v69, 0xffff0000, v65
	v_pk_add_f32 v[72:73], v[66:67], v[68:69]
	v_pk_mul_f32 v[68:69], v[64:65], v[68:69] op_sel_hi:[0,1]
	v_lshlrev_b32_e32 v70, 16, v71
	v_and_b32_e32 v71, 0xffff0000, v71
	v_pk_fma_f32 v[86:87], v[66:67], s[22:23], v[68:69] op_sel_hi:[1,0,1]
	v_pk_mul_f32 v[66:67], v[72:73], s[22:23] op_sel_hi:[1,0]
	v_exp_f32_e32 v78, v78
	v_pk_fma_f32 v[88:89], v[64:65], v[70:71], v[66:67] op_sel_hi:[0,1,1]
	v_pk_add_f32 v[66:67], v[72:73], v[70:71]
	s_waitcnt vmcnt(23)
	v_mov_b32_e32 v65, v134
	v_mov_b32_e32 v71, v134
	s_nop 1
	v_permlane32_swap_b32_e32 v65, v71
	s_nop 1
	v_exp_f32_e32 v79, v79
	v_lshlrev_b32_e32 v68, 16, v65
	v_and_b32_e32 v69, 0xffff0000, v65
	v_pk_add_f32 v[72:73], v[66:67], v[68:69]
	v_pk_mul_f32 v[68:69], v[64:65], v[68:69] op_sel_hi:[0,1]
	v_lshlrev_b32_e32 v70, 16, v71
	v_and_b32_e32 v71, 0xffff0000, v71
	v_pk_fma_f32 v[90:91], v[66:67], s[22:23], v[68:69] op_sel_hi:[1,0,1]
	v_pk_mul_f32 v[66:67], v[72:73], s[22:23] op_sel_hi:[1,0]
	v_and_b32_e32 v103, 0xffff0000, v128
	v_pk_fma_f32 v[92:93], v[64:65], v[70:71], v[66:67] op_sel_hi:[0,1,1]
	v_pk_add_f32 v[66:67], v[72:73], v[70:71]
	s_waitcnt vmcnt(19)
	v_mov_b32_e32 v65, v138
	v_mov_b32_e32 v71, v138
	s_nop 1
	v_permlane32_swap_b32_e32 v65, v71
	s_nop 1
	v_lshlrev_b32_e32 v106, 16, v129
	v_lshlrev_b32_e32 v68, 16, v65
	v_and_b32_e32 v69, 0xffff0000, v65
	v_pk_add_f32 v[72:73], v[66:67], v[68:69]
	v_pk_mul_f32 v[68:69], v[64:65], v[68:69] op_sel_hi:[0,1]
	v_lshlrev_b32_e32 v70, 16, v71
	v_and_b32_e32 v71, 0xffff0000, v71
	v_pk_fma_f32 v[94:95], v[66:67], s[22:23], v[68:69] op_sel_hi:[1,0,1]
	v_pk_mul_f32 v[66:67], v[72:73], s[22:23] op_sel_hi:[1,0]
	v_and_b32_e32 v107, 0xffff0000, v129
	v_pk_fma_f32 v[96:97], v[64:65], v[70:71], v[66:67] op_sel_hi:[0,1,1]
	v_pk_add_f32 v[66:67], v[72:73], v[70:71]
	s_waitcnt vmcnt(15)
	v_mov_b32_e32 v65, v142
	v_mov_b32_e32 v71, v142
	s_nop 1
	v_permlane32_swap_b32_e32 v65, v71
	s_nop 1
	v_lshlrev_b32_e32 v161, 4, v160
	v_lshlrev_b32_e32 v68, 16, v65
	v_and_b32_e32 v69, 0xffff0000, v65
	v_pk_add_f32 v[72:73], v[66:67], v[68:69]
	v_pk_mul_f32 v[68:69], v[64:65], v[68:69] op_sel_hi:[0,1]
	v_lshlrev_b32_e32 v70, 16, v71
	v_and_b32_e32 v71, 0xffff0000, v71
	v_pk_fma_f32 v[82:83], v[66:67], s[22:23], v[68:69] op_sel_hi:[1,0,1]
	v_pk_mul_f32 v[66:67], v[72:73], s[22:23] op_sel_hi:[1,0]
	v_exp_f32_e32 v82, v82
	v_pk_fma_f32 v[98:99], v[64:65], v[70:71], v[66:67] op_sel_hi:[0,1,1]
	v_pk_add_f32 v[66:67], v[72:73], v[70:71]
	s_waitcnt vmcnt(11)
	v_mov_b32_e32 v65, v146
	v_mov_b32_e32 v71, v146
	s_nop 1
	v_permlane32_swap_b32_e32 v65, v71
	s_nop 1
	v_exp_f32_e32 v83, v83
	v_lshlrev_b32_e32 v68, 16, v65
	v_and_b32_e32 v69, 0xffff0000, v65
	v_pk_add_f32 v[72:73], v[66:67], v[68:69]
	v_pk_mul_f32 v[68:69], v[64:65], v[68:69] op_sel_hi:[0,1]
	v_lshlrev_b32_e32 v70, 16, v71
	v_and_b32_e32 v71, 0xffff0000, v71
	v_pk_fma_f32 v[76:77], v[66:67], s[22:23], v[68:69] op_sel_hi:[1,0,1]
	v_pk_mul_f32 v[66:67], v[72:73], s[22:23] op_sel_hi:[1,0]
	v_exp_f32_e32 v76, v76
	v_pk_fma_f32 v[80:81], v[64:65], v[70:71], v[66:67] op_sel_hi:[0,1,1]
	v_pk_add_f32 v[66:67], v[72:73], v[70:71]
	s_waitcnt vmcnt(7)
	v_mov_b32_e32 v65, v150
	v_mov_b32_e32 v71, v150
	s_nop 1
	v_permlane32_swap_b32_e32 v65, v71
	s_nop 1
	v_exp_f32_e32 v80, v80
	v_lshlrev_b32_e32 v68, 16, v65
	v_and_b32_e32 v69, 0xffff0000, v65
	v_pk_add_f32 v[100:101], v[66:67], v[68:69]
	v_pk_mul_f32 v[68:69], v[64:65], v[68:69] op_sel_hi:[0,1]
	v_lshlrev_b32_e32 v70, 16, v71
	v_and_b32_e32 v71, 0xffff0000, v71
	v_pk_fma_f32 v[72:73], v[66:67], s[22:23], v[68:69] op_sel_hi:[1,0,1]
	v_pk_mul_f32 v[66:67], v[100:101], s[22:23] op_sel_hi:[1,0]
	v_exp_f32_e32 v81, v81
	v_pk_fma_f32 v[74:75], v[64:65], v[70:71], v[66:67] op_sel_hi:[0,1,1]
	v_pk_add_f32 v[66:67], v[100:101], v[70:71]
	s_waitcnt vmcnt(3)
; #define LAS __attribute__((address_space(3)))
; __device__ __forceinline__ unsigned cvt_pk_bf16(float lo, float hi) { unsigned r; asm volatile("v_cvt_pk_bf16_f32 %0, %1, %2" : "=v"(r) : "v"(lo), "v"(hi)); return r; }
; #define RAW2(w) ((f32x2){__uint_as_float((w) << 16), __uint_as_float((w) & 0xffff0000u)})
; template <int role> __device__ __forceinline__ void ph_scan1m_r(Ctx& C) {
;     ...
;               GT2 = (f32x2){__builtin_amdgcn_exp2f(bef.x * 1.44269504f), __builtin_amdgcn_exp2f(bef.y * 1.44269504f)}; }
;             *(LAS f32x2*)(gT + c0) = GT2;
;             float bgx[8], bgy[8], kgx[8], kgy[8];
;             { LAS bf16* wKR = imKR + par * 72 + c0; LAS bf16* wBK = imBK + (8 * par) * 72 + c0;
; #pragma unroll
;               for (int j = 0; j < 8; ++j) {
;                   const f32x2 eL = (f32x2){__builtin_amdgcn_exp2f(Lt[j].x), __builtin_amdgcn_exp2f(Lt[j].y)}, eLm = (f32x2){__builtin_amdgcn_exp2f(Lm[j].x), __builtin_amdgcn_exp2f(Lm[j].y)};
;                   const f32x2 ie = (f32x2){__builtin_amdgcn_rcpf(eL.x), __builtin_amdgcn_rcpf(eL.y)};
;                   const f32x2 nk = RAW2(rn[j]), a_ = RAW2(ra[j]), rr = RAW2(rr_[j]);
;                   const f32x2 b_ = -nk * a_;
;                   const f32x2 kkh = nk * eLm, rh = rr * eL, bt = b_ * ie, bgf = bt * GT2;
;                   *(LAS unsigned*)(wKR + (2 * j) * 72) = pg8::cvt_pk_bf16(kkh.x, kkh.y); *(LAS unsigned*)(wKR + (16 + 2 * j) * 72) = pg8::cvt_pk_bf16(rh.x, rh.y);
;                   *(LAS unsigned*)(wBK + j * 72) = pg8::cvt_pk_bf16(bt.x, bt.y);
;                   f32x2 kgf = (f32x2){0.f, 0.f};
;                   if (role) { const f32x2 kr = RAW2(rk[j]); const f32x2 kd = kr * (a_ * ka2 + k1), kt_ = kd * ie; kgf = kt_ * GT2; *(LAS unsigned*)(wBK + (16 + j) * 72) = pg8::cvt_pk_bf16(kt_.x, kt_.y); }
;                   bgx[j] = bgf.x; bgy[j] = bgf.y; if (role) { kgx[j] = kgf.x; kgy[j] = kgf.y; } } }
	v_mov_b32_e32 v65, v154
	v_mov_b32_e32 v71, v154
	s_nop 1
	v_permlane32_swap_b32_e32 v65, v71
	s_nop 1
	v_exp_f32_e32 v77, v77
	v_lshlrev_b32_e32 v68, 16, v65
	v_and_b32_e32 v69, 0xffff0000, v65
	v_pk_add_f32 v[100:101], v[66:67], v[68:69]
	v_pk_mul_f32 v[68:69], v[64:65], v[68:69] op_sel_hi:[0,1]
	v_lshlrev_b32_e32 v70, 16, v71
	v_and_b32_e32 v71, 0xffff0000, v71
	v_pk_fma_f32 v[66:67], v[66:67], s[22:23], v[68:69] op_sel_hi:[1,0,1]
	v_pk_mul_f32 v[68:69], v[100:101], s[22:23] op_sel_hi:[1,0]
	v_exp_f32_e32 v74, v74
	v_pk_fma_f32 v[68:69], v[64:65], v[70:71], v[68:69] op_sel_hi:[0,1,1]
	v_pk_add_f32 v[64:65], v[100:101], v[70:71]
	v_lshl_add_u32 v70, v158, 3, s42
	v_mul_f32_e32 v64, 0x3fb8aa3b, v64
	v_mul_f32_e32 v65, 0x3fb8aa3b, v65
	v_exp_f32_e32 v64, v64
	v_exp_f32_e32 v65, v65
	v_lshlrev_b32_e32 v71, 2, v158
	v_lshlrev_b32_e32 v100, 16, v127
	v_and_b32_e32 v101, 0xffff0000, v127
	ds_write_b64 v70, v[64:65] offset:14336
	v_mul_lo_u32 v70, v160, s54
	v_add3_u32 v104, s42, v70, v71
	v_mul_lo_u32 v70, v160, s55
	v_add3_u32 v108, s42, v70, v71
	v_exp_f32_e32 v70, v84
	v_exp_f32_e32 v71, v85
	v_pk_mul_f32 v[78:79], v[78:79], v[100:101]
	v_pk_mul_f32 v[102:103], v[102:103], v[100:101] neg_lo:[0,1] neg_hi:[0,1]
	v_rcp_f32_e32 v84, v70
	v_rcp_f32_e32 v85, v71
	v_cvt_pk_bf16_f32 v78, v78, v79
	v_pk_mul_f32 v[100:101], v[70:71], v[106:107]
	ds_write_b32 v104, v78
	v_cvt_pk_bf16_f32 v78, v100, v101
	v_pk_mul_f32 v[84:85], v[102:103], v[84:85]
	ds_write_b32 v104, v78 offset:2304
	v_cvt_pk_bf16_f32 v78, v84, v85
	ds_write_b32 v108, v78 offset:4608
	v_exp_f32_e32 v78, v88
	v_exp_f32_e32 v79, v89
	v_pk_mul_f32 v[70:71], v[84:85], v[64:65]
	v_exp_f32_e32 v84, v86
	v_exp_f32_e32 v85, v87
	v_rcp_f32_e32 v86, v78
	v_rcp_f32_e32 v87, v79
	v_lshlrev_b32_e32 v88, 16, v131
	v_and_b32_e32 v89, 0xffff0000, v131
	v_pk_mul_f32 v[84:85], v[84:85], v[88:89]
	v_lshlrev_b32_e32 v100, 16, v132
	v_and_b32_e32 v101, 0xffff0000, v132
	v_lshlrev_b32_e32 v102, 16, v133
	v_and_b32_e32 v103, 0xffff0000, v133
	v_cvt_pk_bf16_f32 v84, v84, v85
	v_pk_mul_f32 v[100:101], v[100:101], v[88:89] neg_lo:[0,1] neg_hi:[0,1]
	v_pk_mul_f32 v[88:89], v[78:79], v[102:103]
	ds_write_b32 v104, v84 offset:288
	v_cvt_pk_bf16_f32 v84, v88, v89
	v_pk_mul_f32 v[86:87], v[100:101], v[86:87]
	ds_write_b32 v104, v84 offset:2592
	v_cvt_pk_bf16_f32 v84, v86, v87
	ds_write_b32 v108, v84 offset:4752
	v_exp_f32_e32 v84, v92
	v_exp_f32_e32 v85, v93
	v_pk_mul_f32 v[78:79], v[86:87], v[64:65]
	v_exp_f32_e32 v86, v90
	v_exp_f32_e32 v87, v91
	v_rcp_f32_e32 v88, v84
	v_rcp_f32_e32 v89, v85
	v_lshlrev_b32_e32 v90, 16, v135
	v_and_b32_e32 v91, 0xffff0000, v135
	v_lshlrev_b32_e32 v100, 16, v137
	v_and_b32_e32 v101, 0xffff0000, v137
	v_lshlrev_b32_e32 v92, 16, v136
	v_and_b32_e32 v93, 0xffff0000, v136
	v_pk_mul_f32 v[86:87], v[86:87], v[90:91]
	v_pk_mul_f32 v[84:85], v[84:85], v[100:101]
	v_pk_mul_f32 v[92:93], v[92:93], v[90:91] neg_lo:[0,1] neg_hi:[0,1]
	v_cvt_pk_bf16_f32 v86, v86, v87
	ds_write_b32 v104, v86 offset:576
	v_cvt_pk_bf16_f32 v84, v84, v85
	v_pk_mul_f32 v[88:89], v[92:93], v[88:89]
	ds_write_b32 v104, v84 offset:2880
	v_cvt_pk_bf16_f32 v84, v88, v89
	ds_write_b32 v108, v84 offset:4896
	v_exp_f32_e32 v84, v96
	v_exp_f32_e32 v85, v97
	v_exp_f32_e32 v86, v94
	v_exp_f32_e32 v87, v95
	v_pk_mul_f32 v[90:91], v[88:89], v[64:65]
	v_rcp_f32_e32 v88, v84
	v_rcp_f32_e32 v89, v85
	v_lshlrev_b32_e32 v92, 16, v139
	v_and_b32_e32 v93, 0xffff0000, v139
	v_lshlrev_b32_e32 v96, 16, v141
	v_and_b32_e32 v97, 0xffff0000, v141
	v_lshlrev_b32_e32 v94, 16, v140
	v_and_b32_e32 v95, 0xffff0000, v140
	v_pk_mul_f32 v[86:87], v[86:87], v[92:93]
	v_pk_mul_f32 v[84:85], v[84:85], v[96:97]
	v_pk_mul_f32 v[94:95], v[94:95], v[92:93] neg_lo:[0,1] neg_hi:[0,1]
	v_cvt_pk_bf16_f32 v86, v86, v87
	ds_write_b32 v104, v86 offset:864
	v_cvt_pk_bf16_f32 v84, v84, v85
	v_pk_mul_f32 v[88:89], v[94:95], v[88:89]
	ds_write_b32 v104, v84 offset:3168
	v_cvt_pk_bf16_f32 v84, v88, v89
	ds_write_b32 v108, v84 offset:5040
	v_exp_f32_e32 v84, v98
	v_exp_f32_e32 v85, v99
	v_pk_mul_f32 v[92:93], v[88:89], v[64:65]
	v_lshlrev_b32_e32 v88, 16, v143
	v_rcp_f32_e32 v86, v84
	v_rcp_f32_e32 v87, v85
	v_and_b32_e32 v89, 0xffff0000, v143
	v_pk_mul_f32 v[82:83], v[82:83], v[88:89]
	v_lshlrev_b32_e32 v94, 16, v144
	v_and_b32_e32 v95, 0xffff0000, v144
	v_lshlrev_b32_e32 v96, 16, v145
	v_and_b32_e32 v97, 0xffff0000, v145
	v_cvt_pk_bf16_f32 v82, v82, v83
	v_pk_mul_f32 v[94:95], v[94:95], v[88:89] neg_lo:[0,1] neg_hi:[0,1]
	v_pk_mul_f32 v[84:85], v[84:85], v[96:97]
	ds_write_b32 v104, v82 offset:1152
	v_cvt_pk_bf16_f32 v82, v84, v85
	v_pk_mul_f32 v[86:87], v[94:95], v[86:87]
	ds_write_b32 v104, v82 offset:3456
	v_cvt_pk_bf16_f32 v82, v86, v87
	ds_write_b32 v108, v82 offset:5184
	v_rcp_f32_e32 v82, v80
	v_rcp_f32_e32 v83, v81
	v_lshlrev_b32_e32 v84, 16, v147
	v_and_b32_e32 v85, 0xffff0000, v147
	v_pk_mul_f32 v[76:77], v[76:77], v[84:85]
	v_exp_f32_e32 v75, v75
	v_pk_mul_f32 v[88:89], v[86:87], v[64:65]
	v_lshlrev_b32_e32 v86, 16, v148
	v_and_b32_e32 v87, 0xffff0000, v148
	v_lshlrev_b32_e32 v94, 16, v149
	v_and_b32_e32 v95, 0xffff0000, v149
	v_cvt_pk_bf16_f32 v76, v76, v77
	v_exp_f32_e32 v72, v72
	v_exp_f32_e32 v73, v73
	v_pk_mul_f32 v[86:87], v[86:87], v[84:85] neg_lo:[0,1] neg_hi:[0,1]
	v_pk_mul_f32 v[80:81], v[80:81], v[94:95]
	ds_write_b32 v104, v76 offset:1440
	v_cvt_pk_bf16_f32 v76, v80, v81
	v_pk_mul_f32 v[82:83], v[86:87], v[82:83]
	ds_write_b32 v104, v76 offset:3744
	v_cvt_pk_bf16_f32 v76, v82, v83
	ds_write_b32 v108, v76 offset:5328
	v_rcp_f32_e32 v76, v74
	v_rcp_f32_e32 v77, v75
	v_lshlrev_b32_e32 v80, 16, v151
	v_and_b32_e32 v81, 0xffff0000, v151
	v_pk_mul_f32 v[72:73], v[72:73], v[80:81]
	v_exp_f32_e32 v68, v68
	v_exp_f32_e32 v69, v69
	v_pk_mul_f32 v[84:85], v[82:83], v[64:65]
	v_lshlrev_b32_e32 v82, 16, v152
	v_and_b32_e32 v83, 0xffff0000, v152
	v_lshlrev_b32_e32 v86, 16, v153
	v_and_b32_e32 v87, 0xffff0000, v153
	v_cvt_pk_bf16_f32 v72, v72, v73
	v_pk_mul_f32 v[82:83], v[82:83], v[80:81] neg_lo:[0,1] neg_hi:[0,1]
	v_pk_mul_f32 v[74:75], v[74:75], v[86:87]
	ds_write_b32 v104, v72 offset:1728
	v_cvt_pk_bf16_f32 v72, v74, v75
	v_pk_mul_f32 v[76:77], v[82:83], v[76:77]
	ds_write_b32 v104, v72 offset:4032
	v_cvt_pk_bf16_f32 v72, v76, v77
	ds_write_b32 v108, v72 offset:5472
	v_rcp_f32_e32 v72, v68
	v_rcp_f32_e32 v73, v69
	v_exp_f32_e32 v66, v66
	v_exp_f32_e32 v67, v67
	v_pk_mul_f32 v[80:81], v[64:65], v[76:77]
	s_waitcnt vmcnt(2)
; #define LAS __attribute__((address_space(3)))
; __device__ __forceinline__ unsigned cvt_pk_bf16(float lo, float hi) { unsigned r; asm volatile("v_cvt_pk_bf16_f32 %0, %1, %2" : "=v"(r) : "v"(lo), "v"(hi)); return r; }
; template <int role> __device__ __forceinline__ void ph_scan1m_r(Ctx& C) {
;     ...
;             { u32x4 w0, w1;
; #pragma unroll
;               for (int q = 0; q < 4; ++q) { w0[q] = pg8::cvt_pk_bf16(bgx[2 * q], bgx[2 * q + 1]); w1[q] = pg8::cvt_pk_bf16(bgy[2 * q], bgy[2 * q + 1]); }
;               *(LAS u32x4*)(imBGT + c0 * 40 + 8 * par) = w0; *(LAS u32x4*)(imBGT + (c0 + 1) * 40 + 8 * par) = w1;
;     ...
;             if (sb + 1 < CHL / 16) SM_LOADRAW(sb + 1);
	v_lshlrev_b32_e32 v74, 16, v155
	v_and_b32_e32 v75, 0xffff0000, v155
	s_waitcnt vmcnt(1)
	v_lshlrev_b32_e32 v76, 16, v156
	v_and_b32_e32 v77, 0xffff0000, v156
	v_pk_mul_f32 v[76:77], v[76:77], v[74:75] neg_lo:[0,1] neg_hi:[0,1]
	s_waitcnt vmcnt(0)
	v_lshlrev_b32_e32 v82, 16, v157
	v_pk_mul_f32 v[72:73], v[76:77], v[72:73]
	v_and_b32_e32 v83, 0xffff0000, v157
	v_pk_mul_f32 v[66:67], v[66:67], v[74:75]
	v_pk_mul_f32 v[74:75], v[64:65], v[72:73]
	v_cvt_pk_bf16_f32 v64, v66, v67
	v_pk_mul_f32 v[68:69], v[68:69], v[82:83]
	ds_write_b32 v104, v64 offset:2016
	v_cvt_pk_bf16_f32 v64, v68, v69
	ds_write_b32 v104, v64 offset:4320
	v_cvt_pk_bf16_f32 v64, v72, v73
	v_mul_u32_u24_e32 v72, 0xa0, v158
	ds_write_b32 v108, v64 offset:5616
	v_cvt_pk_bf16_f32 v64, v70, v78
	v_cvt_pk_bf16_f32 v68, v71, v79
	v_cvt_pk_bf16_f32 v65, v90, v92
	v_cvt_pk_bf16_f32 v69, v91, v93
	v_cvt_pk_bf16_f32 v66, v88, v84
	v_cvt_pk_bf16_f32 v70, v89, v85
	v_cvt_pk_bf16_f32 v67, v80, v74
	v_add3_u32 v72, s42, v72, v161
	v_cvt_pk_bf16_f32 v71, v81, v75
	ds_write_b128 v72, v[64:67] offset:9216
	ds_write_b128 v72, v[68:71] offset:9296
	s_add_i32 s67, s25, s62
	s_add_i32 s2, s65, 16
	s_waitcnt lgkmcnt(0)
	s_and_b64 s[0:1], s[28:29], exec
	s_cselect_b32 s36, s67, s2
	v_lshlrev_b32_e32 v96, 3, v160
	s_cmpk_eq_i32 s62, 0x1f0
	s_cbranch_scc1 .Lsc1_r0_noload
	s_add_i32 s67, s67, 16
	s_and_b64 s[0:1], s[28:29], exec
	s_cselect_b32 s0, s67, s65
	s_ashr_i32 s1, s0, 31
	s_lshl_b64 s[0:1], s[0:1], 11
	s_or_b32 s0, s0, s66
	s_add_u32 s2, s27, s0
	s_addc_u32 s3, s59, s1
	s_add_u32 s4, s40, s0
	s_addc_u32 s5, s41, s1
	v_mov_b32_e32 v232, v124
	s_add_u32 s6, s60, s0
	s_addc_u32 s7, s61, s1
	v_ashrrev_i32_e32 v242, 5, v232
	v_ashrrev_i32_e32 v233, 31, v242
	v_lshlrev_b32_e32 v232, 1, v232
	s_add_u32 s8, s23, s0
	v_mov_b64_e32 v[240:241], s[34:35]
	v_and_b32_e32 v250, 62, v232
	s_addc_u32 s9, s38, s1
	v_mul_lo_u32 v243, s30, v233
	v_mul_lo_u32 v244, s31, v242
	v_mad_u64_u32 v[232:233], s[0:1], s30, v242, 0
	v_mad_u64_u32 v[240:241], s[0:1], s30, v242, v[240:241]
	v_add3_u32 v233, v233, v243, v244
	v_or_b32_e32 v232, v232, v250
	v_add3_u32 v241, v244, v241, v243
	v_lshlrev_b64 v[232:233], 1, v[232:233]
	v_or_b32_e32 v242, v240, v250
	v_mov_b32_e32 v243, v241
	v_lshl_add_u64 v[234:235], s[2:3], 0, v[232:233]
	v_lshl_add_u64 v[236:237], s[4:5], 0, v[232:233]
	v_lshl_add_u64 v[238:239], s[6:7], 0, v[232:233]
	v_lshl_add_u64 v[232:233], s[8:9], 0, v[232:233]
	v_lshlrev_b64 v[242:243], 1, v[242:243]
	v_lshl_add_u64 v[244:245], s[2:3], 0, v[242:243]
	v_lshl_add_u64 v[246:247], s[4:5], 0, v[242:243]
	v_lshl_add_u64 v[248:249], s[6:7], 0, v[242:243]
	v_lshl_add_u64 v[242:243], s[8:9], 0, v[242:243]
	global_load_dword v126, v[234:235], off
	global_load_dword v127, v[236:237], off
	global_load_dword v128, v[238:239], off
	global_load_dword v129, v[232:233], off
	global_load_dword v130, v[244:245], off
	global_load_dword v131, v[246:247], off
	global_load_dword v132, v[248:249], off
	global_load_dword v133, v[242:243], off
	v_lshl_add_u64 v[232:233], v[240:241], 0, s[34:35]
	v_or_b32_e32 v234, v232, v250
	v_mov_b32_e32 v235, v233
	v_lshl_add_u64 v[232:233], v[232:233], 0, s[34:35]
	v_lshlrev_b64 v[234:235], 1, v[234:235]
	v_or_b32_e32 v242, v232, v250
	v_mov_b32_e32 v243, v233
	v_lshl_add_u64 v[236:237], s[2:3], 0, v[234:235]
	v_lshl_add_u64 v[238:239], s[4:5], 0, v[234:235]
	v_lshl_add_u64 v[240:241], s[6:7], 0, v[234:235]
	v_lshl_add_u64 v[234:235], s[8:9], 0, v[234:235]
	v_lshlrev_b64 v[242:243], 1, v[242:243]
	v_lshl_add_u64 v[232:233], v[232:233], 0, s[34:35]
	v_lshl_add_u64 v[244:245], s[2:3], 0, v[242:243]
	v_lshl_add_u64 v[246:247], s[4:5], 0, v[242:243]
	v_lshl_add_u64 v[248:249], s[6:7], 0, v[242:243]
	v_lshl_add_u64 v[242:243], s[8:9], 0, v[242:243]
	global_load_dword v134, v[236:237], off
	global_load_dword v135, v[238:239], off
	global_load_dword v136, v[240:241], off
	global_load_dword v137, v[234:235], off
	global_load_dword v138, v[244:245], off
	global_load_dword v139, v[246:247], off
	global_load_dword v140, v[248:249], off
	global_load_dword v141, v[242:243], off
	v_or_b32_e32 v234, v232, v250
	v_mov_b32_e32 v235, v233
	v_lshl_add_u64 v[232:233], v[232:233], 0, s[34:35]
	v_lshlrev_b64 v[234:235], 1, v[234:235]
	v_or_b32_e32 v242, v232, v250
	v_mov_b32_e32 v243, v233
	v_lshl_add_u64 v[236:237], s[2:3], 0, v[234:235]
	v_lshl_add_u64 v[238:239], s[4:5], 0, v[234:235]
	v_lshl_add_u64 v[240:241], s[6:7], 0, v[234:235]
	v_lshl_add_u64 v[234:235], s[8:9], 0, v[234:235]
	v_lshlrev_b64 v[242:243], 1, v[242:243]
	v_lshl_add_u64 v[232:233], v[232:233], 0, s[34:35]
	v_lshl_add_u64 v[244:245], s[2:3], 0, v[242:243]
	v_lshl_add_u64 v[246:247], s[4:5], 0, v[242:243]
	v_lshl_add_u64 v[248:249], s[6:7], 0, v[242:243]
	v_lshl_add_u64 v[242:243], s[8:9], 0, v[242:243]
	global_load_dword v142, v[236:237], off
	global_load_dword v143, v[238:239], off
	global_load_dword v144, v[240:241], off
	global_load_dword v145, v[234:235], off
	global_load_dword v146, v[244:245], off
	global_load_dword v147, v[246:247], off
	global_load_dword v148, v[248:249], off
	global_load_dword v149, v[242:243], off
	v_or_b32_e32 v234, v232, v250
	v_mov_b32_e32 v235, v233
	v_lshl_add_u64 v[232:233], v[232:233], 0, s[34:35]
	v_lshlrev_b64 v[234:235], 1, v[234:235]
	v_or_b32_e32 v232, v232, v250
	v_lshl_add_u64 v[236:237], s[2:3], 0, v[234:235]
	v_lshlrev_b64 v[232:233], 1, v[232:233]
	v_lshl_add_u64 v[238:239], s[4:5], 0, v[234:235]
	v_lshl_add_u64 v[240:241], s[6:7], 0, v[234:235]
	v_lshl_add_u64 v[234:235], s[8:9], 0, v[234:235]
	v_lshl_add_u64 v[242:243], s[2:3], 0, v[232:233]
	v_lshl_add_u64 v[244:245], s[4:5], 0, v[232:233]
	v_lshl_add_u64 v[246:247], s[6:7], 0, v[232:233]
	v_lshl_add_u64 v[232:233], s[8:9], 0, v[232:233]
	global_load_dword v150, v[236:237], off
	global_load_dword v151, v[238:239], off
	global_load_dword v152, v[240:241], off
	global_load_dword v153, v[234:235], off
	global_load_dword v154, v[242:243], off
	global_load_dword v155, v[244:245], off
	global_load_dword v156, v[246:247], off
	global_load_dword v157, v[232:233], off
; #define LAS __attribute__((address_space(3)))
; template <int role> __device__ __forceinline__ void ph_scan1m_r(Ctx& C) {
;     ...
;             { f32x16 m;
; #pragma unroll
;               for (int e = 0; e < 16; ++e) m[e] = 0.f;
; #pragma unroll
;               for (int ks = 0; ks < 4; ++ks) { const bf16x8 af = *(const LAS bf16x8*)(imBK + r31 * 72 + 16 * ks + 8 * hh), bfr = *(const LAS bf16x8*)(imKR + r31 * 72 + 16 * ks + 8 * hh); m = __builtin_amdgcn_mfma_f32_32x32x16_bf16(af, bfr, m, 0, 0, 0); }
;               asm volatile("s_waitcnt lgkmcnt(0)" ::: "memory");
;               const int tq = r31 & 15; const bool ycol = r31 >= 16;
; #pragma unroll
;               for (int g = 0; g < 4; ++g) { f32x4 o;
; #pragma unroll
;                   for (int e = 0; e < 4; ++e) { const int sq = 2 * (4 * hh + e) + (g & 1); const bool ok = ycol ? (sq <= tq) : (sq < tq); o[e] = ok ? m[4 * g + e] : 0.f; }
;                   *(LAS f32x4*)(MT + r31 * 36 + 8 * g + 4 * hh) = o; } }
;             asm volatile("s_waitcnt lgkmcnt(0)" ::: "memory");
;             __builtin_amdgcn_sched_barrier(0);
;             f32x16 ya[2];
; #pragma unroll
;             for (int ct = 0; ct < 2; ++ct)
; #pragma unroll
;                 for (int e = 0; e < 16; ++e) ya[ct][e] = 0.f;
; #pragma unroll
;             for (int kt = 0; kt < 2; ++kt)
; #pragma unroll
;                 for (int sI = 0; sI < 2; ++sI) { const LAS bf16* ap = imKR + r31 * 72 + 32 * kt + 16 * sI + 4 * hh; const u32x2 lo = *(const LAS u32x2*)ap, hi = *(const LAS u32x2*)(ap + 8);
;                     u32x4 pa; pa.x = lo.x; pa.y = lo.y; pa.z = hi.x; pa.w = hi.y; const bf16x8 af = __builtin_bit_cast(bf16x8, pa);
; #pragma unroll
;                     for (int ct = 0; ct < 2; ++ct) { const f32x16& x = st[kt][ct];
;                         const bf16x8 bfr = pack8s(x[8 * sI], x[8 * sI + 1], x[8 * sI + 2], x[8 * sI + 3], x[8 * sI + 4], x[8 * sI + 5], x[8 * sI + 6], x[8 * sI + 7]);
;                         ya[ct] = __builtin_amdgcn_mfma_f32_32x32x16_bf16(af, bfr, ya[ct], 0, 0, 0); } }
.Lsc1_r0_noload:
	v_mov_b32_e32 v162, s42
	s_ashr_i32 s37, s36, 31
	v_lshlrev_b32_e32 v64, 4, v158
	v_sub_u32_e32 v92, v72, v64
	ds_read_b128 v[64:67], v92 offset:4608
	ds_read_b128 v[68:71], v92
	ds_read_b128 v[80:83], v92 offset:32
	ds_read_b128 v[84:87], v92 offset:4640
	ds_read_b128 v[88:91], v92 offset:4672
	v_and_b32_e32 v97, 15, v159
	v_or_b32_e32 v98, 2, v96
	v_cmp_lt_i32_e64 s[2:3], v96, v97
	v_cmp_le_i32_e64 s[4:5], v98, v97
	v_mad_u32_u24 v163, v158, s54, v162
	s_waitcnt lgkmcnt(3)
	v_mfma_f32_32x32x16_bf16 v[64:79], v[64:67], v[68:71], 0
	v_cndmask_b32_e64 v100, 0, 1, s[2:3]
	v_cmp_le_i32_e64 s[2:3], v96, v97
	v_add_u32_e32 v99, v163, v161
	s_nop 0
	v_cndmask_b32_e64 v101, 0, 1, s[2:3]
	v_cmp_lt_i32_e64 s[2:3], v98, v97
	s_waitcnt lgkmcnt(1)
	v_mfma_f32_32x32x16_bf16 v[64:79], v[84:87], v[80:83], v[64:79]
	ds_read_b128 v[80:83], v92 offset:4704
	ds_read_b128 v[84:87], v92 offset:64
	ds_read_b128 v[92:95], v92 offset:96
	v_cndmask_b32_e64 v102, 0, 1, s[2:3]
	v_cmp_gt_u32_e64 s[2:3], 16, v158
	s_waitcnt lgkmcnt(0)
	s_nop 1
	v_cndmask_b32_e64 v100, v101, v100, s[2:3]
	s_waitcnt lgkmcnt(1)
	v_mfma_f32_32x32x16_bf16 v[64:79], v[88:91], v[84:87], v[64:79]
	v_or_b32_e32 v85, 4, v96
	v_cndmask_b32_e64 v84, 0, 1, s[4:5]
	v_cmp_lt_i32_e64 s[4:5], v85, v97
	v_cndmask_b32_e64 v84, v84, v102, s[2:3]
	v_and_b32_e32 v100, 1, v100
	v_cndmask_b32_e64 v86, 0, 1, s[4:5]
	v_cmp_le_i32_e64 s[4:5], v85, v97
	s_waitcnt lgkmcnt(0)
	v_mfma_f32_32x32x16_bf16 v[64:79], v[80:83], v[92:95], v[64:79]
	v_or_b32_e32 v80, 6, v96
	v_cmp_lt_i32_e64 s[10:11], v80, v97
	v_cndmask_b32_e64 v85, 0, 1, s[4:5]
	v_cndmask_b32_e64 v85, v85, v86, s[2:3]
	v_cndmask_b32_e64 v81, 0, 1, s[10:11]
	v_cmp_le_i32_e64 s[10:11], v80, v97
	v_and_b32_e32 v84, 1, v84
	v_and_b32_e32 v85, 1, v85
	v_cndmask_b32_e64 v80, 0, 1, s[10:11]
	v_cndmask_b32_e64 v80, v80, v81, s[2:3]
	v_and_b32_e32 v80, 1, v80
	v_cmp_eq_u32_e64 s[4:5], 1, v100
	v_cmp_eq_u32_e64 s[6:7], 1, v84
	v_cmp_eq_u32_e64 s[8:9], 1, v85
	v_cmp_eq_u32_e64 s[10:11], 1, v80
	v_cndmask_b32_e64 v64, 0, v64, s[4:5]
	v_cndmask_b32_e64 v65, 0, v65, s[6:7]
	v_cndmask_b32_e64 v66, 0, v66, s[8:9]
	v_cndmask_b32_e64 v67, 0, v67, s[10:11]
	ds_write_b128 v99, v[64:67] offset:4608
	v_or_b32_e32 v65, 3, v96
	v_cmp_lt_i32_e64 s[14:15], v65, v97
	v_cndmask_b32_e64 v64, 0, 1, s[2:3]
	v_or_b32_e32 v64, v96, v64
	v_cndmask_b32_e64 v66, 0, 1, s[14:15]
	v_cmp_le_i32_e64 s[14:15], v65, v97
	v_cmp_gt_i32_e64 s[12:13], v97, v64
	s_nop 0
	v_cndmask_b32_e64 v65, 0, 1, s[14:15]
	v_cndmask_b32_e64 v65, v65, v66, s[2:3]
	v_or_b32_e32 v66, 5, v96
	v_cmp_lt_i32_e64 s[16:17], v66, v97
	v_cndmask_b32_e64 v64, 0, v68, s[12:13]
	v_and_b32_e32 v65, 1, v65
	v_cndmask_b32_e64 v67, 0, 1, s[16:17]
	v_cmp_le_i32_e64 s[16:17], v66, v97
	v_cmp_eq_u32_e64 s[14:15], 1, v65
	s_nop 0
	v_cndmask_b32_e64 v66, 0, 1, s[16:17]
	v_cndmask_b32_e64 v66, v66, v67, s[2:3]
	v_or_b32_e32 v67, 7, v96
	v_cmp_lt_i32_e64 s[18:19], v67, v97
	v_and_b32_e32 v66, 1, v66
	v_cmp_eq_u32_e64 s[16:17], 1, v66
	v_cndmask_b32_e64 v68, 0, 1, s[18:19]
	v_cmp_le_i32_e64 s[18:19], v67, v97
	v_cndmask_b32_e64 v65, 0, v69, s[14:15]
	v_cndmask_b32_e64 v66, 0, v70, s[16:17]
	v_cndmask_b32_e64 v67, 0, 1, s[18:19]
	v_cndmask_b32_e64 v67, v67, v68, s[2:3]
	v_and_b32_e32 v67, 1, v67
	v_cmp_eq_u32_e64 s[2:3], 1, v67
	s_nop 1
	v_cndmask_b32_e64 v67, 0, v71, s[2:3]
	ds_write_b128 v99, v[64:67] offset:4640
	v_cndmask_b32_e64 v64, 0, v72, s[4:5]
	v_cndmask_b32_e64 v65, 0, v73, s[6:7]
	v_cndmask_b32_e64 v66, 0, v74, s[8:9]
	v_cndmask_b32_e64 v67, 0, v75, s[10:11]
	ds_write_b128 v99, v[64:67] offset:4672
	v_cndmask_b32_e64 v64, 0, v76, s[12:13]
	v_cndmask_b32_e64 v65, 0, v77, s[14:15]
	v_cndmask_b32_e64 v66, 0, v78, s[16:17]
	v_cndmask_b32_e64 v67, 0, v79, s[2:3]
	ds_write_b128 v99, v[64:67] offset:4704
	s_waitcnt lgkmcnt(0)
	v_add_u32_e32 v104, v163, v96
	ds_read2_b64 v[64:67], v104 offset1:2
	v_cvt_pk_bf16_f32 v68, v0, v1
	v_cvt_pk_bf16_f32 v69, v2, v3
	v_cvt_pk_bf16_f32 v70, v4, v5
	v_cvt_pk_bf16_f32 v71, v6, v7
	s_nop 1
	s_waitcnt lgkmcnt(0)
	v_mfma_f32_32x32x16_bf16 v[80:95], v[64:67], v[68:71], 0
	v_cvt_pk_bf16_f32 v68, v16, v17
	v_cvt_pk_bf16_f32 v69, v18, v19
	v_cvt_pk_bf16_f32 v70, v20, v21
	v_cvt_pk_bf16_f32 v71, v22, v23
	s_nop 1
	ds_read2_b64 v[96:99], v104 offset0:4 offset1:6
	v_cvt_pk_bf16_f32 v100, v8, v9
	v_cvt_pk_bf16_f32 v101, v10, v11
	v_cvt_pk_bf16_f32 v102, v12, v13
	v_cvt_pk_bf16_f32 v103, v14, v15
	s_nop 1
	v_mfma_f32_32x32x16_bf16 v[64:79], v[64:67], v[68:71], 0
	s_waitcnt lgkmcnt(0)
	v_mfma_f32_32x32x16_bf16 v[80:95], v[96:99], v[100:103], v[80:95]
	v_cvt_pk_bf16_f32 v100, v24, v25
	v_cvt_pk_bf16_f32 v101, v26, v27
	v_cvt_pk_bf16_f32 v102, v28, v29
	v_cvt_pk_bf16_f32 v103, v30, v31
	s_nop 1
	s_nop 0
	v_mfma_f32_32x32x16_bf16 v[64:79], v[96:99], v[100:103], v[64:79]
	ds_read2_b64 v[96:99], v104 offset0:8 offset1:10
	v_cvt_pk_bf16_f32 v100, v32, v33
	v_cvt_pk_bf16_f32 v101, v34, v35
	v_cvt_pk_bf16_f32 v102, v36, v37
	v_cvt_pk_bf16_f32 v103, v38, v39
	s_nop 1
	s_waitcnt lgkmcnt(0)
	v_mfma_f32_32x32x16_bf16 v[80:95], v[96:99], v[100:103], v[80:95]
	v_cvt_pk_bf16_f32 v100, v48, v49
	v_cvt_pk_bf16_f32 v101, v50, v51
	v_cvt_pk_bf16_f32 v102, v52, v53
	v_cvt_pk_bf16_f32 v103, v54, v55
	s_nop 1
	s_nop 0
	v_mfma_f32_32x32x16_bf16 v[64:79], v[96:99], v[100:103], v[64:79]
	ds_read2_b64 v[96:99], v104 offset0:12 offset1:14
	v_cvt_pk_bf16_f32 v100, v40, v41
	v_cvt_pk_bf16_f32 v101, v42, v43
	v_cvt_pk_bf16_f32 v102, v44, v45
	v_cvt_pk_bf16_f32 v103, v46, v47
	s_nop 1
	s_waitcnt lgkmcnt(0)
; #define LAS __attribute__((address_space(3)))
; template <int role> __device__ __forceinline__ void ph_scan1m_r(Ctx& C) {
;     ...
;                         ya[ct] = __builtin_amdgcn_mfma_f32_32x32x16_bf16(af, bfr, ya[ct], 0, 0, 0); } }
;             bf16x8 vfr[2];
;             if (role) { const f32x4 m0 = *(const LAS f32x4*)(MT + r31 * 36 + 16 + 8 * hh), m1 = *(const LAS f32x4*)(MT + r31 * 36 + 20 + 8 * hh); const bf16x8 af = pack8s(m0[0], m0[1], m0[2], m0[3], m1[0], m1[1], m1[2], m1[3]);
; #pragma unroll
;                 for (int ct = 0; ct < 2; ++ct) { vfr[ct] = *(const LAS bf16x8*)(imVT + (32 * ct + r31) * 24 + 8 * hh); ya[ct] = __builtin_amdgcn_mfma_f32_32x32x16_bf16(af, vfr[ct], ya[ct], 0, 0, 0); } }
;             __builtin_amdgcn_sched_barrier(0);
;             f32x2 u2[16];
; #pragma unroll
;             for (int e = 0; e < 4; ++e) {
;                 const auto a0 = __builtin_amdgcn_permlane32_swap(__float_as_uint(ya[0][e]), __float_as_uint(ya[0][e]), false, false), a1 = __builtin_amdgcn_permlane32_swap(__float_as_uint(ya[1][e]), __float_as_uint(ya[1][e]), false, false);
;                 const auto b0 = __builtin_amdgcn_permlane32_swap(__float_as_uint(ya[0][4 + e]), __float_as_uint(ya[0][4 + e]), false, false), b1 = __builtin_amdgcn_permlane32_swap(__float_as_uint(ya[1][4 + e]), __float_as_uint(ya[1][4 + e]), false, false);
;                 u2[e] = (f32x2){__uint_as_float(a0[0]), __uint_as_float(a1[0])}; u2[4 + e] = (f32x2){__uint_as_float(a0[1]), __uint_as_float(a1[1])};
;                 u2[8 + e] = (f32x2){__uint_as_float(b0[0]), __uint_as_float(b1[0])}; u2[12 + e] = (f32x2){__uint_as_float(b0[1]), __uint_as_float(b1[1])}; }
; #pragma unroll
;             for (int t = 1; t < 16; ++t) { f32x2 a = u2[t]; float clast = 0.f;
; #pragma unroll
;                 for (int q = 0; q < 4; ++q) { const int smin = q < 2 ? 8 * q : 8 * (q - 2) + 1;
;                     if (smin < t) { const f32x4 cf = *(const LAS f32x4*)(MT + t * 36 + 4 * q);
; #pragma unroll
;                         for (int e = 0; e < 4; ++e) { const int sl = 4 * q + e, st_ = sl < 8 ? 2 * sl : 2 * (sl - 8) + 1; if (st_ == t - 1) clast = cf[e]; else if (st_ < t) a += u2[st_] * cf[e]; } } }
;                 a += u2[t - 1] * clast;
;                 u2[t] = a; }
	v_mfma_f32_32x32x16_bf16 v[80:95], v[96:99], v[100:103], v[80:95]
	v_cvt_pk_bf16_f32 v100, v56, v57
	v_cvt_pk_bf16_f32 v101, v58, v59
	v_cvt_pk_bf16_f32 v102, v60, v61
	v_cvt_pk_bf16_f32 v103, v62, v63
	s_nop 1
	s_nop 0
	v_mfma_f32_32x32x16_bf16 v[64:79], v[96:99], v[100:103], v[64:79]
	v_add_u32_e32 v112, 0x1000, v162
	ds_read2_b32 v[110:111], v112 offset0:164 offset1:200
	s_nop 7
	v_mov_b32_e32 v96, v80
	v_mov_b32_e32 v122, v80
	v_mov_b32_e32 v97, v64
	v_mov_b32_e32 v123, v64
	v_mov_b32_e32 v98, v81
	v_mov_b32_e32 v164, v81
	v_mov_b32_e32 v99, v65
	v_mov_b32_e32 v165, v65
	v_permlane32_swap_b32_e32 v96, v122
	v_permlane32_swap_b32_e32 v97, v123
	v_permlane32_swap_b32_e32 v98, v164
	v_permlane32_swap_b32_e32 v99, v165
	v_mov_b32_e32 v106, v82
	v_mov_b32_e32 v168, v82
	v_mov_b32_e32 v107, v66
	v_mov_b32_e32 v169, v66
	v_permlane32_swap_b32_e32 v106, v168
	s_nop 0
	v_permlane32_swap_b32_e32 v107, v169
	s_waitcnt lgkmcnt(0)
	v_pk_fma_f32 v[98:99], v[110:111], v[96:97], v[98:99] op_sel_hi:[0,1,1]
	v_mov_b32_e32 v110, v111
	v_pk_fma_f32 v[106:107], v[110:111], v[96:97], v[106:107] op_sel_hi:[0,1,1]
	ds_read_b32 v166, v162 offset:4928
	ds_read_b64 v[172:173], v162 offset:5040
	ds_read_b32 v174, v162 offset:5072
	ds_read2_b64 v[110:113], v112 offset0:136 offset1:140
	ds_read_b96 v[114:116], v162 offset:5328
	v_mov_b32_e32 v108, v83
	v_mov_b32_e32 v170, v83
	v_mov_b32_e32 v109, v67
	v_mov_b32_e32 v171, v67
	v_permlane32_swap_b32_e32 v108, v170
	s_nop 0
	v_permlane32_swap_b32_e32 v109, v171
	s_waitcnt lgkmcnt(4)
	v_pk_fma_f32 v[106:107], v[98:99], v[166:167], v[106:107] op_sel_hi:[1,0,1]
	s_waitcnt lgkmcnt(3)
	v_pk_fma_f32 v[108:109], v[172:173], v[96:97], v[108:109] op_sel_hi:[0,1,1]
	s_waitcnt lgkmcnt(1)
	v_pk_fma_f32 v[122:123], v[110:111], v[96:97], v[122:123] op_sel_hi:[0,1,1]
	v_pk_fma_f32 v[108:109], v[98:99], v[174:175], v[108:109] op_sel_hi:[1,0,1]
	v_pk_fma_f32 v[110:111], v[106:107], v[110:111], v[122:123] op_sel:[0,1,0]
	ds_read_b64 v[122:123], v162 offset:5360
	v_pk_fma_f32 v[108:109], v[172:173], v[106:107], v[108:109] op_sel:[1,0,0]
	v_pk_fma_f32 v[110:111], v[98:99], v[112:113], v[110:111] op_sel_hi:[1,0,1]
	ds_read_b96 v[172:174], v162 offset:5648
	v_pk_fma_f32 v[110:111], v[112:113], v[108:109], v[110:111] op_sel:[1,0,0]
	s_waitcnt lgkmcnt(2)
	v_pk_fma_f32 v[112:113], v[114:115], v[96:97], v[164:165] op_sel_hi:[0,1,1]
	ds_read_b96 v[164:166], v162 offset:5472
	v_pk_fma_f32 v[112:113], v[106:107], v[114:115], v[112:113] op_sel:[0,1,0]
	v_mov_b32_e32 v114, v116
	s_waitcnt lgkmcnt(2)
	v_pk_fma_f32 v[112:113], v[98:99], v[122:123], v[112:113] op_sel_hi:[1,0,1]
	v_mov_b32_e32 v176, v84
	v_pk_fma_f32 v[112:113], v[108:109], v[122:123], v[112:113] op_sel:[0,1,0]
	s_waitcnt lgkmcnt(0)
	v_pk_fma_f32 v[122:123], v[164:165], v[96:97], v[168:169] op_sel_hi:[0,1,1]
	v_pk_fma_f32 v[112:113], v[114:115], v[110:111], v[112:113] op_sel_hi:[0,1,1]
	ds_read_b96 v[114:116], v162 offset:5504
	v_pk_fma_f32 v[122:123], v[106:107], v[164:165], v[122:123] op_sel:[0,1,0]
	v_mov_b32_e32 v164, v166
	v_pk_fma_f32 v[122:123], v[164:165], v[110:111], v[122:123] op_sel_hi:[0,1,1]
	ds_read_b128 v[164:167], v162 offset:5616
	s_waitcnt lgkmcnt(1)
	v_pk_fma_f32 v[122:123], v[98:99], v[114:115], v[122:123] op_sel_hi:[1,0,1]
	v_mov_b32_e32 v120, v84
	v_pk_fma_f32 v[114:115], v[108:109], v[114:115], v[122:123] op_sel:[0,1,0]
	v_mov_b32_e32 v177, v68
	v_pk_fma_f32 v[114:115], v[116:117], v[112:113], v[114:115] op_sel_hi:[0,1,1]
	s_waitcnt lgkmcnt(0)
	v_pk_fma_f32 v[116:117], v[164:165], v[96:97], v[170:171] op_sel_hi:[0,1,1]
	v_pk_fma_f32 v[116:117], v[106:107], v[164:165], v[116:117] op_sel:[0,1,0]
	ds_read_b128 v[168:171], v162 offset:5760
	v_pk_fma_f32 v[116:117], v[110:111], v[166:167], v[116:117] op_sel_hi:[1,0,1]
	v_mov_b32_e32 v121, v68
	v_pk_fma_f32 v[116:117], v[98:99], v[172:173], v[116:117] op_sel_hi:[1,0,1]
	v_mov_b32_e32 v122, v174
	v_pk_fma_f32 v[116:117], v[108:109], v[172:173], v[116:117] op_sel:[0,1,0]
	v_permlane32_swap_b32_e32 v176, v120
	v_permlane32_swap_b32_e32 v177, v121
	v_pk_fma_f32 v[116:117], v[122:123], v[112:113], v[116:117] op_sel_hi:[0,1,1]
	v_mov_b32_e32 v122, v167
	v_pk_fma_f32 v[116:117], v[122:123], v[114:115], v[116:117] op_sel_hi:[0,1,1]
	s_waitcnt lgkmcnt(0)
	v_pk_fma_f32 v[122:123], v[168:169], v[96:97], v[176:177] op_sel_hi:[0,1,1]
	ds_read_b128 v[164:167], v162 offset:5792
	v_pk_fma_f32 v[122:123], v[106:107], v[168:169], v[122:123] op_sel:[0,1,0]
	v_mov_b32_e32 v168, v171
	v_pk_fma_f32 v[122:123], v[110:111], v[170:171], v[122:123] op_sel_hi:[1,0,1]
	v_mov_b32_e32 v178, v85
	v_pk_fma_f32 v[122:123], v[168:169], v[114:115], v[122:123] op_sel_hi:[0,1,1]
	ds_read_b128 v[168:171], v162 offset:5904
	s_waitcnt lgkmcnt(1)
	v_pk_fma_f32 v[122:123], v[98:99], v[164:165], v[122:123] op_sel_hi:[1,0,1]
	v_mov_b32_e32 v118, v85
	v_mov_b32_e32 v179, v69
	v_mov_b32_e32 v119, v69
	v_pk_fma_f32 v[122:123], v[108:109], v[164:165], v[122:123] op_sel:[0,1,0]
	v_permlane32_swap_b32_e32 v178, v118
	v_permlane32_swap_b32_e32 v179, v119
	v_pk_fma_f32 v[122:123], v[112:113], v[166:167], v[122:123] op_sel_hi:[1,0,1]
	v_mov_b32_e32 v164, v167
	v_pk_fma_f32 v[122:123], v[164:165], v[116:117], v[122:123] op_sel_hi:[0,1,1]
	s_waitcnt lgkmcnt(0)
	v_pk_fma_f32 v[164:165], v[168:169], v[96:97], v[178:179] op_sel_hi:[0,1,1]
	v_pk_fma_f32 v[164:165], v[106:107], v[168:169], v[164:165] op_sel:[0,1,0]
	v_mov_b32_e32 v180, v86
	v_pk_fma_f32 v[168:169], v[110:111], v[170:171], v[164:165] op_sel_hi:[1,0,1]
	ds_read_b128 v[164:167], v162 offset:5936
	v_mov_b32_e32 v170, v171
	v_pk_fma_f32 v[172:173], v[170:171], v[114:115], v[168:169] op_sel_hi:[0,1,1]
	v_add_u32_e32 v168, 0x1400, v162
	ds_read2_b32 v[174:175], v168 offset0:200 offset1:236
	ds_read_b128 v[168:171], v162 offset:6048
	s_waitcnt lgkmcnt(2)
; #define LAS __attribute__((address_space(3)))
; template <int role> __device__ __forceinline__ void ph_scan1m_r(Ctx& C) {
;     ...
;             for (int t = 1; t < 16; ++t) { f32x2 a = u2[t]; float clast = 0.f;
; #pragma unroll
;                 for (int q = 0; q < 4; ++q) { const int smin = q < 2 ? 8 * q : 8 * (q - 2) + 1;
;                     if (smin < t) { const f32x4 cf = *(const LAS f32x4*)(MT + t * 36 + 4 * q);
; #pragma unroll
;                         for (int e = 0; e < 4; ++e) { const int sl = 4 * q + e, st_ = sl < 8 ? 2 * sl : 2 * (sl - 8) + 1; if (st_ == t - 1) clast = cf[e]; else if (st_ < t) a += u2[st_] * cf[e]; } } }
;                 a += u2[t - 1] * clast;
;                 u2[t] = a; }
	v_pk_fma_f32 v[172:173], v[98:99], v[164:165], v[172:173] op_sel_hi:[1,0,1]
	v_mov_b32_e32 v102, v86
	v_pk_fma_f32 v[164:165], v[108:109], v[164:165], v[172:173] op_sel:[0,1,0]
	v_mov_b32_e32 v181, v70
	v_mov_b32_e32 v103, v70
	v_pk_fma_f32 v[164:165], v[112:113], v[166:167], v[164:165] op_sel_hi:[1,0,1]
	v_mov_b32_e32 v166, v167
	v_permlane32_swap_b32_e32 v180, v102
	v_permlane32_swap_b32_e32 v181, v103
	v_pk_fma_f32 v[164:165], v[166:167], v[116:117], v[164:165] op_sel_hi:[0,1,1]
	s_waitcnt lgkmcnt(1)
	v_pk_fma_f32 v[176:177], v[174:175], v[122:123], v[164:165] op_sel_hi:[0,1,1]
	s_waitcnt lgkmcnt(0)
	v_pk_fma_f32 v[164:165], v[168:169], v[96:97], v[180:181] op_sel_hi:[0,1,1]
	v_pk_fma_f32 v[164:165], v[106:107], v[168:169], v[164:165] op_sel:[0,1,0]
	ds_read_b32 v172, v162 offset:6096
	v_pk_fma_f32 v[168:169], v[110:111], v[170:171], v[164:165] op_sel_hi:[1,0,1]
	ds_read_b128 v[164:167], v162 offset:6080
	v_mov_b32_e32 v170, v171
	v_pk_fma_f32 v[168:169], v[114:115], v[170:171], v[168:169] op_sel_hi:[1,0,1]
	v_mov_b32_e32 v170, v175
	v_pk_fma_f32 v[168:169], v[170:171], v[122:123], v[168:169] op_sel_hi:[0,1,1]
	s_waitcnt lgkmcnt(0)
	v_pk_fma_f32 v[168:169], v[98:99], v[164:165], v[168:169] op_sel_hi:[1,0,1]
	v_mov_b32_e32 v182, v87
	v_pk_fma_f32 v[164:165], v[108:109], v[164:165], v[168:169] op_sel:[0,1,0]
	ds_read_b128 v[168:171], v162 offset:6192
	v_mov_b32_e32 v100, v87
	v_mov_b32_e32 v183, v71
	v_mov_b32_e32 v101, v71
	v_pk_fma_f32 v[164:165], v[112:113], v[166:167], v[164:165] op_sel_hi:[1,0,1]
	v_mov_b32_e32 v166, v167
	v_permlane32_swap_b32_e32 v182, v100
	v_permlane32_swap_b32_e32 v183, v101
	v_pk_fma_f32 v[164:165], v[116:117], v[166:167], v[164:165] op_sel_hi:[1,0,1]
	s_nop 0
	v_pk_fma_f32 v[178:179], v[172:173], v[176:177], v[164:165] op_sel_hi:[0,1,1]
	ds_read_b64 v[172:173], v162 offset:6208
	s_waitcnt lgkmcnt(1)
	v_pk_fma_f32 v[164:165], v[168:169], v[96:97], v[182:183] op_sel_hi:[0,1,1]
	v_pk_fma_f32 v[164:165], v[106:107], v[168:169], v[164:165] op_sel:[0,1,0]
	s_nop 0
	v_pk_fma_f32 v[168:169], v[110:111], v[170:171], v[164:165] op_sel_hi:[1,0,1]
	ds_read_b128 v[164:167], v162 offset:6224
	v_mov_b32_e32 v170, v171
	v_pk_fma_f32 v[168:169], v[114:115], v[170:171], v[168:169] op_sel_hi:[1,0,1]
	ds_read_b32 v170, v162 offset:6240
	s_waitcnt lgkmcnt(2)
	v_pk_fma_f32 v[168:169], v[122:123], v[172:173], v[168:169] op_sel_hi:[1,0,1]
	s_waitcnt lgkmcnt(1)
	v_mov_b32_e32 v174, v167
	v_pk_fma_f32 v[168:169], v[98:99], v[164:165], v[168:169] op_sel_hi:[1,0,1]
	s_nop 0
	v_pk_fma_f32 v[164:165], v[108:109], v[164:165], v[168:169] op_sel:[0,1,0]
	s_nop 0
	v_pk_fma_f32 v[168:169], v[112:113], v[166:167], v[164:165] op_sel_hi:[1,0,1]
	ds_read_b128 v[164:167], v162 offset:6336
	v_pk_fma_f32 v[168:169], v[116:117], v[174:175], v[168:169] op_sel_hi:[1,0,1]
	s_waitcnt lgkmcnt(1)
	v_pk_fma_f32 v[168:169], v[170:171], v[176:177], v[168:169] op_sel_hi:[0,1,1]
	v_pk_fma_f32 v[180:181], v[172:173], v[178:179], v[168:169] op_sel:[1,0,0]
	v_add_u32_e32 v172, 0x1800, v162
	ds_read2_b64 v[172:175], v172 offset0:26 offset1:30
	ds_read_b128 v[168:171], v162 offset:6368
	s_waitcnt lgkmcnt(2)
	v_pk_fma_f32 v[120:121], v[164:165], v[96:97], v[120:121] op_sel_hi:[0,1,1]
	v_pk_fma_f32 v[120:121], v[106:107], v[164:165], v[120:121] op_sel:[0,1,0]
	v_mov_b32_e32 v164, v167
	v_pk_fma_f32 v[120:121], v[110:111], v[166:167], v[120:121] op_sel_hi:[1,0,1]
	s_nop 0
	v_pk_fma_f32 v[120:121], v[114:115], v[164:165], v[120:121] op_sel_hi:[1,0,1]
	ds_read_b128 v[164:167], v162 offset:6480
	s_waitcnt lgkmcnt(2)
	v_pk_fma_f32 v[120:121], v[122:123], v[172:173], v[120:121] op_sel_hi:[1,0,1]
	s_nop 0
	v_pk_fma_f32 v[120:121], v[172:173], v[178:179], v[120:121] op_sel:[1,0,0]
	s_waitcnt lgkmcnt(1)
	v_pk_fma_f32 v[120:121], v[98:99], v[168:169], v[120:121] op_sel_hi:[1,0,1]
	s_nop 0
	v_pk_fma_f32 v[120:121], v[108:109], v[168:169], v[120:121] op_sel:[0,1,0]
	v_mov_b32_e32 v168, v171
	v_pk_fma_f32 v[120:121], v[112:113], v[170:171], v[120:121] op_sel_hi:[1,0,1]
	s_nop 0
	v_pk_fma_f32 v[120:121], v[116:117], v[168:169], v[120:121] op_sel_hi:[1,0,1]
	ds_read_b96 v[168:170], v162 offset:6496
	s_waitcnt lgkmcnt(1)
	v_pk_fma_f32 v[118:119], v[164:165], v[96:97], v[118:119] op_sel_hi:[0,1,1]
	v_pk_fma_f32 v[120:121], v[176:177], v[174:175], v[120:121] op_sel_hi:[1,0,1]
	v_pk_fma_f32 v[118:119], v[106:107], v[164:165], v[118:119] op_sel:[0,1,0]
	v_pk_fma_f32 v[172:173], v[174:175], v[180:181], v[120:121] op_sel:[1,0,0]
	v_pk_fma_f32 v[164:165], v[110:111], v[166:167], v[118:119] op_sel_hi:[1,0,1]
	ds_read_b128 v[118:121], v162 offset:6512
	v_mov_b32_e32 v166, v167
	v_pk_fma_f32 v[164:165], v[114:115], v[166:167], v[164:165] op_sel_hi:[1,0,1]
	ds_read_b64 v[166:167], v162 offset:6528
	s_waitcnt lgkmcnt(2)
	v_pk_fma_f32 v[164:165], v[122:123], v[168:169], v[164:165] op_sel_hi:[1,0,1]
	s_nop 0
	v_pk_fma_f32 v[164:165], v[178:179], v[168:169], v[164:165] op_sel:[0,1,0]
	s_waitcnt lgkmcnt(1)
	v_pk_fma_f32 v[164:165], v[98:99], v[118:119], v[164:165] op_sel_hi:[1,0,1]
	s_nop 0
	v_pk_fma_f32 v[118:119], v[108:109], v[118:119], v[164:165] op_sel:[0,1,0]
	s_nop 0
	v_pk_fma_f32 v[118:119], v[112:113], v[120:121], v[118:119] op_sel_hi:[1,0,1]
	v_mov_b32_e32 v120, v121
	v_pk_fma_f32 v[118:119], v[116:117], v[120:121], v[118:119] op_sel_hi:[1,0,1]
	s_waitcnt lgkmcnt(0)
	v_pk_fma_f32 v[164:165], v[176:177], v[166:167], v[118:119] op_sel_hi:[1,0,1]
	ds_read_b128 v[118:121], v162 offset:6624
	v_pk_fma_f32 v[164:165], v[166:167], v[180:181], v[164:165] op_sel:[1,0,0]
	v_mov_b32_e32 v166, v170
	v_pk_fma_f32 v[168:169], v[166:167], v[172:173], v[164:165] op_sel_hi:[0,1,1]
	ds_read_b96 v[164:166], v162 offset:6640
	s_waitcnt lgkmcnt(1)
; #define LAS __attribute__((address_space(3)))
; template <int role> __device__ __forceinline__ void ph_scan1m_r(Ctx& C) {
;     ...
;             for (int t = 1; t < 16; ++t) { f32x2 a = u2[t]; float clast = 0.f;
; #pragma unroll
;                 for (int q = 0; q < 4; ++q) { const int smin = q < 2 ? 8 * q : 8 * (q - 2) + 1;
;                     if (smin < t) { const f32x4 cf = *(const LAS f32x4*)(MT + t * 36 + 4 * q);
; #pragma unroll
;                         for (int e = 0; e < 4; ++e) { const int sl = 4 * q + e, st_ = sl < 8 ? 2 * sl : 2 * (sl - 8) + 1; if (st_ == t - 1) clast = cf[e]; else if (st_ < t) a += u2[st_] * cf[e]; } } }
;                 a += u2[t - 1] * clast;
;                 u2[t] = a; }
;             bf16x8 ufr[2];
;             ufr[0] = pack8s(hh ? u2[1].x : u2[0].x, hh ? u2[3].x : u2[2].x, hh ? u2[5].x : u2[4].x, hh ? u2[7].x : u2[6].x, hh ? u2[9].x : u2[8].x, hh ? u2[11].x : u2[10].x, hh ? u2[13].x : u2[12].x, hh ? u2[15].x : u2[14].x);
;             ufr[1] = pack8s(hh ? u2[1].y : u2[0].y, hh ? u2[3].y : u2[2].y, hh ? u2[5].y : u2[4].y, hh ? u2[7].y : u2[6].y, hh ? u2[9].y : u2[8].y, hh ? u2[11].y : u2[10].y, hh ? u2[13].y : u2[12].y, hh ? u2[15].y : u2[14].y);
;             __builtin_amdgcn_sched_barrier(0);
;             { const f32x4 m0 = *(const LAS f32x4*)(MT + r31 * 36 + 8 * hh), m1 = *(const LAS f32x4*)(MT + r31 * 36 + 4 + 8 * hh); const bf16x8 af = pack8s(m0[0], m0[1], m0[2], m0[3], m1[0], m1[1], m1[2], m1[3]);
; #pragma unroll
;               for (int ct = 0; ct < 2; ++ct) ya[ct] = __builtin_amdgcn_mfma_f32_32x32x16_bf16(af, ufr[ct], ya[ct], 0, 0, 0); }
;             { LAS bf16* ys = (LAS bf16*)MT;
; #pragma unroll
;               for (int ct = 0; ct < 2; ++ct)
; #pragma unroll
;                   for (int e = 0; e < 8; e += 2) { const unsigned pw = pg8::cvt_pk_bf16(ya[ct][8 + e], ya[ct][9 + e]); const int t = (e & 3) + 4 * hh + 8 * (e >> 2); LAS bf16* d = ys + t * 72 + 32 * ct + r31; d[0] = (bf16)pw; d[72] = (bf16)(pw >> 16); }
;               asm volatile("s_waitcnt lgkmcnt(0)" ::: "memory");
; #pragma unroll
;               for (int i = 0; i < 2; ++i) { const int t = (lane >> 3) + 8 * i; const u32x4 w = *(const LAS u32x4*)(ys + t * 72 + 8 * (lane & 7)); *(u32x4*)(g_out + zoff + rowu + (long)t * dix + 8 * (lane & 7)) = w; }
;               asm volatile("s_waitcnt lgkmcnt(0)" ::: "memory"); }
	v_pk_fma_f32 v[102:103], v[118:119], v[96:97], v[102:103] op_sel_hi:[0,1,1]
	v_pk_fma_f32 v[102:103], v[106:107], v[118:119], v[102:103] op_sel:[0,1,0]
	v_mov_b32_e32 v118, v121
	v_pk_fma_f32 v[102:103], v[110:111], v[120:121], v[102:103] op_sel_hi:[1,0,1]
	s_nop 0
	v_pk_fma_f32 v[102:103], v[114:115], v[118:119], v[102:103] op_sel_hi:[1,0,1]
	ds_read_b128 v[118:121], v162 offset:6656
	s_waitcnt lgkmcnt(1)
	v_pk_fma_f32 v[102:103], v[122:123], v[164:165], v[102:103] op_sel_hi:[1,0,1]
	s_nop 0
	v_pk_fma_f32 v[102:103], v[178:179], v[164:165], v[102:103] op_sel:[0,1,0]
	v_mov_b32_e32 v164, v166
	v_pk_fma_f32 v[102:103], v[164:165], v[172:173], v[102:103] op_sel_hi:[0,1,1]
	ds_read_b96 v[164:166], v162 offset:6672
	s_waitcnt lgkmcnt(1)
	v_pk_fma_f32 v[102:103], v[98:99], v[118:119], v[102:103] op_sel_hi:[1,0,1]
	s_nop 0
	v_pk_fma_f32 v[102:103], v[108:109], v[118:119], v[102:103] op_sel:[0,1,0]
	v_mov_b32_e32 v118, v121
	v_pk_fma_f32 v[102:103], v[112:113], v[120:121], v[102:103] op_sel_hi:[1,0,1]
	s_nop 0
	v_pk_fma_f32 v[102:103], v[116:117], v[118:119], v[102:103] op_sel_hi:[1,0,1]
	ds_read_b128 v[118:121], v162 offset:6768
	s_waitcnt lgkmcnt(1)
	v_pk_fma_f32 v[102:103], v[176:177], v[164:165], v[102:103] op_sel_hi:[1,0,1]
	s_nop 0
	v_pk_fma_f32 v[102:103], v[180:181], v[164:165], v[102:103] op_sel:[0,1,0]
	v_mov_b32_e32 v164, v166
	v_pk_fma_f32 v[170:171], v[164:165], v[168:169], v[102:103] op_sel_hi:[0,1,1]
	ds_read_b128 v[164:167], v162 offset:6784
	s_waitcnt lgkmcnt(1)
	v_pk_fma_f32 v[100:101], v[118:119], v[96:97], v[100:101] op_sel_hi:[0,1,1]
	v_pk_fma_f32 v[100:101], v[106:107], v[118:119], v[100:101] op_sel:[0,1,0]
	v_mov_b32_e32 v102, v121
	v_pk_fma_f32 v[100:101], v[110:111], v[120:121], v[100:101] op_sel_hi:[1,0,1]
	v_cndmask_b32_e32 v96, v98, v96, vcc
	v_pk_fma_f32 v[118:119], v[114:115], v[102:103], v[100:101] op_sel_hi:[1,0,1]
	ds_read_b128 v[100:103], v162 offset:6800
	s_waitcnt lgkmcnt(1)
	v_pk_fma_f32 v[118:119], v[122:123], v[164:165], v[118:119] op_sel_hi:[1,0,1]
	v_cndmask_b32_e32 v107, v109, v107, vcc
	v_pk_fma_f32 v[118:119], v[178:179], v[164:165], v[118:119] op_sel:[0,1,0]
	s_nop 0
	v_pk_fma_f32 v[164:165], v[166:167], v[172:173], v[118:119] op_sel_hi:[0,1,1]
	ds_read_b96 v[118:120], v162 offset:6816
	s_waitcnt lgkmcnt(1)
	v_pk_fma_f32 v[164:165], v[98:99], v[100:101], v[164:165] op_sel_hi:[1,0,1]
	v_cndmask_b32_e32 v98, v108, v106, vcc
	v_pk_fma_f32 v[100:101], v[108:109], v[100:101], v[164:165] op_sel:[0,1,0]
	v_cndmask_b32_e32 v106, v112, v110, vcc
	v_pk_fma_f32 v[100:101], v[112:113], v[102:103], v[100:101] op_sel_hi:[1,0,1]
	v_mov_b32_e32 v102, v103
	v_pk_fma_f32 v[100:101], v[116:117], v[102:103], v[100:101] op_sel_hi:[1,0,1]
	s_waitcnt lgkmcnt(0)
	v_mov_b32_e32 v102, v120
	v_pk_fma_f32 v[100:101], v[176:177], v[118:119], v[100:101] op_sel_hi:[1,0,1]
	v_cndmask_b32_e32 v108, v116, v114, vcc
	v_pk_fma_f32 v[100:101], v[180:181], v[118:119], v[100:101] op_sel:[0,1,0]
	v_cndmask_b32_e32 v110, v176, v122, vcc
	v_pk_fma_f32 v[100:101], v[102:103], v[168:169], v[100:101] op_sel_hi:[0,1,1]
	v_mov_b32_e32 v102, v167
	v_pk_fma_f32 v[118:119], v[102:103], v[170:171], v[100:101] op_sel_hi:[0,1,1]
	v_cndmask_b32_e32 v112, v180, v178, vcc
	v_cndmask_b32_e32 v114, v168, v172, vcc
	v_cndmask_b32_e32 v116, v118, v170, vcc
	v_cvt_pk_bf16_f32 v100, v96, v98
	v_cvt_pk_bf16_f32 v101, v106, v108
	v_cvt_pk_bf16_f32 v102, v110, v112
	v_cvt_pk_bf16_f32 v103, v114, v116
	s_nop 1
	v_cndmask_b32_e32 v106, v99, v97, vcc
	v_cndmask_b32_e32 v108, v113, v111, vcc
	v_cndmask_b32_e32 v109, v117, v115, vcc
	v_cndmask_b32_e32 v110, v177, v123, vcc
	v_cndmask_b32_e32 v111, v181, v179, vcc
	v_cndmask_b32_e32 v112, v169, v173, vcc
	v_cndmask_b32_e32 v113, v119, v171, vcc
	v_cvt_pk_bf16_f32 v96, v106, v107
	v_cvt_pk_bf16_f32 v97, v108, v109
	v_cvt_pk_bf16_f32 v98, v110, v111
	v_cvt_pk_bf16_f32 v99, v112, v113
	s_nop 1
	v_mad_u64_u32 v[110:111], s[0:1], v160, 24, v[104:105]
	ds_read_b128 v[106:109], v110 offset:4608
	ds_read_b128 v[110:113], v110 offset:4624
	s_lshl_b64 s[0:1], s[36:37], 11
	s_add_u32 s0, s63, s0
	s_addc_u32 s1, s64, s1
	s_waitcnt lgkmcnt(0)
	v_cvt_pk_bf16_f32 v114, v106, v107
	v_cvt_pk_bf16_f32 v115, v108, v109
	v_cvt_pk_bf16_f32 v116, v110, v111
	v_cvt_pk_bf16_f32 v117, v112, v113
	s_nop 1
	s_nop 0
	v_mfma_f32_32x32x16_bf16 v[80:95], v[114:117], v[100:103], v[80:95]
	v_mfma_f32_32x32x16_bf16 v[64:79], v[114:117], v[96:99], v[64:79]
	s_nop 10
	v_mul_i32_i24_e32 v80, 0xffffff72, v158
	v_mul_lo_u32 v81, v160, s56
	v_add3_u32 v80, v163, v80, v81
	v_cvt_pk_bf16_f32 v64, v88, v89
	ds_write_b16 v80, v64 offset:4608
	ds_write_b16_d16_hi v80, v64 offset:4752
	v_cvt_pk_bf16_f32 v64, v90, v91
	ds_write_b16 v80, v64 offset:4896
	ds_write_b16_d16_hi v80, v64 offset:5040
	v_cvt_pk_bf16_f32 v64, v92, v93
	ds_write_b16 v80, v64 offset:5760
	ds_write_b16_d16_hi v80, v64 offset:5904
	v_cvt_pk_bf16_f32 v64, v94, v95
	ds_write_b16 v80, v64 offset:6048
	ds_write_b16_d16_hi v80, v64 offset:6192
	v_cvt_pk_bf16_f32 v64, v72, v73
	ds_write_b16 v80, v64 offset:4672
	ds_write_b16_d16_hi v80, v64 offset:4816
	v_cvt_pk_bf16_f32 v64, v74, v75
	ds_write_b16 v80, v64 offset:4960
	ds_write_b16_d16_hi v80, v64 offset:5104
	v_cvt_pk_bf16_f32 v64, v76, v77
	ds_write_b16 v80, v64 offset:5824
	ds_write_b16_d16_hi v80, v64 offset:5968
	v_cvt_pk_bf16_f32 v64, v78, v79
	ds_write_b16 v80, v64 offset:6112
	ds_write_b16_d16_hi v80, v64 offset:6256
	v_ashrrev_i32_e32 v76, 3, v159
	v_lshlrev_b32_e32 v64, 4, v159
	v_and_b32_e32 v104, 0x70, v64
	v_mul_lo_u32 v64, v76, s54
	s_waitcnt lgkmcnt(0)
	v_add3_u32 v70, s42, v104, v64
	ds_read_b128 v[64:67], v70 offset:4608
	v_ashrrev_i32_e32 v68, 31, v76
	v_lshl_add_u64 v[72:73], s[0:1], 0, v[104:105]
	v_mul_lo_u32 v71, s30, v68
	v_mul_lo_u32 v74, s31, v76
	v_mad_u64_u32 v[68:69], s[0:1], s30, v76, 0
	v_add3_u32 v69, v69, v71, v74
	v_lshl_add_u64 v[74:75], v[68:69], 1, v[72:73]
	ds_read_b128 v[68:71], v70 offset:5760
	s_waitcnt lgkmcnt(1)
	global_store_dwordx4 v[74:75], v[64:67], off
	s_nop 1
	v_add_u32_e32 v64, 8, v76
	v_ashrrev_i32_e32 v65, 31, v64
	v_mul_lo_u32 v66, s30, v65
	v_mul_lo_u32 v67, s31, v64
	v_mad_u64_u32 v[64:65], s[0:1], s30, v64, 0
	v_add3_u32 v65, v65, v66, v67
	v_lshl_add_u64 v[64:65], v[64:65], 1, v[72:73]
	s_waitcnt lgkmcnt(0)
	global_store_dwordx4 v[64:65], v[68:71], off
	s_waitcnt lgkmcnt(0)
	s_branch .LBB0_719

.LBB0_1103:
	s_lshl_b32 s0, s11, 8
	v_mov_b32_e32 v44, v161
	v_mov_b32_e32 v45, v160
	s_or_b32 s0, s0, s73
	s_nop 0
	v_lshl_add_u32 v158, v45, 3, s0
	v_ashrrev_i32_e32 v159, 31, v158
	s_waitcnt lgkmcnt(0)
	v_lshl_add_u64 v[52:53], v[158:159], 2, s[16:17]
	global_load_dwordx4 v[68:71], v[52:53], off
	global_load_dwordx4 v[60:63], v[52:53], off offset:16
	s_lshl_b32 s0, s10, 8
	s_add_i32 s0, s0, s71
	v_add_u32_e32 v44, s0, v44
	v_ashrrev_i32_e32 v45, 31, v44
	v_lshlrev_b64 v[166:167], 13, v[44:45]
	global_load_dwordx4 v[44:47], v[52:53], off offset:144
	s_nop 0
	global_load_dwordx4 v[52:55], v[52:53], off offset:128
	v_lshl_add_u64 v[166:167], s[24:25], 0, v[166:167]
	v_lshl_add_u64 v[158:159], v[158:159], 1, v[166:167]
	s_waitcnt vmcnt(0)
	v_add_f32_e32 v140, v140, v68
	v_add_f32_e32 v141, v141, v69
	v_mul_f32_e32 v140, 0xbfb8aa3b, v140
	v_add_f32_e32 v142, v142, v70
	v_mul_f32_e32 v141, 0xbfb8aa3b, v141
	v_exp_f32_e32 v140, v140
	v_add_f32_e32 v143, v143, v71
	v_mul_f32_e32 v142, 0xbfb8aa3b, v142
	v_exp_f32_e32 v141, v141
	v_mul_f32_e32 v143, 0xbfb8aa3b, v143
	v_exp_f32_e32 v142, v142
	v_add_f32_e32 v136, v136, v60
	v_exp_f32_e32 v143, v143
	v_mul_f32_e32 v136, 0xbfb8aa3b, v136
	v_add_f32_e32 v140, 1.0, v140
	v_exp_f32_e32 v136, v136
	v_add_f32_e32 v141, 1.0, v141
	v_add_f32_e32 v142, 1.0, v142
	v_add_f32_e32 v143, 1.0, v143
	v_add_f32_e32 v136, 1.0, v136
	v_add_f32_e32 v137, v137, v61
	v_mul_f32_e32 v137, 0xbfb8aa3b, v137
	v_exp_f32_e32 v137, v137
	s_nop 0
	v_add_f32_e32 v137, 1.0, v137
	v_rcp_f32_e32 v140, v140
	v_rcp_f32_e32 v141, v141
	v_rcp_f32_e32 v142, v142
	v_rcp_f32_e32 v143, v143
	v_add_f32_e32 v138, v138, v62
	v_mul_f32_e32 v138, 0xbfb8aa3b, v138
	v_rcp_f32_e32 v166, v136
	v_exp_f32_e32 v138, v138
	s_nop 0
	v_add_f32_e32 v138, 1.0, v138
	v_add_f32_e32 v139, v139, v63
	v_mul_f32_e32 v139, 0xbfb8aa3b, v139
	v_rcp_f32_e32 v168, v137
	v_exp_f32_e32 v139, v139
	s_nop 0
	v_add_f32_e32 v139, 1.0, v139
	v_rcp_f32_e32 v170, v138
	v_add_f32_e32 v132, v132, v52
	v_mul_f32_e32 v132, 0xbfb8aa3b, v132
	v_exp_f32_e32 v132, v132
	s_nop 0
	v_add_f32_e32 v132, 1.0, v132
	v_rcp_f32_e32 v139, v139
	v_cvt_pk_bf16_f32 v136, v140, v141
	v_add_f32_e32 v133, v133, v53
	v_mul_f32_e32 v133, 0xbfb8aa3b, v133
	v_exp_f32_e32 v133, v133
	v_cvt_pk_bf16_f32 v137, v142, v143
	v_cvt_pk_bf16_f32 v138, v166, v168
	v_cvt_pk_bf16_f32 v139, v170, v139
	global_store_dwordx4 v[158:159], v[136:139], off
	v_add_f32_e32 v133, 1.0, v133
	v_add_f32_e32 v134, v134, v54
	v_mul_f32_e32 v134, 0xbfb8aa3b, v134
	v_rcp_f32_e32 v132, v132
	v_exp_f32_e32 v134, v134
	s_nop 0
	v_add_f32_e32 v134, 1.0, v134
	v_add_f32_e32 v135, v135, v55
	v_mul_f32_e32 v135, 0xbfb8aa3b, v135
	v_rcp_f32_e32 v133, v133
	v_exp_f32_e32 v135, v135
	s_nop 0
	v_add_f32_e32 v135, 1.0, v135
	v_add_f32_e32 v128, v128, v44
	v_mul_f32_e32 v128, 0xbfb8aa3b, v128
	v_rcp_f32_e32 v134, v134
	v_exp_f32_e32 v128, v128
	s_nop 0
	v_add_f32_e32 v128, 1.0, v128
	v_add_f32_e32 v129, v129, v45
	v_mul_f32_e32 v129, 0xbfb8aa3b, v129
	v_rcp_f32_e32 v135, v135
	v_exp_f32_e32 v129, v129
	s_nop 0
	v_add_f32_e32 v129, 1.0, v129
	v_add_f32_e32 v130, v130, v46
	v_mul_f32_e32 v130, 0xbfb8aa3b, v130
	v_rcp_f32_e32 v136, v128
	v_exp_f32_e32 v130, v130
	s_nop 0
	v_add_f32_e32 v130, 1.0, v130
	v_add_f32_e32 v131, v131, v47
	v_mul_f32_e32 v131, 0xbfb8aa3b, v131
	v_rcp_f32_e32 v137, v129
	v_exp_f32_e32 v131, v131
	s_nop 0
	v_add_f32_e32 v131, 1.0, v131
	v_rcp_f32_e32 v140, v130
	v_add_f32_e32 v124, v124, v68
	v_mul_f32_e32 v124, 0xbfb8aa3b, v124
	v_exp_f32_e32 v124, v124
	s_nop 0
	v_add_f32_e32 v124, 1.0, v124
	v_rcp_f32_e32 v131, v131
	v_cvt_pk_bf16_f32 v128, v132, v133
	v_add_f32_e32 v125, v125, v69
	v_cvt_pk_bf16_f32 v129, v134, v135
	v_cvt_pk_bf16_f32 v130, v136, v137
	v_mul_f32_e32 v125, 0xbfb8aa3b, v125
	v_cvt_pk_bf16_f32 v131, v140, v131
	global_store_dwordx4 v[158:159], v[128:131], off offset:64
	v_exp_f32_e32 v125, v125
	v_add_f32_e32 v126, v126, v70
	v_add_f32_e32 v125, 1.0, v125
	v_mul_f32_e32 v126, 0xbfb8aa3b, v126
	v_rcp_f32_e32 v124, v124
	v_exp_f32_e32 v126, v126
	s_nop 0
	v_add_f32_e32 v126, 1.0, v126
	v_add_f32_e32 v127, v127, v71
	v_mul_f32_e32 v127, 0xbfb8aa3b, v127
	v_rcp_f32_e32 v125, v125
	v_exp_f32_e32 v127, v127
	s_nop 0
	v_add_f32_e32 v127, 1.0, v127
	v_add_f32_e32 v120, v120, v60
	v_mul_f32_e32 v120, 0xbfb8aa3b, v120
	v_rcp_f32_e32 v126, v126
	v_exp_f32_e32 v120, v120
	s_nop 0
	v_add_f32_e32 v120, 1.0, v120
	v_add_f32_e32 v121, v121, v61
	v_mul_f32_e32 v121, 0xbfb8aa3b, v121
	v_rcp_f32_e32 v127, v127
	v_exp_f32_e32 v121, v121
	s_nop 0
	v_add_f32_e32 v121, 1.0, v121
	v_add_f32_e32 v122, v122, v62
	v_mul_f32_e32 v122, 0xbfb8aa3b, v122
	v_rcp_f32_e32 v130, v120
	v_exp_f32_e32 v122, v122
	s_nop 0
	v_add_f32_e32 v122, 1.0, v122
	v_add_f32_e32 v123, v123, v63
	v_mul_f32_e32 v123, 0xbfb8aa3b, v123
	v_rcp_f32_e32 v131, v121
	v_exp_f32_e32 v123, v123
	s_nop 0
	v_add_f32_e32 v123, 1.0, v123
	v_rcp_f32_e32 v133, v122
	v_add_f32_e32 v116, v116, v52
	v_mul_f32_e32 v116, 0xbfb8aa3b, v116
	v_exp_f32_e32 v116, v116
	s_nop 0
	v_add_f32_e32 v116, 1.0, v116
	v_rcp_f32_e32 v123, v123
	v_cvt_pk_bf16_f32 v120, v124, v125
	v_cvt_pk_bf16_f32 v121, v126, v127
	v_add_f32_e32 v117, v117, v53
	v_add_co_u32_e32 v124, vcc, s79, v158
	v_mul_f32_e32 v117, 0xbfb8aa3b, v117
	s_nop 0
	v_addc_co_u32_e32 v125, vcc, 0, v159, vcc
	v_exp_f32_e32 v117, v117
	v_cvt_pk_bf16_f32 v122, v130, v131
	v_cvt_pk_bf16_f32 v123, v133, v123
	global_store_dwordx4 v[124:125], v[120:123], off
	v_add_f32_e32 v117, 1.0, v117
	v_add_f32_e32 v118, v118, v54
	v_mul_f32_e32 v118, 0xbfb8aa3b, v118
	v_rcp_f32_e32 v116, v116
	v_exp_f32_e32 v118, v118
	s_nop 0
	v_add_f32_e32 v118, 1.0, v118
	v_add_f32_e32 v119, v119, v55
	v_mul_f32_e32 v119, 0xbfb8aa3b, v119
	v_rcp_f32_e32 v117, v117
	v_exp_f32_e32 v119, v119
	s_nop 0
	v_add_f32_e32 v119, 1.0, v119
	v_add_f32_e32 v112, v112, v44
	v_mul_f32_e32 v112, 0xbfb8aa3b, v112
	v_rcp_f32_e32 v118, v118
	v_exp_f32_e32 v112, v112
	s_nop 0
	v_add_f32_e32 v112, 1.0, v112
	v_add_f32_e32 v113, v113, v45
	v_mul_f32_e32 v113, 0xbfb8aa3b, v113
	v_rcp_f32_e32 v119, v119
	v_exp_f32_e32 v113, v113
	s_nop 0
	v_add_f32_e32 v113, 1.0, v113
	v_add_f32_e32 v114, v114, v46
	v_mul_f32_e32 v114, 0xbfb8aa3b, v114
	v_rcp_f32_e32 v120, v112
	v_exp_f32_e32 v114, v114
	s_nop 0
	v_add_f32_e32 v114, 1.0, v114
	v_add_f32_e32 v115, v115, v47
	v_mul_f32_e32 v115, 0xbfb8aa3b, v115
	v_rcp_f32_e32 v121, v113
	v_exp_f32_e32 v115, v115
	s_nop 0
	v_add_f32_e32 v115, 1.0, v115
	v_rcp_f32_e32 v124, v114
	v_add_f32_e32 v108, v108, v68
	v_mul_f32_e32 v108, 0xbfb8aa3b, v108
	v_exp_f32_e32 v108, v108
	s_nop 0
	v_add_f32_e32 v108, 1.0, v108
	v_rcp_f32_e32 v115, v115
	v_cvt_pk_bf16_f32 v112, v116, v117
	v_add_f32_e32 v109, v109, v69
	v_lshl_add_u64 v[128:129], v[158:159], 0, s[34:35]
	v_cvt_pk_bf16_f32 v113, v118, v119
	v_cvt_pk_bf16_f32 v114, v120, v121
	v_mul_f32_e32 v109, 0xbfb8aa3b, v109
	v_cvt_pk_bf16_f32 v115, v124, v115
	global_store_dwordx4 v[128:129], v[112:115], off offset:64
	v_exp_f32_e32 v109, v109
	v_add_f32_e32 v110, v110, v70
	v_add_f32_e32 v109, 1.0, v109
	v_mul_f32_e32 v110, 0xbfb8aa3b, v110
	v_rcp_f32_e32 v108, v108
	v_exp_f32_e32 v110, v110
	s_nop 0
	v_add_f32_e32 v110, 1.0, v110
	v_add_f32_e32 v111, v111, v71
	v_mul_f32_e32 v111, 0xbfb8aa3b, v111
	v_rcp_f32_e32 v109, v109
	v_exp_f32_e32 v111, v111
	s_nop 0
	v_add_f32_e32 v111, 1.0, v111
	v_add_f32_e32 v104, v104, v60
	v_mul_f32_e32 v104, 0xbfb8aa3b, v104
	v_rcp_f32_e32 v110, v110
	v_exp_f32_e32 v104, v104
	s_nop 0
	v_add_f32_e32 v104, 1.0, v104
	v_add_f32_e32 v105, v105, v61
	v_mul_f32_e32 v105, 0xbfb8aa3b, v105
	v_rcp_f32_e32 v111, v111
	v_exp_f32_e32 v105, v105
	s_nop 0
	v_add_f32_e32 v105, 1.0, v105
	v_add_f32_e32 v106, v106, v62
	v_mul_f32_e32 v106, 0xbfb8aa3b, v106
	v_rcp_f32_e32 v114, v104
	v_exp_f32_e32 v106, v106
	s_nop 0
	v_add_f32_e32 v106, 1.0, v106
	v_add_f32_e32 v107, v107, v63
	v_mul_f32_e32 v107, 0xbfb8aa3b, v107
	v_rcp_f32_e32 v115, v105
	v_exp_f32_e32 v107, v107
	s_nop 0
	v_add_f32_e32 v107, 1.0, v107
	v_rcp_f32_e32 v117, v106
	v_add_f32_e32 v100, v100, v52
	v_mul_f32_e32 v100, 0xbfb8aa3b, v100
	v_exp_f32_e32 v100, v100
	s_nop 0
	v_add_f32_e32 v100, 1.0, v100
	v_rcp_f32_e32 v107, v107
	v_cvt_pk_bf16_f32 v104, v108, v109
	v_cvt_pk_bf16_f32 v105, v110, v111
	v_add_f32_e32 v101, v101, v53
	v_add_co_u32_e32 v108, vcc, s80, v158
	v_mul_f32_e32 v101, 0xbfb8aa3b, v101
	s_nop 0
	v_addc_co_u32_e32 v109, vcc, 0, v159, vcc
	v_exp_f32_e32 v101, v101
	v_cvt_pk_bf16_f32 v106, v114, v115
	v_cvt_pk_bf16_f32 v107, v117, v107
	global_store_dwordx4 v[108:109], v[104:107], off
	v_add_f32_e32 v101, 1.0, v101
	v_add_f32_e32 v102, v102, v54
	v_mul_f32_e32 v102, 0xbfb8aa3b, v102
	v_rcp_f32_e32 v100, v100
	v_exp_f32_e32 v102, v102
	s_nop 0
	v_add_f32_e32 v102, 1.0, v102
	v_add_f32_e32 v103, v103, v55
	v_mul_f32_e32 v103, 0xbfb8aa3b, v103
	v_rcp_f32_e32 v101, v101
	v_exp_f32_e32 v103, v103
	s_nop 0
	v_add_f32_e32 v103, 1.0, v103
	v_add_f32_e32 v96, v96, v44
	v_mul_f32_e32 v96, 0xbfb8aa3b, v96
	v_rcp_f32_e32 v102, v102
	v_exp_f32_e32 v96, v96
	s_nop 0
	v_add_f32_e32 v96, 1.0, v96
	v_add_f32_e32 v97, v97, v45
	v_mul_f32_e32 v97, 0xbfb8aa3b, v97
	v_rcp_f32_e32 v103, v103
	v_exp_f32_e32 v97, v97
	s_nop 0
	v_add_f32_e32 v97, 1.0, v97
	v_add_f32_e32 v98, v98, v46
	v_mul_f32_e32 v98, 0xbfb8aa3b, v98
	v_rcp_f32_e32 v104, v96
	v_exp_f32_e32 v98, v98
	s_nop 0
	v_add_f32_e32 v98, 1.0, v98
	v_add_f32_e32 v99, v99, v47
	v_mul_f32_e32 v99, 0xbfb8aa3b, v99
	v_rcp_f32_e32 v105, v97
	v_exp_f32_e32 v99, v99
	s_nop 0
	v_add_f32_e32 v99, 1.0, v99
	v_rcp_f32_e32 v108, v98
	v_add_f32_e32 v92, v92, v68
	v_mul_f32_e32 v92, 0xbfb8aa3b, v92
	v_exp_f32_e32 v92, v92
	s_nop 0
	v_add_f32_e32 v92, 1.0, v92
	v_rcp_f32_e32 v99, v99
	v_cvt_pk_bf16_f32 v96, v100, v101
	v_add_f32_e32 v93, v93, v69
	v_lshl_add_u64 v[112:113], v[158:159], 0, s[36:37]
	v_cvt_pk_bf16_f32 v97, v102, v103
	v_cvt_pk_bf16_f32 v98, v104, v105
	v_mul_f32_e32 v93, 0xbfb8aa3b, v93
	v_cvt_pk_bf16_f32 v99, v108, v99
	global_store_dwordx4 v[112:113], v[96:99], off offset:64
	v_exp_f32_e32 v93, v93
	v_add_f32_e32 v94, v94, v70
	v_add_f32_e32 v93, 1.0, v93
	v_mul_f32_e32 v94, 0xbfb8aa3b, v94
	v_rcp_f32_e32 v92, v92
	v_exp_f32_e32 v94, v94
	s_nop 0
	v_add_f32_e32 v94, 1.0, v94
	v_add_f32_e32 v95, v95, v71
	v_mul_f32_e32 v95, 0xbfb8aa3b, v95
	v_rcp_f32_e32 v93, v93
	v_exp_f32_e32 v95, v95
	s_nop 0
	v_add_f32_e32 v95, 1.0, v95
	v_add_f32_e32 v88, v88, v60
	v_mul_f32_e32 v88, 0xbfb8aa3b, v88
	v_rcp_f32_e32 v94, v94
	v_exp_f32_e32 v88, v88
	s_nop 0
	v_add_f32_e32 v88, 1.0, v88
	v_add_f32_e32 v89, v89, v61
	v_mul_f32_e32 v89, 0xbfb8aa3b, v89
	v_rcp_f32_e32 v95, v95
	v_exp_f32_e32 v89, v89
	s_nop 0
	v_add_f32_e32 v89, 1.0, v89
	v_add_f32_e32 v90, v90, v62
	v_mul_f32_e32 v90, 0xbfb8aa3b, v90
	v_rcp_f32_e32 v98, v88
	v_exp_f32_e32 v90, v90
	s_nop 0
	v_add_f32_e32 v90, 1.0, v90
	v_add_f32_e32 v91, v91, v63
	v_mul_f32_e32 v91, 0xbfb8aa3b, v91
	v_rcp_f32_e32 v99, v89
	v_exp_f32_e32 v91, v91
	s_nop 0
	v_add_f32_e32 v91, 1.0, v91
	v_rcp_f32_e32 v101, v90
	v_add_f32_e32 v84, v84, v52
	v_mul_f32_e32 v84, 0xbfb8aa3b, v84
	v_exp_f32_e32 v84, v84
	s_nop 0
	v_add_f32_e32 v84, 1.0, v84
	v_rcp_f32_e32 v91, v91
	v_cvt_pk_bf16_f32 v88, v92, v93
	v_cvt_pk_bf16_f32 v89, v94, v95
	v_add_f32_e32 v85, v85, v53
	v_add_co_u32_e32 v92, vcc, s81, v158
	v_mul_f32_e32 v85, 0xbfb8aa3b, v85
	s_nop 0
	v_addc_co_u32_e32 v93, vcc, 0, v159, vcc
	v_exp_f32_e32 v85, v85
	v_cvt_pk_bf16_f32 v90, v98, v99
	v_cvt_pk_bf16_f32 v91, v101, v91
	global_store_dwordx4 v[92:93], v[88:91], off
	v_add_f32_e32 v85, 1.0, v85
	v_add_f32_e32 v86, v86, v54
	v_mul_f32_e32 v86, 0xbfb8aa3b, v86
	v_rcp_f32_e32 v84, v84
	v_exp_f32_e32 v86, v86
	s_nop 0
	v_add_f32_e32 v86, 1.0, v86
	v_add_f32_e32 v87, v87, v55
	v_mul_f32_e32 v87, 0xbfb8aa3b, v87
	v_rcp_f32_e32 v85, v85
	v_exp_f32_e32 v87, v87
	s_nop 0
	v_add_f32_e32 v87, 1.0, v87
	v_add_f32_e32 v80, v80, v44
	v_mul_f32_e32 v80, 0xbfb8aa3b, v80
	v_rcp_f32_e32 v86, v86
	v_exp_f32_e32 v80, v80
	s_nop 0
	v_add_f32_e32 v80, 1.0, v80
	v_add_f32_e32 v81, v81, v45
	v_mul_f32_e32 v81, 0xbfb8aa3b, v81
	v_rcp_f32_e32 v87, v87
	v_exp_f32_e32 v81, v81
	s_nop 0
	v_add_f32_e32 v81, 1.0, v81
	v_add_f32_e32 v82, v82, v46
	v_mul_f32_e32 v82, 0xbfb8aa3b, v82
	v_rcp_f32_e32 v88, v80
	v_exp_f32_e32 v82, v82
	s_nop 0
	v_add_f32_e32 v82, 1.0, v82
	v_add_f32_e32 v83, v83, v47
	v_mul_f32_e32 v83, 0xbfb8aa3b, v83
	v_rcp_f32_e32 v89, v81
	v_exp_f32_e32 v83, v83
	s_nop 0
	v_add_f32_e32 v83, 1.0, v83
	v_rcp_f32_e32 v92, v82
	v_add_f32_e32 v76, v76, v68
	v_mul_f32_e32 v76, 0xbfb8aa3b, v76
	v_exp_f32_e32 v76, v76
	s_nop 0
	v_add_f32_e32 v76, 1.0, v76
	v_rcp_f32_e32 v83, v83
	v_cvt_pk_bf16_f32 v80, v84, v85
	v_add_f32_e32 v77, v77, v69
	v_lshl_add_u64 v[96:97], v[158:159], 0, s[38:39]
	v_cvt_pk_bf16_f32 v81, v86, v87
	v_cvt_pk_bf16_f32 v82, v88, v89
	v_mul_f32_e32 v77, 0xbfb8aa3b, v77
	v_cvt_pk_bf16_f32 v83, v92, v83
	global_store_dwordx4 v[96:97], v[80:83], off offset:64
	v_exp_f32_e32 v77, v77
	v_add_f32_e32 v78, v78, v70
	v_add_f32_e32 v77, 1.0, v77
	v_mul_f32_e32 v78, 0xbfb8aa3b, v78
	v_rcp_f32_e32 v76, v76
	v_exp_f32_e32 v78, v78
	s_nop 0
	v_add_f32_e32 v78, 1.0, v78
	v_add_f32_e32 v79, v79, v71
	v_mul_f32_e32 v79, 0xbfb8aa3b, v79
	v_rcp_f32_e32 v77, v77
	v_exp_f32_e32 v79, v79
	s_nop 0
	v_add_f32_e32 v79, 1.0, v79
	v_add_f32_e32 v72, v72, v60
	v_mul_f32_e32 v72, 0xbfb8aa3b, v72
	v_rcp_f32_e32 v78, v78
	v_exp_f32_e32 v72, v72
	s_nop 0
	v_add_f32_e32 v72, 1.0, v72
	v_add_f32_e32 v73, v73, v61
	v_mul_f32_e32 v73, 0xbfb8aa3b, v73
	v_rcp_f32_e32 v79, v79
	v_exp_f32_e32 v73, v73
	s_nop 0
	v_add_f32_e32 v73, 1.0, v73
	v_add_f32_e32 v74, v74, v62
	v_mul_f32_e32 v74, 0xbfb8aa3b, v74
	v_rcp_f32_e32 v82, v72
	v_exp_f32_e32 v74, v74
	s_nop 0
	v_add_f32_e32 v74, 1.0, v74
	v_add_f32_e32 v75, v75, v63
	v_mul_f32_e32 v75, 0xbfb8aa3b, v75
	v_rcp_f32_e32 v83, v73
	v_exp_f32_e32 v75, v75
	s_nop 0
	v_add_f32_e32 v75, 1.0, v75
	v_rcp_f32_e32 v85, v74
	v_add_f32_e32 v64, v64, v52
	v_mul_f32_e32 v64, 0xbfb8aa3b, v64
	v_exp_f32_e32 v64, v64
	s_nop 0
	v_add_f32_e32 v64, 1.0, v64
	v_rcp_f32_e32 v75, v75
	v_cvt_pk_bf16_f32 v72, v76, v77
	v_cvt_pk_bf16_f32 v73, v78, v79
	v_add_f32_e32 v65, v65, v53
	v_add_co_u32_e32 v76, vcc, s82, v158
	v_mul_f32_e32 v65, 0xbfb8aa3b, v65
	s_nop 0
	v_addc_co_u32_e32 v77, vcc, 0, v159, vcc
	v_exp_f32_e32 v65, v65
	v_cvt_pk_bf16_f32 v74, v82, v83
	v_cvt_pk_bf16_f32 v75, v85, v75
	global_store_dwordx4 v[76:77], v[72:75], off
	v_add_f32_e32 v65, 1.0, v65
	v_add_f32_e32 v66, v66, v54
	v_mul_f32_e32 v66, 0xbfb8aa3b, v66
	v_rcp_f32_e32 v64, v64
	v_exp_f32_e32 v66, v66
	s_nop 0
	v_add_f32_e32 v66, 1.0, v66
	v_add_f32_e32 v67, v67, v55
	v_mul_f32_e32 v67, 0xbfb8aa3b, v67
	v_rcp_f32_e32 v65, v65
	v_exp_f32_e32 v67, v67
	s_nop 0
	v_add_f32_e32 v67, 1.0, v67
	v_add_f32_e32 v56, v56, v44
	v_mul_f32_e32 v56, 0xbfb8aa3b, v56
	v_rcp_f32_e32 v66, v66
	v_exp_f32_e32 v56, v56
	s_nop 0
	v_add_f32_e32 v56, 1.0, v56
	v_add_f32_e32 v57, v57, v45
	v_mul_f32_e32 v57, 0xbfb8aa3b, v57
	v_rcp_f32_e32 v67, v67
	v_exp_f32_e32 v57, v57
	s_nop 0
	v_add_f32_e32 v57, 1.0, v57
	v_add_f32_e32 v58, v58, v46
	v_mul_f32_e32 v58, 0xbfb8aa3b, v58
	v_rcp_f32_e32 v72, v56
	v_exp_f32_e32 v58, v58
	s_nop 0
	v_add_f32_e32 v58, 1.0, v58
	v_add_f32_e32 v59, v59, v47
	v_mul_f32_e32 v59, 0xbfb8aa3b, v59
	v_rcp_f32_e32 v73, v57
	v_exp_f32_e32 v59, v59
	s_nop 0
	v_add_f32_e32 v59, 1.0, v59
	v_rcp_f32_e32 v76, v58
	v_add_f32_e32 v48, v48, v68
	v_mul_f32_e32 v48, 0xbfb8aa3b, v48
	v_exp_f32_e32 v48, v48
	s_nop 0
	v_add_f32_e32 v48, 1.0, v48
	v_rcp_f32_e32 v59, v59
	v_cvt_pk_bf16_f32 v56, v64, v65
	v_add_f32_e32 v49, v49, v69
	v_lshl_add_u64 v[80:81], v[158:159], 0, s[40:41]
	v_cvt_pk_bf16_f32 v57, v66, v67
	v_cvt_pk_bf16_f32 v58, v72, v73
	v_mul_f32_e32 v49, 0xbfb8aa3b, v49
	v_cvt_pk_bf16_f32 v59, v76, v59
	global_store_dwordx4 v[80:81], v[56:59], off offset:64
	v_exp_f32_e32 v49, v49
	v_add_f32_e32 v50, v50, v70
	v_add_f32_e32 v49, 1.0, v49
	v_mul_f32_e32 v50, 0xbfb8aa3b, v50
	v_rcp_f32_e32 v48, v48
	v_exp_f32_e32 v50, v50
	s_nop 0
	v_add_f32_e32 v50, 1.0, v50
	v_add_f32_e32 v51, v51, v71
	v_mul_f32_e32 v51, 0xbfb8aa3b, v51
	v_rcp_f32_e32 v49, v49
	v_exp_f32_e32 v51, v51
	s_nop 0
	v_add_f32_e32 v51, 1.0, v51
	v_add_f32_e32 v40, v40, v60
	v_mul_f32_e32 v40, 0xbfb8aa3b, v40
	v_rcp_f32_e32 v50, v50
	v_exp_f32_e32 v40, v40
	s_nop 0
	v_add_f32_e32 v40, 1.0, v40
	v_add_f32_e32 v41, v41, v61
	v_mul_f32_e32 v41, 0xbfb8aa3b, v41
	v_rcp_f32_e32 v51, v51
	v_exp_f32_e32 v41, v41
	s_nop 0
	v_add_f32_e32 v41, 1.0, v41
	v_add_f32_e32 v42, v42, v62
	v_mul_f32_e32 v42, 0xbfb8aa3b, v42
	v_rcp_f32_e32 v58, v40
	v_exp_f32_e32 v42, v42
	s_nop 0
	v_add_f32_e32 v42, 1.0, v42
	v_add_f32_e32 v43, v43, v63
	v_mul_f32_e32 v43, 0xbfb8aa3b, v43
	v_rcp_f32_e32 v59, v41
	v_exp_f32_e32 v43, v43
	s_nop 0
	v_add_f32_e32 v43, 1.0, v43
	v_rcp_f32_e32 v65, v42
	v_add_f32_e32 v36, v36, v52
	v_mul_f32_e32 v36, 0xbfb8aa3b, v36
	v_exp_f32_e32 v36, v36
	s_nop 0
	v_add_f32_e32 v36, 1.0, v36
	v_rcp_f32_e32 v43, v43
	v_cvt_pk_bf16_f32 v40, v48, v49
	v_cvt_pk_bf16_f32 v41, v50, v51
	v_add_f32_e32 v37, v37, v53
	v_add_co_u32_e32 v48, vcc, s83, v158
	v_mul_f32_e32 v37, 0xbfb8aa3b, v37
	s_nop 0
	v_addc_co_u32_e32 v49, vcc, 0, v159, vcc
	v_exp_f32_e32 v37, v37
	v_cvt_pk_bf16_f32 v42, v58, v59
	v_cvt_pk_bf16_f32 v43, v65, v43
	global_store_dwordx4 v[48:49], v[40:43], off
	v_add_f32_e32 v37, 1.0, v37
	v_add_f32_e32 v38, v38, v54
	v_mul_f32_e32 v38, 0xbfb8aa3b, v38
	v_rcp_f32_e32 v36, v36
	v_exp_f32_e32 v38, v38
	s_nop 0
	v_add_f32_e32 v38, 1.0, v38
	v_add_f32_e32 v39, v39, v55
	v_mul_f32_e32 v39, 0xbfb8aa3b, v39
	v_rcp_f32_e32 v37, v37
	v_exp_f32_e32 v39, v39
	s_nop 0
	v_add_f32_e32 v39, 1.0, v39
	v_add_f32_e32 v32, v32, v44
	v_mul_f32_e32 v32, 0xbfb8aa3b, v32
	v_rcp_f32_e32 v38, v38
	v_exp_f32_e32 v32, v32
	s_nop 0
	v_add_f32_e32 v32, 1.0, v32
	v_add_f32_e32 v33, v33, v45
	v_mul_f32_e32 v33, 0xbfb8aa3b, v33
	v_rcp_f32_e32 v39, v39
	v_exp_f32_e32 v33, v33
	s_nop 0
	v_add_f32_e32 v33, 1.0, v33
	v_add_f32_e32 v34, v34, v46
	v_mul_f32_e32 v34, 0xbfb8aa3b, v34
	v_rcp_f32_e32 v40, v32
	v_exp_f32_e32 v34, v34
	s_nop 0
	v_add_f32_e32 v34, 1.0, v34
	v_add_f32_e32 v35, v35, v47
	v_mul_f32_e32 v35, 0xbfb8aa3b, v35
	v_rcp_f32_e32 v41, v33
	v_exp_f32_e32 v35, v35
	s_nop 0
	v_add_f32_e32 v35, 1.0, v35
	v_rcp_f32_e32 v48, v34
	v_add_f32_e32 v28, v28, v68
	v_mul_f32_e32 v28, 0xbfb8aa3b, v28
	v_exp_f32_e32 v28, v28
	s_nop 0
	v_add_f32_e32 v28, 1.0, v28
	v_rcp_f32_e32 v35, v35
	v_cvt_pk_bf16_f32 v32, v36, v37
	v_add_f32_e32 v29, v29, v69
	v_lshl_add_u64 v[56:57], v[158:159], 0, s[42:43]
	v_cvt_pk_bf16_f32 v33, v38, v39
	v_cvt_pk_bf16_f32 v34, v40, v41
	v_mul_f32_e32 v29, 0xbfb8aa3b, v29
	v_cvt_pk_bf16_f32 v35, v48, v35
	global_store_dwordx4 v[56:57], v[32:35], off offset:64
	v_exp_f32_e32 v29, v29
	v_add_f32_e32 v30, v30, v70
	v_add_f32_e32 v29, 1.0, v29
	v_mul_f32_e32 v30, 0xbfb8aa3b, v30
	v_rcp_f32_e32 v28, v28
	v_exp_f32_e32 v30, v30
	s_nop 0
	v_add_f32_e32 v30, 1.0, v30
	v_add_f32_e32 v31, v31, v71
	v_mul_f32_e32 v31, 0xbfb8aa3b, v31
	v_rcp_f32_e32 v29, v29
	v_exp_f32_e32 v31, v31
	s_nop 0
	v_add_f32_e32 v31, 1.0, v31
	v_add_f32_e32 v24, v24, v60
	v_mul_f32_e32 v24, 0xbfb8aa3b, v24
	v_rcp_f32_e32 v30, v30
	v_exp_f32_e32 v24, v24
	s_nop 0
	v_add_f32_e32 v24, 1.0, v24
	v_add_f32_e32 v25, v25, v61
	v_mul_f32_e32 v25, 0xbfb8aa3b, v25
	v_rcp_f32_e32 v31, v31
	v_exp_f32_e32 v25, v25
	s_nop 0
	v_add_f32_e32 v25, 1.0, v25
	v_add_f32_e32 v26, v26, v62
	v_mul_f32_e32 v26, 0xbfb8aa3b, v26
	v_rcp_f32_e32 v34, v24
	v_exp_f32_e32 v26, v26
	s_nop 0
	v_add_f32_e32 v26, 1.0, v26
	v_add_f32_e32 v27, v27, v63
	v_mul_f32_e32 v27, 0xbfb8aa3b, v27
	v_rcp_f32_e32 v35, v25
	v_exp_f32_e32 v27, v27
	s_nop 0
	v_add_f32_e32 v27, 1.0, v27
	v_rcp_f32_e32 v37, v26
	v_add_f32_e32 v20, v20, v52
	v_mul_f32_e32 v20, 0xbfb8aa3b, v20
	v_exp_f32_e32 v20, v20
	s_nop 0
	v_add_f32_e32 v20, 1.0, v20
	v_rcp_f32_e32 v27, v27
	v_cvt_pk_bf16_f32 v24, v28, v29
	v_cvt_pk_bf16_f32 v25, v30, v31
	v_add_f32_e32 v21, v21, v53
	v_add_co_u32_e32 v28, vcc, s84, v158
	v_mul_f32_e32 v21, 0xbfb8aa3b, v21
	s_nop 0
	v_addc_co_u32_e32 v29, vcc, 0, v159, vcc
	v_exp_f32_e32 v21, v21
	v_cvt_pk_bf16_f32 v26, v34, v35
	v_cvt_pk_bf16_f32 v27, v37, v27
	global_store_dwordx4 v[28:29], v[24:27], off
	v_add_f32_e32 v21, 1.0, v21
	v_add_f32_e32 v22, v22, v54
	v_mul_f32_e32 v22, 0xbfb8aa3b, v22
	v_rcp_f32_e32 v20, v20
	v_exp_f32_e32 v22, v22
	s_nop 0
	v_add_f32_e32 v22, 1.0, v22
	v_add_f32_e32 v23, v23, v55
	v_mul_f32_e32 v23, 0xbfb8aa3b, v23
	v_rcp_f32_e32 v21, v21
	v_exp_f32_e32 v23, v23
	s_nop 0
	v_add_f32_e32 v23, 1.0, v23
	v_add_f32_e32 v16, v16, v44
	v_mul_f32_e32 v16, 0xbfb8aa3b, v16
	v_rcp_f32_e32 v22, v22
	v_exp_f32_e32 v16, v16
	s_nop 0
; #define PG8_BAR __builtin_amdgcn_s_barrier()
; template <class Epi, class Sched, bool ALIGN_EPI = false, bool SP2 = false>
; __device__ __forceinline__ void gemm_phase(PG8_LAS unsigned char* lds, const Gemm g, const Sched& S, const Epi& E, const int wid) {
;     ...
;         if constexpr (!Epi::AFTER_DRAIN) { int fr_e = fr, fq_e = fq; asm volatile("" : "+v"(fr_e), "+v"(fq_e)); E(acc, cur, wr, wc, fr_e, fq_e); S.done(cur); }
;         if (!has_next) break;
; #pragma unroll
;         for (int a = 0; a < 2; ++a)
; #pragma unroll
;             for (int b = 0; b < 2; ++b)
; #pragma unroll
;                 for (int m = 0; m < 4; ++m)
; #pragma unroll
;                     for (int n = 0; n < 2; ++n) acc[a][b][m][n] = (f32x4){0.f, 0.f, 0.f, 0.f};
;         cur = nxt; cA = nA; cB = nB; ++ui;
;         if constexpr (ALIGN_EPI) { if (wr == 1) PG8_BAR; }
;     }
	v_add_f32_e32 v16, 1.0, v16
	v_add_f32_e32 v17, v17, v45
	v_mul_f32_e32 v17, 0xbfb8aa3b, v17
	v_rcp_f32_e32 v23, v23
	v_exp_f32_e32 v17, v17
	s_nop 0
	v_add_f32_e32 v17, 1.0, v17
	v_add_f32_e32 v18, v18, v46
	v_mul_f32_e32 v18, 0xbfb8aa3b, v18
	v_rcp_f32_e32 v24, v16
	v_exp_f32_e32 v18, v18
	s_nop 0
	v_add_f32_e32 v18, 1.0, v18
	v_add_f32_e32 v19, v19, v47
	v_mul_f32_e32 v19, 0xbfb8aa3b, v19
	v_rcp_f32_e32 v25, v17
	v_exp_f32_e32 v19, v19
	s_nop 0
	v_add_f32_e32 v19, 1.0, v19
	v_rcp_f32_e32 v28, v18
	v_add_f32_e32 v12, v12, v68
	v_mul_f32_e32 v12, 0xbfb8aa3b, v12
	v_exp_f32_e32 v12, v12
	s_nop 0
	v_add_f32_e32 v12, 1.0, v12
	v_rcp_f32_e32 v19, v19
	v_cvt_pk_bf16_f32 v16, v20, v21
	v_add_f32_e32 v13, v13, v69
	v_lshl_add_u64 v[32:33], v[158:159], 0, s[44:45]
	v_cvt_pk_bf16_f32 v17, v22, v23
	v_cvt_pk_bf16_f32 v18, v24, v25
	v_mul_f32_e32 v13, 0xbfb8aa3b, v13
	v_cvt_pk_bf16_f32 v19, v28, v19
	global_store_dwordx4 v[32:33], v[16:19], off offset:64
	v_exp_f32_e32 v13, v13
	v_add_f32_e32 v14, v14, v70
	v_add_f32_e32 v13, 1.0, v13
	v_mul_f32_e32 v14, 0xbfb8aa3b, v14
	v_rcp_f32_e32 v12, v12
	v_exp_f32_e32 v14, v14
	s_nop 0
	v_add_f32_e32 v14, 1.0, v14
	v_add_f32_e32 v15, v15, v71
	v_mul_f32_e32 v15, 0xbfb8aa3b, v15
	v_rcp_f32_e32 v13, v13
	v_exp_f32_e32 v15, v15
	s_nop 0
	v_add_f32_e32 v15, 1.0, v15
	v_add_f32_e32 v8, v8, v60
	v_mul_f32_e32 v8, 0xbfb8aa3b, v8
	v_rcp_f32_e32 v14, v14
	v_exp_f32_e32 v8, v8
	s_nop 0
	v_add_f32_e32 v8, 1.0, v8
	v_add_f32_e32 v9, v9, v61
	v_mul_f32_e32 v9, 0xbfb8aa3b, v9
	v_rcp_f32_e32 v15, v15
	v_exp_f32_e32 v9, v9
	s_nop 0
	v_add_f32_e32 v9, 1.0, v9
	v_add_f32_e32 v10, v10, v62
	v_mul_f32_e32 v10, 0xbfb8aa3b, v10
	v_rcp_f32_e32 v18, v8
	v_exp_f32_e32 v10, v10
	s_nop 0
	v_add_f32_e32 v10, 1.0, v10
	v_add_f32_e32 v11, v11, v63
	v_mul_f32_e32 v11, 0xbfb8aa3b, v11
	v_rcp_f32_e32 v19, v9
	v_exp_f32_e32 v11, v11
	s_nop 0
	v_add_f32_e32 v11, 1.0, v11
	v_rcp_f32_e32 v21, v10
	v_add_f32_e32 v4, v4, v52
	v_mul_f32_e32 v4, 0xbfb8aa3b, v4
	v_exp_f32_e32 v4, v4
	s_nop 0
	v_add_f32_e32 v4, 1.0, v4
	v_rcp_f32_e32 v11, v11
	v_cvt_pk_bf16_f32 v8, v12, v13
	v_cvt_pk_bf16_f32 v9, v14, v15
	v_add_f32_e32 v5, v5, v53
	v_add_co_u32_e32 v12, vcc, s85, v158
	v_mul_f32_e32 v5, 0xbfb8aa3b, v5
	s_nop 0
	v_addc_co_u32_e32 v13, vcc, 0, v159, vcc
	v_exp_f32_e32 v5, v5
	v_cvt_pk_bf16_f32 v10, v18, v19
	v_cvt_pk_bf16_f32 v11, v21, v11
	global_store_dwordx4 v[12:13], v[8:11], off
	v_add_f32_e32 v5, 1.0, v5
	v_add_f32_e32 v6, v6, v54
	v_mul_f32_e32 v6, 0xbfb8aa3b, v6
	v_rcp_f32_e32 v4, v4
	v_exp_f32_e32 v6, v6
	s_nop 0
	v_add_f32_e32 v6, 1.0, v6
	v_add_f32_e32 v7, v7, v55
	v_mul_f32_e32 v7, 0xbfb8aa3b, v7
	v_rcp_f32_e32 v5, v5
	v_exp_f32_e32 v7, v7
	s_nop 0
	v_add_f32_e32 v7, 1.0, v7
	v_add_f32_e32 v0, v0, v44
	v_mul_f32_e32 v0, 0xbfb8aa3b, v0
	v_rcp_f32_e32 v6, v6
	v_exp_f32_e32 v0, v0
	s_nop 0
	v_add_f32_e32 v0, 1.0, v0
	v_add_f32_e32 v1, v1, v45
	v_mul_f32_e32 v1, 0xbfb8aa3b, v1
	v_rcp_f32_e32 v7, v7
	v_exp_f32_e32 v1, v1
	s_nop 0
	v_add_f32_e32 v1, 1.0, v1
	v_add_f32_e32 v2, v2, v46
	v_mul_f32_e32 v2, 0xbfb8aa3b, v2
	v_rcp_f32_e32 v8, v0
	v_exp_f32_e32 v2, v2
	s_nop 0
	v_add_f32_e32 v2, 1.0, v2
	v_add_f32_e32 v3, v3, v47
	v_mul_f32_e32 v3, 0xbfb8aa3b, v3
	v_rcp_f32_e32 v9, v1
	v_exp_f32_e32 v3, v3
	s_nop 0
	v_add_f32_e32 v3, 1.0, v3
	v_rcp_f32_e32 v12, v2
	v_lshl_add_u64 v[16:17], v[158:159], 0, s[46:47]
	v_rcp_f32_e32 v3, v3
	s_and_b64 vcc, exec, s[2:3]
	s_mov_b64 s[2:3], -1
	v_cvt_pk_bf16_f32 v0, v4, v5
	v_cvt_pk_bf16_f32 v1, v6, v7
	v_cvt_pk_bf16_f32 v2, v8, v9
	v_cvt_pk_bf16_f32 v3, v12, v3
	global_store_dwordx4 v[16:17], v[0:3], off offset:64
	s_cbranch_vccnz .LBB0_1091
	s_andn2_b64 vcc, exec, s[18:19]
	s_cbranch_vccnz .LBB0_1090
	s_barrier
	s_branch .LBB0_1090

.LBB0_1498:
	v_mov_b32_e32 v142, v147
	v_mov_b32_e32 v153, v146
	s_lshl_b32 s0, s63, 8
	s_add_i32 s0, s0, s53
	v_add_u32_e32 v142, s0, v142
	v_ashrrev_i32_e32 v143, 31, v142
	v_lshl_add_u64 v[144:145], v[142:143], 2, s[18:19]
	global_load_dword v152, v[144:145], off
	global_load_dword v233, v[144:145], off offset:64
	global_load_dword v234, v[144:145], off offset:128
	global_load_dword v235, v[144:145], off offset:192
	global_load_dword v236, v[144:145], off offset:512
	global_load_dword v237, v[144:145], off offset:576
	global_load_dword v238, v[144:145], off offset:640
	global_load_dword v239, v[144:145], off offset:704
	v_mov_b32_e32 v154, v124
	v_mov_b32_e32 v155, v120
	v_mov_b32_e32 v120, v125
	v_mov_b32_e32 v124, v126
	v_mov_b32_e32 v125, v122
	v_mov_b32_e32 v122, v127
	v_mov_b32_e32 v126, v116
	v_mov_b32_e32 v127, v112
	s_lshl_b32 s0, s62, 7
	s_or_b32 s0, s0, s54
	v_lshl_add_u32 v156, v153, 3, s0
	v_ashrrev_i32_e32 v157, 31, v156
	s_waitcnt vmcnt(0)
	v_pk_mul_f32 v[154:155], v[154:155], v[152:153] op_sel_hi:[1,0]
	v_pk_mul_f32 v[120:121], v[120:121], v[152:153] op_sel_hi:[1,0]
	v_mul_f32_e32 v112, 0xbfb8aa3b, v155
	v_pk_mul_f32 v[124:125], v[124:125], v[152:153] op_sel_hi:[1,0]
	v_pk_mul_f32 v[126:127], v[126:127], v[152:153] op_sel_hi:[1,0]
	v_mul_f32_e32 v116, 0xbfb8aa3b, v121
	v_exp_f32_e32 v112, v112
	v_pk_mul_f32 v[122:123], v[122:123], v[152:153] op_sel_hi:[1,0]
	v_mul_f32_e32 v143, 0xbfb8aa3b, v125
	v_mul_f32_e32 v158, 0xbfb8aa3b, v127
	v_exp_f32_e32 v116, v116
	v_mul_f32_e32 v153, 0xbfb8aa3b, v123
	v_exp_f32_e32 v143, v143
	v_exp_f32_e32 v158, v158
	v_exp_f32_e32 v153, v153
	v_add_f32_e32 v112, 1.0, v112
	v_add_f32_e32 v116, 1.0, v116
	v_add_f32_e32 v143, 1.0, v143
	v_add_f32_e32 v158, 1.0, v158
	v_add_f32_e32 v153, 1.0, v153
	v_rcp_f32_e32 v112, v112
	s_nop 0
	v_mul_f32_e32 v112, v155, v112
	v_rcp_f32_e32 v116, v116
	v_mul_f32_e32 v154, v154, v112
	v_mul_f32_e32 v112, v121, v116
	v_rcp_f32_e32 v116, v143
	v_mul_f32_e32 v120, v120, v112
	v_mul_f32_e32 v112, v125, v116
	v_rcp_f32_e32 v116, v153
	v_mul_f32_e32 v121, v124, v112
	v_mul_f32_e32 v112, v123, v116
	v_mul_f32_e32 v122, v122, v112
	v_mov_b32_e32 v112, v117
	v_pk_mul_f32 v[112:113], v[112:113], v[152:153] op_sel_hi:[1,0]
	v_mul_f32_e32 v117, 0xbfb8aa3b, v113
	v_exp_f32_e32 v117, v117
	v_rcp_f32_e32 v116, v158
	s_nop 0
	v_mul_f32_e32 v116, v127, v116
	v_add_f32_e32 v123, 1.0, v117
	v_mul_f32_e32 v126, v126, v116
	v_mov_b32_e32 v116, v118
	v_mov_b32_e32 v117, v114
	v_pk_mul_f32 v[116:117], v[116:117], v[152:153] op_sel_hi:[1,0]
	v_mul_f32_e32 v114, 0xbfb8aa3b, v117
	v_exp_f32_e32 v114, v114
	s_nop 0
	v_add_f32_e32 v124, 1.0, v114
	v_rcp_f32_e32 v114, v123
	s_nop 0
	v_mul_f32_e32 v113, v113, v114
	v_mul_f32_e32 v118, v112, v113
	v_mov_b32_e32 v114, v119
	v_pk_mul_f32 v[112:113], v[114:115], v[152:153] op_sel_hi:[1,0]
	v_mul_f32_e32 v114, 0xbfb8aa3b, v113
	v_exp_f32_e32 v114, v114
	v_rcp_f32_e32 v115, v124
	s_nop 0
	v_mul_f32_e32 v115, v117, v115
	v_add_f32_e32 v114, 1.0, v114
	v_mul_f32_e32 v115, v116, v115
	v_rcp_f32_e32 v114, v114
	s_nop 0
	v_mul_f32_e32 v113, v113, v114
	v_mul_f32_e32 v112, v112, v113
	v_cvt_pk_bf16_f32 v116, v154, v120
	v_cvt_pk_bf16_f32 v117, v121, v122
	v_cvt_pk_bf16_f32 v118, v126, v118
	v_cvt_pk_bf16_f32 v119, v115, v112
	v_mov_b64_e32 v[112:113], s[10:11]
	v_mad_i64_i32 v[120:121], s[0:1], v142, s59, v[112:113]
	v_lshlrev_b64 v[114:115], 1, v[156:157]
	v_lshl_add_u64 v[120:121], v[120:121], 0, v[114:115]
	global_store_dwordx4 v[120:121], v[116:119], off
	s_nop 0
	v_add_u32_e32 v121, 16, v142
	v_mov_b32_e32 v118, v108
	v_mov_b32_e32 v119, v104
	v_mov_b32_e32 v116, v233
	v_pk_mul_f32 v[118:119], v[118:119], v[116:117] op_sel_hi:[1,0]
	s_nop 0
	v_mul_f32_e32 v104, 0xbfb8aa3b, v119
	v_exp_f32_e32 v104, v104
	s_nop 0
	v_add_f32_e32 v108, 1.0, v104
	v_mov_b32_e32 v104, v109
	v_pk_mul_f32 v[104:105], v[104:105], v[116:117] op_sel_hi:[1,0]
	v_mul_f32_e32 v109, 0xbfb8aa3b, v105
	v_exp_f32_e32 v109, v109
	v_rcp_f32_e32 v108, v108
	s_nop 0
	v_mul_f32_e32 v108, v119, v108
	v_add_f32_e32 v120, 1.0, v109
	v_mul_f32_e32 v117, v118, v108
	v_mov_b32_e32 v108, v110
	v_mov_b32_e32 v109, v106
	v_pk_mul_f32 v[108:109], v[108:109], v[116:117] op_sel_hi:[1,0]
	v_mul_f32_e32 v106, 0xbfb8aa3b, v109
	v_exp_f32_e32 v106, v106
	s_nop 0
	v_add_f32_e32 v118, 1.0, v106
	v_rcp_f32_e32 v106, v120
	s_nop 0
	v_mul_f32_e32 v105, v105, v106
	v_mul_f32_e32 v110, v104, v105
	v_mov_b32_e32 v106, v111
	v_pk_mul_f32 v[104:105], v[106:107], v[116:117] op_sel_hi:[1,0]
	v_mul_f32_e32 v106, 0xbfb8aa3b, v105
	v_exp_f32_e32 v106, v106
	s_nop 0
	v_add_f32_e32 v111, 1.0, v106
	v_rcp_f32_e32 v106, v118
	s_nop 0
	v_mul_f32_e32 v106, v109, v106
	v_mul_f32_e32 v108, v108, v106
	v_mov_b32_e32 v106, v100
	v_mov_b32_e32 v107, v96
	v_pk_mul_f32 v[106:107], v[106:107], v[116:117] op_sel_hi:[1,0]
	v_mul_f32_e32 v96, 0xbfb8aa3b, v107
	v_exp_f32_e32 v96, v96
	s_nop 0
	v_add_f32_e32 v109, 1.0, v96
	v_rcp_f32_e32 v96, v111
	s_nop 0
	v_mul_f32_e32 v96, v105, v96
	v_mul_f32_e32 v104, v104, v96
	v_mov_b32_e32 v96, v101
	v_pk_mul_f32 v[96:97], v[96:97], v[116:117] op_sel_hi:[1,0]
	v_mul_f32_e32 v101, 0xbfb8aa3b, v97
	v_exp_f32_e32 v101, v101
	v_rcp_f32_e32 v100, v109
	s_nop 0
	v_mul_f32_e32 v100, v107, v100
	v_add_f32_e32 v105, 1.0, v101
	v_mul_f32_e32 v106, v106, v100
	v_mov_b32_e32 v100, v102
	v_mov_b32_e32 v101, v98
	v_pk_mul_f32 v[100:101], v[100:101], v[116:117] op_sel_hi:[1,0]
	v_mul_f32_e32 v98, 0xbfb8aa3b, v101
	v_exp_f32_e32 v98, v98
	s_nop 0
	v_add_f32_e32 v107, 1.0, v98
	v_rcp_f32_e32 v98, v105
	s_nop 0
	v_mul_f32_e32 v97, v97, v98
	v_mul_f32_e32 v102, v96, v97
	v_mov_b32_e32 v98, v103
	v_pk_mul_f32 v[96:97], v[98:99], v[116:117] op_sel_hi:[1,0]
	v_mul_f32_e32 v98, 0xbfb8aa3b, v97
	v_exp_f32_e32 v98, v98
	v_rcp_f32_e32 v99, v107
	s_nop 0
	v_mul_f32_e32 v99, v101, v99
	v_add_f32_e32 v98, 1.0, v98
	v_mul_f32_e32 v99, v100, v99
	v_rcp_f32_e32 v98, v98
	s_nop 0
	v_mul_f32_e32 v97, v97, v98
	v_mul_f32_e32 v100, v96, v97
	v_cvt_pk_bf16_f32 v96, v117, v110
	v_cvt_pk_bf16_f32 v97, v108, v104
	v_cvt_pk_bf16_f32 v98, v106, v102
	v_cvt_pk_bf16_f32 v99, v99, v100
	v_mad_i64_i32 v[100:101], s[0:1], v121, s59, v[112:113]
	v_lshl_add_u64 v[100:101], v[100:101], 0, v[114:115]
	global_store_dwordx4 v[100:101], v[96:99], off
	s_nop 0
	v_add_u32_e32 v101, 32, v142
	v_mov_b32_e32 v98, v92
	v_mov_b32_e32 v99, v88
	v_mov_b32_e32 v96, v234
	v_pk_mul_f32 v[98:99], v[98:99], v[96:97] op_sel_hi:[1,0]
	s_nop 0
	v_mul_f32_e32 v88, 0xbfb8aa3b, v99
	v_exp_f32_e32 v88, v88
	s_nop 0
	v_add_f32_e32 v92, 1.0, v88
	v_mov_b32_e32 v88, v93
	v_pk_mul_f32 v[88:89], v[88:89], v[96:97] op_sel_hi:[1,0]
	v_mul_f32_e32 v93, 0xbfb8aa3b, v89
	v_exp_f32_e32 v93, v93
	v_rcp_f32_e32 v92, v92
	s_nop 0
	v_mul_f32_e32 v92, v99, v92
	v_add_f32_e32 v100, 1.0, v93
	v_mul_f32_e32 v97, v98, v92
	v_mov_b32_e32 v92, v94
	v_mov_b32_e32 v93, v90
	v_pk_mul_f32 v[92:93], v[92:93], v[96:97] op_sel_hi:[1,0]
	v_mul_f32_e32 v90, 0xbfb8aa3b, v93
	v_exp_f32_e32 v90, v90
	s_nop 0
	v_add_f32_e32 v98, 1.0, v90
	v_rcp_f32_e32 v90, v100
	s_nop 0
	v_mul_f32_e32 v89, v89, v90
	v_mul_f32_e32 v94, v88, v89
	v_mov_b32_e32 v90, v95
	v_pk_mul_f32 v[88:89], v[90:91], v[96:97] op_sel_hi:[1,0]
	v_mul_f32_e32 v90, 0xbfb8aa3b, v89
	v_exp_f32_e32 v90, v90
	s_nop 0
	v_add_f32_e32 v95, 1.0, v90
	v_rcp_f32_e32 v90, v98
	s_nop 0
	v_mul_f32_e32 v90, v93, v90
	v_mul_f32_e32 v92, v92, v90
	v_mov_b32_e32 v90, v84
	v_mov_b32_e32 v91, v80
	v_pk_mul_f32 v[90:91], v[90:91], v[96:97] op_sel_hi:[1,0]
	v_mul_f32_e32 v80, 0xbfb8aa3b, v91
	v_exp_f32_e32 v80, v80
	s_nop 0
	v_add_f32_e32 v93, 1.0, v80
	v_rcp_f32_e32 v80, v95
	s_nop 0
	v_mul_f32_e32 v80, v89, v80
	v_mul_f32_e32 v88, v88, v80
	v_mov_b32_e32 v80, v85
	v_pk_mul_f32 v[80:81], v[80:81], v[96:97] op_sel_hi:[1,0]
	v_mul_f32_e32 v85, 0xbfb8aa3b, v81
	v_exp_f32_e32 v85, v85
	v_rcp_f32_e32 v84, v93
	s_nop 0
	v_mul_f32_e32 v84, v91, v84
	v_add_f32_e32 v89, 1.0, v85
	v_mul_f32_e32 v90, v90, v84
	v_mov_b32_e32 v84, v86
	v_mov_b32_e32 v85, v82
	v_pk_mul_f32 v[84:85], v[84:85], v[96:97] op_sel_hi:[1,0]
	v_mul_f32_e32 v82, 0xbfb8aa3b, v85
	v_exp_f32_e32 v82, v82
	s_nop 0
	v_add_f32_e32 v91, 1.0, v82
	v_rcp_f32_e32 v82, v89
	s_nop 0
	v_mul_f32_e32 v81, v81, v82
	v_mul_f32_e32 v86, v80, v81
	v_mov_b32_e32 v82, v87
	v_pk_mul_f32 v[80:81], v[82:83], v[96:97] op_sel_hi:[1,0]
	v_mul_f32_e32 v82, 0xbfb8aa3b, v81
	v_exp_f32_e32 v82, v82
	v_rcp_f32_e32 v83, v91
	s_nop 0
	v_mul_f32_e32 v83, v85, v83
	v_add_f32_e32 v82, 1.0, v82
	v_mul_f32_e32 v83, v84, v83
	v_rcp_f32_e32 v82, v82
	s_nop 0
	v_mul_f32_e32 v81, v81, v82
	v_mul_f32_e32 v84, v80, v81
	v_cvt_pk_bf16_f32 v80, v97, v94
	v_cvt_pk_bf16_f32 v81, v92, v88
	v_cvt_pk_bf16_f32 v82, v90, v86
	v_cvt_pk_bf16_f32 v83, v83, v84
	v_mad_i64_i32 v[84:85], s[0:1], v101, s59, v[112:113]
	v_lshl_add_u64 v[84:85], v[84:85], 0, v[114:115]
	global_store_dwordx4 v[84:85], v[80:83], off
	s_nop 0
	v_add_u32_e32 v85, 48, v142
	v_mov_b32_e32 v82, v76
	v_mov_b32_e32 v83, v72
	v_mov_b32_e32 v80, v235
	v_pk_mul_f32 v[82:83], v[82:83], v[80:81] op_sel_hi:[1,0]
	s_nop 0
	v_mul_f32_e32 v72, 0xbfb8aa3b, v83
	v_exp_f32_e32 v72, v72
	s_nop 0
	v_add_f32_e32 v76, 1.0, v72
	v_mov_b32_e32 v72, v77
	v_pk_mul_f32 v[72:73], v[72:73], v[80:81] op_sel_hi:[1,0]
	v_mul_f32_e32 v77, 0xbfb8aa3b, v73
	v_exp_f32_e32 v77, v77
	v_rcp_f32_e32 v76, v76
	s_nop 0
	v_mul_f32_e32 v76, v83, v76
	v_add_f32_e32 v84, 1.0, v77
	v_mul_f32_e32 v81, v82, v76
	v_mov_b32_e32 v76, v78
	v_mov_b32_e32 v77, v74
	v_pk_mul_f32 v[76:77], v[76:77], v[80:81] op_sel_hi:[1,0]
	v_mul_f32_e32 v74, 0xbfb8aa3b, v77
	v_exp_f32_e32 v74, v74
	s_nop 0
	v_add_f32_e32 v82, 1.0, v74
	v_rcp_f32_e32 v74, v84
	s_nop 0
	v_mul_f32_e32 v73, v73, v74
	v_mul_f32_e32 v78, v72, v73
	v_mov_b32_e32 v74, v79
	v_pk_mul_f32 v[72:73], v[74:75], v[80:81] op_sel_hi:[1,0]
	v_mul_f32_e32 v74, 0xbfb8aa3b, v73
	v_exp_f32_e32 v74, v74
	s_nop 0
	v_add_f32_e32 v79, 1.0, v74
	v_rcp_f32_e32 v74, v82
	s_nop 0
	v_mul_f32_e32 v74, v77, v74
	v_mul_f32_e32 v76, v76, v74
	v_mov_b32_e32 v74, v68
	v_mov_b32_e32 v75, v64
	v_pk_mul_f32 v[74:75], v[74:75], v[80:81] op_sel_hi:[1,0]
	v_mul_f32_e32 v64, 0xbfb8aa3b, v75
	v_exp_f32_e32 v64, v64
	s_nop 0
	v_add_f32_e32 v77, 1.0, v64
	v_rcp_f32_e32 v64, v79
	s_nop 0
	v_mul_f32_e32 v64, v73, v64
	v_mul_f32_e32 v72, v72, v64
	v_mov_b32_e32 v64, v69
	v_pk_mul_f32 v[64:65], v[64:65], v[80:81] op_sel_hi:[1,0]
	v_mul_f32_e32 v69, 0xbfb8aa3b, v65
	v_exp_f32_e32 v69, v69
	v_rcp_f32_e32 v68, v77
	s_nop 0
	v_mul_f32_e32 v68, v75, v68
	v_add_f32_e32 v73, 1.0, v69
	v_mul_f32_e32 v74, v74, v68
	v_mov_b32_e32 v68, v70
	v_mov_b32_e32 v69, v66
	v_pk_mul_f32 v[68:69], v[68:69], v[80:81] op_sel_hi:[1,0]
	v_mul_f32_e32 v66, 0xbfb8aa3b, v69
	v_exp_f32_e32 v66, v66
	s_nop 0
	v_add_f32_e32 v75, 1.0, v66
	v_rcp_f32_e32 v66, v73
	s_nop 0
	v_mul_f32_e32 v65, v65, v66
	v_mul_f32_e32 v70, v64, v65
	v_mov_b32_e32 v66, v71
	v_pk_mul_f32 v[64:65], v[66:67], v[80:81] op_sel_hi:[1,0]
	v_mul_f32_e32 v66, 0xbfb8aa3b, v65
	v_exp_f32_e32 v66, v66
	v_rcp_f32_e32 v67, v75
	s_nop 0
	v_mul_f32_e32 v67, v69, v67
	v_add_f32_e32 v66, 1.0, v66
	v_mul_f32_e32 v67, v68, v67
	v_rcp_f32_e32 v66, v66
	s_nop 0
	v_mul_f32_e32 v65, v65, v66
	v_mul_f32_e32 v68, v64, v65
	v_cvt_pk_bf16_f32 v64, v81, v78
	v_cvt_pk_bf16_f32 v65, v76, v72
	v_cvt_pk_bf16_f32 v66, v74, v70
	v_cvt_pk_bf16_f32 v67, v67, v68
	v_mad_i64_i32 v[68:69], s[0:1], v85, s59, v[112:113]
	v_lshl_add_u64 v[68:69], v[68:69], 0, v[114:115]
	global_store_dwordx4 v[68:69], v[64:67], off
	s_nop 0
	v_add_u32_e32 v69, 0x80, v142
	v_mov_b32_e32 v66, v60
	v_mov_b32_e32 v67, v56
	v_mov_b32_e32 v64, v236
	v_pk_mul_f32 v[66:67], v[66:67], v[64:65] op_sel_hi:[1,0]
	s_nop 0
	v_mul_f32_e32 v56, 0xbfb8aa3b, v67
	v_exp_f32_e32 v56, v56
	s_nop 0
	v_add_f32_e32 v60, 1.0, v56
	v_mov_b32_e32 v56, v61
	v_pk_mul_f32 v[56:57], v[56:57], v[64:65] op_sel_hi:[1,0]
	v_mul_f32_e32 v61, 0xbfb8aa3b, v57
	v_exp_f32_e32 v61, v61
	v_rcp_f32_e32 v60, v60
	s_nop 0
	v_mul_f32_e32 v60, v67, v60
	v_add_f32_e32 v68, 1.0, v61
	v_mul_f32_e32 v65, v66, v60
	v_mov_b32_e32 v60, v62
	v_mov_b32_e32 v61, v58
	v_pk_mul_f32 v[60:61], v[60:61], v[64:65] op_sel_hi:[1,0]
	v_mul_f32_e32 v58, 0xbfb8aa3b, v61
	v_exp_f32_e32 v58, v58
	s_nop 0
	v_add_f32_e32 v66, 1.0, v58
	v_rcp_f32_e32 v58, v68
	s_nop 0
	v_mul_f32_e32 v57, v57, v58
	v_mul_f32_e32 v62, v56, v57
	v_mov_b32_e32 v58, v63
	v_pk_mul_f32 v[56:57], v[58:59], v[64:65] op_sel_hi:[1,0]
	v_mul_f32_e32 v58, 0xbfb8aa3b, v57
	v_exp_f32_e32 v58, v58
	s_nop 0
	v_add_f32_e32 v63, 1.0, v58
	v_rcp_f32_e32 v58, v66
	s_nop 0
	v_mul_f32_e32 v58, v61, v58
	v_mul_f32_e32 v60, v60, v58
	v_mov_b32_e32 v58, v52
	v_mov_b32_e32 v59, v48
	v_pk_mul_f32 v[58:59], v[58:59], v[64:65] op_sel_hi:[1,0]
	v_mul_f32_e32 v48, 0xbfb8aa3b, v59
	v_exp_f32_e32 v48, v48
	s_nop 0
	v_add_f32_e32 v61, 1.0, v48
	v_rcp_f32_e32 v48, v63
	s_nop 0
	v_mul_f32_e32 v48, v57, v48
	v_mul_f32_e32 v56, v56, v48
	v_mov_b32_e32 v48, v53
	v_pk_mul_f32 v[48:49], v[48:49], v[64:65] op_sel_hi:[1,0]
	v_mul_f32_e32 v53, 0xbfb8aa3b, v49
	v_exp_f32_e32 v53, v53
	v_rcp_f32_e32 v52, v61
	s_nop 0
	v_mul_f32_e32 v52, v59, v52
	v_add_f32_e32 v57, 1.0, v53
	v_mul_f32_e32 v58, v58, v52
	v_mov_b32_e32 v52, v54
	v_mov_b32_e32 v53, v50
	v_pk_mul_f32 v[52:53], v[52:53], v[64:65] op_sel_hi:[1,0]
	v_mul_f32_e32 v50, 0xbfb8aa3b, v53
	v_exp_f32_e32 v50, v50
	s_nop 0
	v_add_f32_e32 v59, 1.0, v50
	v_rcp_f32_e32 v50, v57
	s_nop 0
	v_mul_f32_e32 v49, v49, v50
	v_mul_f32_e32 v54, v48, v49
	v_mov_b32_e32 v50, v55
	v_pk_mul_f32 v[48:49], v[50:51], v[64:65] op_sel_hi:[1,0]
	v_mul_f32_e32 v50, 0xbfb8aa3b, v49
	v_exp_f32_e32 v50, v50
	v_rcp_f32_e32 v51, v59
	s_nop 0
	v_mul_f32_e32 v51, v53, v51
	v_add_f32_e32 v50, 1.0, v50
	v_mul_f32_e32 v51, v52, v51
	v_rcp_f32_e32 v50, v50
	s_nop 0
	v_mul_f32_e32 v49, v49, v50
	v_mul_f32_e32 v52, v48, v49
	v_cvt_pk_bf16_f32 v48, v65, v62
	v_cvt_pk_bf16_f32 v49, v60, v56
	v_cvt_pk_bf16_f32 v50, v58, v54
	v_cvt_pk_bf16_f32 v51, v51, v52
	v_mad_i64_i32 v[52:53], s[0:1], v69, s59, v[112:113]
	v_lshl_add_u64 v[52:53], v[52:53], 0, v[114:115]
	global_store_dwordx4 v[52:53], v[48:51], off
	s_nop 0
	v_add_u32_e32 v53, 0x90, v142
	v_mov_b32_e32 v50, v44
	v_mov_b32_e32 v51, v40
	v_mov_b32_e32 v48, v237
	v_pk_mul_f32 v[50:51], v[50:51], v[48:49] op_sel_hi:[1,0]
	s_nop 0
	v_mul_f32_e32 v40, 0xbfb8aa3b, v51
	v_exp_f32_e32 v40, v40
	s_nop 0
	v_add_f32_e32 v44, 1.0, v40
	v_mov_b32_e32 v40, v45
	v_pk_mul_f32 v[40:41], v[40:41], v[48:49] op_sel_hi:[1,0]
	v_mul_f32_e32 v45, 0xbfb8aa3b, v41
	v_exp_f32_e32 v45, v45
	v_rcp_f32_e32 v44, v44
	s_nop 0
	v_mul_f32_e32 v44, v51, v44
	v_add_f32_e32 v52, 1.0, v45
	v_mul_f32_e32 v49, v50, v44
	v_mov_b32_e32 v44, v46
	v_mov_b32_e32 v45, v42
	v_pk_mul_f32 v[44:45], v[44:45], v[48:49] op_sel_hi:[1,0]
	v_mul_f32_e32 v42, 0xbfb8aa3b, v45
	v_exp_f32_e32 v42, v42
	s_nop 0
	v_add_f32_e32 v50, 1.0, v42
	v_rcp_f32_e32 v42, v52
	s_nop 0
	v_mul_f32_e32 v41, v41, v42
	v_mul_f32_e32 v46, v40, v41
	v_mov_b32_e32 v42, v47
	v_pk_mul_f32 v[40:41], v[42:43], v[48:49] op_sel_hi:[1,0]
	v_mul_f32_e32 v42, 0xbfb8aa3b, v41
	v_exp_f32_e32 v42, v42
	s_nop 0
	v_add_f32_e32 v47, 1.0, v42
	v_rcp_f32_e32 v42, v50
	s_nop 0
	v_mul_f32_e32 v42, v45, v42
	v_mul_f32_e32 v44, v44, v42
	v_mov_b32_e32 v42, v36
	v_mov_b32_e32 v43, v32
	v_pk_mul_f32 v[42:43], v[42:43], v[48:49] op_sel_hi:[1,0]
	v_mul_f32_e32 v32, 0xbfb8aa3b, v43
	v_exp_f32_e32 v32, v32
	s_nop 0
	v_add_f32_e32 v45, 1.0, v32
	v_rcp_f32_e32 v32, v47
	s_nop 0
	v_mul_f32_e32 v32, v41, v32
	v_mul_f32_e32 v40, v40, v32
	v_mov_b32_e32 v32, v37
	v_pk_mul_f32 v[32:33], v[32:33], v[48:49] op_sel_hi:[1,0]
	v_mul_f32_e32 v37, 0xbfb8aa3b, v33
	v_exp_f32_e32 v37, v37
	v_rcp_f32_e32 v36, v45
	s_nop 0
	v_mul_f32_e32 v36, v43, v36
	v_add_f32_e32 v41, 1.0, v37
	v_mul_f32_e32 v42, v42, v36
	v_mov_b32_e32 v36, v38
	v_mov_b32_e32 v37, v34
	v_pk_mul_f32 v[36:37], v[36:37], v[48:49] op_sel_hi:[1,0]
	v_mul_f32_e32 v34, 0xbfb8aa3b, v37
	v_exp_f32_e32 v34, v34
	s_nop 0
	v_add_f32_e32 v43, 1.0, v34
	v_rcp_f32_e32 v34, v41
	s_nop 0
	v_mul_f32_e32 v33, v33, v34
	v_mul_f32_e32 v38, v32, v33
	v_mov_b32_e32 v34, v39
	v_pk_mul_f32 v[32:33], v[34:35], v[48:49] op_sel_hi:[1,0]
	v_mul_f32_e32 v34, 0xbfb8aa3b, v33
	v_exp_f32_e32 v34, v34
	v_rcp_f32_e32 v35, v43
	s_nop 0
	v_mul_f32_e32 v35, v37, v35
	v_add_f32_e32 v34, 1.0, v34
	v_mul_f32_e32 v35, v36, v35
	v_rcp_f32_e32 v34, v34
	s_nop 0
	v_mul_f32_e32 v33, v33, v34
	v_mul_f32_e32 v36, v32, v33
	v_cvt_pk_bf16_f32 v32, v49, v46
	v_cvt_pk_bf16_f32 v33, v44, v40
	v_cvt_pk_bf16_f32 v34, v42, v38
	v_cvt_pk_bf16_f32 v35, v35, v36
	v_mad_i64_i32 v[36:37], s[0:1], v53, s59, v[112:113]
	v_lshl_add_u64 v[36:37], v[36:37], 0, v[114:115]
; #define PG8_BAR __builtin_amdgcn_s_barrier()
; template <class Epi, class Sched, bool ALIGN_EPI = false, bool SP2 = false>
; __device__ __forceinline__ void gemm_phase(PG8_LAS unsigned char* lds, const Gemm g, const Sched& S, const Epi& E, const int wid) {
;     ...
;         if constexpr (!Epi::AFTER_DRAIN) { int fr_e = fr, fq_e = fq; asm volatile("" : "+v"(fr_e), "+v"(fq_e)); E(acc, cur, wr, wc, fr_e, fq_e); S.done(cur); }
;         if (!has_next) break;
; #pragma unroll
;         for (int a = 0; a < 2; ++a)
; #pragma unroll
;             for (int b = 0; b < 2; ++b)
; #pragma unroll
;                 for (int m = 0; m < 4; ++m)
; #pragma unroll
;                     for (int n = 0; n < 2; ++n) acc[a][b][m][n] = (f32x4){0.f, 0.f, 0.f, 0.f};
;         cur = nxt; cA = nA; cB = nB; ++ui;
;         if constexpr (ALIGN_EPI) { if (wr == 1) PG8_BAR; }
;     }
	global_store_dwordx4 v[36:37], v[32:35], off
	s_nop 0
	v_add_u32_e32 v37, 0xa0, v142
	v_mov_b32_e32 v34, v28
	v_mov_b32_e32 v35, v24
	v_mov_b32_e32 v32, v238
	v_pk_mul_f32 v[34:35], v[34:35], v[32:33] op_sel_hi:[1,0]
	s_nop 0
	v_mul_f32_e32 v24, 0xbfb8aa3b, v35
	v_exp_f32_e32 v24, v24
	s_nop 0
	v_add_f32_e32 v28, 1.0, v24
	v_mov_b32_e32 v24, v29
	v_pk_mul_f32 v[24:25], v[24:25], v[32:33] op_sel_hi:[1,0]
	v_mul_f32_e32 v29, 0xbfb8aa3b, v25
	v_exp_f32_e32 v29, v29
	v_rcp_f32_e32 v28, v28
	s_nop 0
	v_mul_f32_e32 v28, v35, v28
	v_add_f32_e32 v36, 1.0, v29
	v_mul_f32_e32 v33, v34, v28
	v_mov_b32_e32 v28, v30
	v_mov_b32_e32 v29, v26
	v_pk_mul_f32 v[28:29], v[28:29], v[32:33] op_sel_hi:[1,0]
	v_mul_f32_e32 v26, 0xbfb8aa3b, v29
	v_exp_f32_e32 v26, v26
	s_nop 0
	v_add_f32_e32 v34, 1.0, v26
	v_rcp_f32_e32 v26, v36
	s_nop 0
	v_mul_f32_e32 v25, v25, v26
	v_mul_f32_e32 v30, v24, v25
	v_mov_b32_e32 v26, v31
	v_pk_mul_f32 v[24:25], v[26:27], v[32:33] op_sel_hi:[1,0]
	v_mul_f32_e32 v26, 0xbfb8aa3b, v25
	v_exp_f32_e32 v26, v26
	s_nop 0
	v_add_f32_e32 v31, 1.0, v26
	v_rcp_f32_e32 v26, v34
	s_nop 0
	v_mul_f32_e32 v26, v29, v26
	v_mul_f32_e32 v28, v28, v26
	v_mov_b32_e32 v26, v20
	v_mov_b32_e32 v27, v16
	v_pk_mul_f32 v[26:27], v[26:27], v[32:33] op_sel_hi:[1,0]
	v_mul_f32_e32 v16, 0xbfb8aa3b, v27
	v_exp_f32_e32 v16, v16
	s_nop 0
	v_add_f32_e32 v29, 1.0, v16
	v_rcp_f32_e32 v16, v31
	s_nop 0
	v_mul_f32_e32 v16, v25, v16
	v_mul_f32_e32 v24, v24, v16
	v_mov_b32_e32 v16, v21
	v_pk_mul_f32 v[16:17], v[16:17], v[32:33] op_sel_hi:[1,0]
	v_mul_f32_e32 v21, 0xbfb8aa3b, v17
	v_exp_f32_e32 v21, v21
	v_rcp_f32_e32 v20, v29
	s_nop 0
	v_mul_f32_e32 v20, v27, v20
	v_add_f32_e32 v25, 1.0, v21
	v_mul_f32_e32 v26, v26, v20
	v_mov_b32_e32 v20, v22
	v_mov_b32_e32 v21, v18
	v_pk_mul_f32 v[20:21], v[20:21], v[32:33] op_sel_hi:[1,0]
	v_mul_f32_e32 v18, 0xbfb8aa3b, v21
	v_exp_f32_e32 v18, v18
	s_nop 0
	v_add_f32_e32 v27, 1.0, v18
	v_rcp_f32_e32 v18, v25
	s_nop 0
	v_mul_f32_e32 v17, v17, v18
	v_mul_f32_e32 v22, v16, v17
	v_mov_b32_e32 v18, v23
	v_pk_mul_f32 v[16:17], v[18:19], v[32:33] op_sel_hi:[1,0]
	v_mul_f32_e32 v18, 0xbfb8aa3b, v17
	v_exp_f32_e32 v18, v18
	v_rcp_f32_e32 v19, v27
	s_nop 0
	v_mul_f32_e32 v19, v21, v19
	v_add_f32_e32 v18, 1.0, v18
	v_mul_f32_e32 v19, v20, v19
	v_rcp_f32_e32 v18, v18
	s_nop 0
	v_mul_f32_e32 v17, v17, v18
	v_mul_f32_e32 v20, v16, v17
	v_cvt_pk_bf16_f32 v16, v33, v30
	v_cvt_pk_bf16_f32 v17, v28, v24
	v_cvt_pk_bf16_f32 v18, v26, v22
	v_cvt_pk_bf16_f32 v19, v19, v20
	v_mad_i64_i32 v[20:21], s[0:1], v37, s59, v[112:113]
	v_lshl_add_u64 v[20:21], v[20:21], 0, v[114:115]
	global_store_dwordx4 v[20:21], v[16:19], off
	s_nop 0
	v_add_u32_e32 v21, 0xb0, v142
	v_mov_b32_e32 v18, v12
	v_mov_b32_e32 v19, v8
	v_mov_b32_e32 v16, v239
	v_pk_mul_f32 v[18:19], v[18:19], v[16:17] op_sel_hi:[1,0]
	s_nop 0
	v_mul_f32_e32 v8, 0xbfb8aa3b, v19
	v_exp_f32_e32 v8, v8
	s_nop 0
	v_add_f32_e32 v12, 1.0, v8
	v_mov_b32_e32 v8, v13
	v_pk_mul_f32 v[8:9], v[8:9], v[16:17] op_sel_hi:[1,0]
	v_mul_f32_e32 v13, 0xbfb8aa3b, v9
	v_exp_f32_e32 v13, v13
	v_rcp_f32_e32 v12, v12
	s_nop 0
	v_mul_f32_e32 v12, v19, v12
	v_add_f32_e32 v20, 1.0, v13
	v_mul_f32_e32 v17, v18, v12
	v_mov_b32_e32 v12, v14
	v_mov_b32_e32 v13, v10
	v_pk_mul_f32 v[12:13], v[12:13], v[16:17] op_sel_hi:[1,0]
	v_mul_f32_e32 v10, 0xbfb8aa3b, v13
	v_exp_f32_e32 v10, v10
	s_nop 0
	v_add_f32_e32 v18, 1.0, v10
	v_rcp_f32_e32 v10, v20
	s_nop 0
	v_mul_f32_e32 v9, v9, v10
	v_mul_f32_e32 v14, v8, v9
	v_mov_b32_e32 v10, v15
	v_pk_mul_f32 v[8:9], v[10:11], v[16:17] op_sel_hi:[1,0]
	v_mul_f32_e32 v10, 0xbfb8aa3b, v9
	v_exp_f32_e32 v10, v10
	s_nop 0
	v_add_f32_e32 v15, 1.0, v10
	v_rcp_f32_e32 v10, v18
	s_nop 0
	v_mul_f32_e32 v10, v13, v10
	v_mul_f32_e32 v12, v12, v10
	v_mov_b32_e32 v10, v0
	v_mov_b32_e32 v11, v4
	v_pk_mul_f32 v[10:11], v[10:11], v[16:17] op_sel_hi:[1,0]
	v_mul_f32_e32 v0, 0xbfb8aa3b, v11
	v_exp_f32_e32 v0, v0
	s_nop 0
	v_add_f32_e32 v13, 1.0, v0
	v_rcp_f32_e32 v0, v15
	s_nop 0
	v_mul_f32_e32 v0, v9, v0
	v_mul_f32_e32 v8, v8, v0
	v_mov_b32_e32 v4, v1
	v_pk_mul_f32 v[0:1], v[4:5], v[16:17] op_sel_hi:[1,0]
	v_mul_f32_e32 v4, 0xbfb8aa3b, v1
	v_exp_f32_e32 v4, v4
	s_nop 0
	v_add_f32_e32 v9, 1.0, v4
	v_rcp_f32_e32 v4, v13
	s_nop 0
	v_mul_f32_e32 v4, v11, v4
	v_mul_f32_e32 v10, v10, v4
	v_mov_b32_e32 v4, v2
	v_mov_b32_e32 v5, v6
	v_pk_mul_f32 v[4:5], v[4:5], v[16:17] op_sel_hi:[1,0]
	v_mul_f32_e32 v2, 0xbfb8aa3b, v5
	v_exp_f32_e32 v2, v2
	v_rcp_f32_e32 v6, v9
	s_nop 0
	v_mul_f32_e32 v1, v1, v6
	v_add_f32_e32 v2, 1.0, v2
	v_mul_f32_e32 v9, v0, v1
	v_mov_b32_e32 v6, v3
	v_pk_mul_f32 v[0:1], v[6:7], v[16:17] op_sel_hi:[1,0]
	v_mul_f32_e32 v3, 0xbfb8aa3b, v1
	v_exp_f32_e32 v3, v3
	v_rcp_f32_e32 v2, v2
	s_nop 0
	v_mul_f32_e32 v2, v5, v2
	v_add_f32_e32 v3, 1.0, v3
	v_mul_f32_e32 v4, v4, v2
	v_rcp_f32_e32 v2, v3
	s_nop 0
	v_mul_f32_e32 v1, v1, v2
	v_mul_f32_e32 v3, v0, v1
	v_cvt_pk_bf16_f32 v0, v17, v14
	v_cvt_pk_bf16_f32 v1, v12, v8
	v_cvt_pk_bf16_f32 v2, v10, v9
	v_cvt_pk_bf16_f32 v3, v4, v3
	v_mad_i64_i32 v[4:5], s[0:1], v21, s59, v[112:113]
	v_lshl_add_u64 v[4:5], v[4:5], 0, v[114:115]
	s_and_b64 vcc, exec, s[2:3]
	s_mov_b64 s[2:3], -1
	global_store_dwordx4 v[4:5], v[0:3], off
	s_cbranch_vccnz .LBB0_1486
	s_andn2_b64 vcc, exec, s[16:17]
	s_cbranch_vccnz .LBB0_1485
	s_barrier
	s_branch .LBB0_1485
